# nt hint on the read-once f32 weight loads of the prep phase
# speedup vs baseline: 1.0217x; 1.0023x over previous
.LBB0_16:
	s_mov_b32 s2, 0x367a25e1
	v_mul_hi_i32 v2, v114, s2
	v_lshrrev_b32_e32 v3, 31, v2
	v_ashrrev_i32_e32 v2, 12, v2
	v_add_u32_e32 v74, v2, v3
	v_mul_i32_i24_e32 v4, 0x4b30, v74
	v_sub_u32_e32 v2, v114, v4
	s_movk_i32 s2, 0x201f
	v_cmp_lt_i32_e32 vcc, s2, v2
	v_ashrrev_i32_e32 v75, 31, v74
	s_and_saveexec_b64 s[2:3], vcc
	s_xor_b64 s[64:65], exec, s[2:3]
	s_cbranch_execz .LBB0_96
	v_add_u32_e32 v81, 0xffffdfe0, v2
	v_cmp_lt_u32_e32 vcc, s77, v81
	s_and_saveexec_b64 s[2:3], vcc
	s_xor_b64 s[2:3], exec, s[2:3]
	v_add_u32_e32 v81, 0xffffdde0, v2
	s_or_saveexec_b64 s[4:5], s[2:3]
	v_mov_b64_e32 v[2:3], s[8:9]
	s_mov_b32 s2, 0xa00000
	v_lshlrev_b64 v[6:7], 21, v[74:75]
	v_mad_i64_i32 v[2:3], s[2:3], v74, s2, v[2:3]
	s_xor_b64 exec, exec, s[4:5]
	s_cbranch_execz .LBB0_21
	v_lshlrev_b32_e32 v5, 6, v4
	v_lshlrev_b32_e32 v4, 1, v4
	v_sub_u32_e32 v4, v102, v4
	v_and_b32_e32 v9, 0x3c0, v4
	v_sub_u32_e32 v5, v101, v5
	v_or_b32_e32 v4, v9, v83
	v_lshl_add_u64 v[10:11], v[6:7], 2, s[38:39]
	v_and_b32_e32 v8, 0x7c0, v5
	v_lshlrev_b32_e32 v68, 13, v4
	v_lshl_add_u64 v[4:5], v[10:11], 0, v[68:69]
	v_lshlrev_b32_e32 v68, 2, v8
	v_lshl_add_u64 v[4:5], v[4:5], 0, v[68:69]
	v_mov_b32_e32 v73, v69
	v_lshl_add_u64 v[4:5], v[4:5], 0, v[72:73]
	v_add_co_u32_e64 v14, s[2:3], s78, v4
	v_lshlrev_b32_e32 v68, 1, v9
	s_nop 0
	v_addc_co_u32_e64 v15, s[2:3], 0, v5, s[2:3]
	v_add_co_u32_e64 v18, s[2:3], s79, v4
	global_load_dwordx4 v[10:13], v[4:5], off nt
	s_nop 0
	global_load_dwordx4 v[14:17], v[14:15], off nt
	v_addc_co_u32_e64 v19, s[2:3], 0, v5, s[2:3]
	v_add_co_u32_e64 v22, s[2:3], s82, v4
	v_add_u32_e32 v9, 0x400, v86
	s_nop 0
	v_addc_co_u32_e64 v23, s[2:3], 0, v5, s[2:3]
	v_add_co_u32_e64 v26, s[2:3], s83, v4
	global_load_dwordx4 v[18:21], v[18:19], off nt
	s_nop 0
	global_load_dwordx4 v[22:25], v[22:23], off nt
	v_addc_co_u32_e64 v27, s[2:3], 0, v5, s[2:3]
	v_add_co_u32_e64 v30, s[2:3], s84, v4
	s_nop 1
	v_addc_co_u32_e64 v31, s[2:3], 0, v5, s[2:3]
	v_add_co_u32_e64 v34, s[2:3], s85, v4
	global_load_dwordx4 v[26:29], v[26:27], off nt
	s_nop 0
	global_load_dwordx4 v[30:33], v[30:31], off nt
	v_addc_co_u32_e64 v35, s[2:3], 0, v5, s[2:3]
	v_add_co_u32_e64 v38, s[2:3], s86, v4
	s_nop 1
	v_addc_co_u32_e64 v39, s[2:3], 0, v5, s[2:3]
	global_load_dwordx4 v[34:37], v[34:35], off nt
	s_nop 0
	global_load_dwordx4 v[38:41], v[38:39], off nt
	v_add_co_u32_e64 v42, s[2:3], s87, v4
	s_nop 1
	v_addc_co_u32_e64 v43, s[2:3], 0, v5, s[2:3]
	v_add_co_u32_e64 v46, s[2:3], s88, v4
	s_nop 1
	v_addc_co_u32_e64 v47, s[2:3], 0, v5, s[2:3]
	global_load_dwordx4 v[42:45], v[42:43], off nt
	s_nop 0
	global_load_dwordx4 v[46:49], v[46:47], off nt
	v_add_co_u32_e64 v50, s[2:3], s89, v4
	s_nop 1
	v_addc_co_u32_e64 v51, s[2:3], 0, v5, s[2:3]
	v_add_co_u32_e64 v54, s[2:3], s90, v4
	s_nop 1
	v_addc_co_u32_e64 v55, s[2:3], 0, v5, s[2:3]
	global_load_dwordx4 v[50:53], v[50:51], off nt
	s_nop 0
	global_load_dwordx4 v[54:57], v[54:55], off nt
	v_add_co_u32_e64 v58, s[2:3], s91, v4
	s_nop 1
	v_addc_co_u32_e64 v59, s[2:3], 0, v5, s[2:3]
	global_load_dwordx4 v[58:61], v[58:59], off nt
	v_add_co_u32_e64 v62, s[2:3], s92, v4
	s_nop 1
	v_addc_co_u32_e64 v63, s[2:3], 0, v5, s[2:3]
	global_load_dwordx4 v[62:65], v[62:63], off nt
	v_add_co_u32_e64 v76, s[2:3], s93, v4
	s_nop 1
	v_addc_co_u32_e64 v77, s[2:3], 0, v5, s[2:3]
	global_load_dwordx4 v[76:79], v[76:77], off nt
	v_add_co_u32_e64 v4, s[2:3], s94, v4
	s_nop 1
	v_addc_co_u32_e64 v5, s[2:3], 0, v5, s[2:3]
	global_load_dwordx4 v[116:119], v[4:5], off nt
	v_add_u32_e32 v4, 0x1458, v84
	s_waitcnt vmcnt(15)
	ds_write2_b32 v84, v10, v11 offset1:1
	ds_write2_b32 v84, v12, v13 offset0:2 offset1:3
	s_waitcnt vmcnt(14)
	ds_write2_b32 v103, v14, v15 offset1:1
	ds_write2_b32 v104, v16, v17 offset1:1
	s_waitcnt vmcnt(13)
	ds_write2_b32 v105, v18, v19 offset1:1
	ds_write2_b32 v106, v20, v21 offset1:1
	s_waitcnt vmcnt(12)
	ds_write2_b32 v107, v22, v23 offset1:1
	ds_write2_b32 v108, v24, v25 offset1:1
	s_waitcnt vmcnt(11)
	ds_write2_b32 v109, v26, v27 offset1:1
	ds_write2_b32 v110, v28, v29 offset1:1
	s_waitcnt vmcnt(10)
	ds_write2_b32 v111, v30, v31 offset1:1
	ds_write2_b32 v4, v32, v33 offset1:1
	v_add_u32_e32 v4, 0x1860, v84
	s_waitcnt vmcnt(9)
	ds_write2_b32 v4, v34, v35 offset1:1
	v_add_u32_e32 v4, 0x1868, v84
	ds_write2_b32 v4, v36, v37 offset1:1
	v_add_u32_e32 v4, 0x1c70, v84
	s_waitcnt vmcnt(8)
	ds_write2_b32 v4, v38, v39 offset1:1
	v_add_u32_e32 v4, 0x1c78, v84
	ds_write2_b32 v4, v40, v41 offset1:1
	v_add_u32_e32 v4, 0x2080, v84
	s_waitcnt vmcnt(7)
	ds_write2_b32 v4, v42, v43 offset1:1
	v_add_u32_e32 v4, 0x2088, v84
	ds_write2_b32 v4, v44, v45 offset1:1
	v_add_u32_e32 v4, 0x2490, v84
	s_waitcnt vmcnt(6)
	ds_write2_b32 v4, v46, v47 offset1:1
	v_add_u32_e32 v4, 0x2498, v84
	ds_write2_b32 v4, v48, v49 offset1:1
	v_add_u32_e32 v4, 0x28a0, v84
	s_waitcnt vmcnt(5)
	ds_write2_b32 v4, v50, v51 offset1:1
	v_add_u32_e32 v4, 0x28a8, v84
	ds_write2_b32 v4, v52, v53 offset1:1
	v_add_u32_e32 v4, 0x2cb0, v84
	s_waitcnt vmcnt(4)
	ds_write2_b32 v4, v54, v55 offset1:1
	v_add_u32_e32 v4, 0x2cb8, v84
	ds_write2_b32 v4, v56, v57 offset1:1
	v_add_u32_e32 v4, 0x30c0, v84
	s_waitcnt vmcnt(3)
	ds_write2_b32 v4, v58, v59 offset1:1
	v_add_u32_e32 v4, 0x30c8, v84
	ds_write2_b32 v4, v60, v61 offset1:1
	v_add_u32_e32 v4, 0x34d0, v84
	s_waitcnt vmcnt(2)
	ds_write2_b32 v4, v62, v63 offset1:1
	v_add_u32_e32 v4, 0x34d8, v84
	ds_write2_b32 v4, v64, v65 offset1:1
	v_add_u32_e32 v4, 0x38e0, v84
	s_waitcnt vmcnt(1)
	ds_write2_b32 v4, v76, v77 offset1:1
	v_add_u32_e32 v4, 0x38e8, v84
	ds_write2_b32 v4, v78, v79 offset1:1
	v_add_u32_e32 v4, 0x3cf0, v84
	s_waitcnt vmcnt(0)
	ds_write2_b32 v4, v116, v117 offset1:1
	v_add_u32_e32 v4, 0x3cf8, v84
	ds_write2_b32 v4, v118, v119 offset1:1
	s_waitcnt lgkmcnt(0)
	ds_read2_b32 v[16:17], v9 offset0:134 offset1:142
	ds_read2_b32 v[14:15], v9 offset0:199 offset1:207
	ds_read2_b32 v[20:21], v9 offset0:4 offset1:12
	ds_read2_b32 v[18:19], v9 offset0:69 offset1:77
	ds_read2_b32 v[24:25], v86 offset0:130 offset1:138
	s_waitcnt lgkmcnt(4)
	v_bfe_u32 v11, v16, 16, 1
	s_waitcnt lgkmcnt(3)
	v_bfe_u32 v10, v14, 16, 1
	v_add3_u32 v11, v16, v11, s95
	v_add3_u32 v10, v14, v10, s95
	v_lshrrev_b32_e32 v11, 16, v11
	ds_read2_b32 v[22:23], v86 offset0:195 offset1:203
	v_and_or_b32 v13, v10, s96, v11
	s_waitcnt lgkmcnt(3)
	v_bfe_u32 v11, v20, 16, 1
	ds_read2_b32 v[28:29], v86 offset1:8
	s_waitcnt lgkmcnt(3)
	v_bfe_u32 v10, v18, 16, 1
	v_add3_u32 v11, v20, v11, s95
	ds_read2_b32 v[26:27], v86 offset0:65 offset1:73
	v_add3_u32 v10, v18, v10, s95
	v_lshrrev_b32_e32 v11, 16, v11
	v_and_or_b32 v12, v10, s96, v11
	s_waitcnt lgkmcnt(3)
	v_bfe_u32 v11, v24, 16, 1
	s_waitcnt lgkmcnt(2)
	v_bfe_u32 v10, v22, 16, 1
	v_add3_u32 v11, v24, v11, s95
	v_add3_u32 v10, v22, v10, s95
	v_lshrrev_b32_e32 v11, 16, v11
	s_waitcnt lgkmcnt(1)
	v_bfe_u32 v14, v28, 16, 1
	v_and_or_b32 v11, v10, s96, v11
	s_waitcnt lgkmcnt(0)
	v_bfe_u32 v10, v26, 16, 1
	v_add3_u32 v14, v28, v14, s95
	v_add3_u32 v10, v26, v10, s95
	v_lshrrev_b32_e32 v14, 16, v14
	v_and_or_b32 v10, v10, s96, v14
	v_or_b32_e32 v14, v8, v85
	v_lshl_add_u64 v[4:5], v[2:3], 0, v[68:69]
	v_lshlrev_b32_e32 v68, 1, v70
	v_mul_u32_u24_e32 v14, 0xa00, v14
	v_lshl_add_u64 v[4:5], v[4:5], 0, v[68:69]
	v_lshlrev_b32_e32 v68, 1, v14
	v_lshl_add_u64 v[30:31], v[4:5], 0, v[68:69]
	global_store_dwordx4 v[30:31], v[10:13], off
	v_bfe_u32 v14, v29, 16, 1
	v_add3_u32 v14, v29, v14, s95
	v_bfe_u32 v11, v17, 16, 1
	v_bfe_u32 v10, v15, 16, 1
	v_add3_u32 v11, v17, v11, s95
	v_add3_u32 v10, v15, v10, s95
	v_lshrrev_b32_e32 v11, 16, v11
	v_and_or_b32 v13, v10, s96, v11
	v_bfe_u32 v11, v21, 16, 1
	v_bfe_u32 v10, v19, 16, 1
	v_add3_u32 v11, v21, v11, s95
	v_add3_u32 v10, v19, v10, s95
	v_lshrrev_b32_e32 v11, 16, v11
	v_and_or_b32 v12, v10, s96, v11
	v_bfe_u32 v11, v25, 16, 1
	v_bfe_u32 v10, v23, 16, 1
	v_add3_u32 v11, v25, v11, s95
	v_add3_u32 v10, v23, v10, s95
	v_lshrrev_b32_e32 v11, 16, v11
	v_and_or_b32 v11, v10, s96, v11
	v_bfe_u32 v10, v27, 16, 1
	v_add3_u32 v10, v27, v10, s95
	v_lshrrev_b32_e32 v14, 16, v14
	v_and_or_b32 v10, v10, s96, v14
	v_or_b32_e32 v14, v8, v87
	v_mul_u32_u24_e32 v16, 0xa00, v14
	v_lshlrev_b32_e32 v68, 1, v16
	ds_read2_b32 v[16:17], v9 offset0:150 offset1:158
	ds_read2_b32 v[14:15], v9 offset0:215 offset1:223
	v_lshl_add_u64 v[18:19], v[4:5], 0, v[68:69]
	ds_read2_b32 v[20:21], v9 offset0:20 offset1:28
	global_store_dwordx4 v[18:19], v[10:13], off
	ds_read2_b32 v[18:19], v9 offset0:85 offset1:93
	ds_read2_b32 v[24:25], v86 offset0:146 offset1:154
	s_waitcnt lgkmcnt(4)
	v_bfe_u32 v11, v16, 16, 1
	s_waitcnt lgkmcnt(3)
	v_bfe_u32 v10, v14, 16, 1
	v_add3_u32 v11, v16, v11, s95
	v_add3_u32 v10, v14, v10, s95
	v_lshrrev_b32_e32 v11, 16, v11
	ds_read2_b32 v[22:23], v86 offset0:211 offset1:219
	v_and_or_b32 v13, v10, s96, v11
	s_waitcnt lgkmcnt(3)
	v_bfe_u32 v11, v20, 16, 1
	ds_read2_b32 v[28:29], v86 offset0:16 offset1:24
	s_waitcnt lgkmcnt(3)
	v_bfe_u32 v10, v18, 16, 1
	v_add3_u32 v11, v20, v11, s95
	ds_read2_b32 v[26:27], v86 offset0:81 offset1:89
	v_add3_u32 v10, v18, v10, s95
	v_lshrrev_b32_e32 v11, 16, v11
	v_and_or_b32 v12, v10, s96, v11
	s_waitcnt lgkmcnt(3)
	v_bfe_u32 v11, v24, 16, 1
	s_waitcnt lgkmcnt(2)
	v_bfe_u32 v10, v22, 16, 1
	v_add3_u32 v11, v24, v11, s95
	v_add3_u32 v10, v22, v10, s95
	v_lshrrev_b32_e32 v11, 16, v11
	s_waitcnt lgkmcnt(1)
	v_bfe_u32 v14, v28, 16, 1
	v_and_or_b32 v11, v10, s96, v11
	s_waitcnt lgkmcnt(0)
	v_bfe_u32 v10, v26, 16, 1
	v_add3_u32 v14, v28, v14, s95
	v_add3_u32 v10, v26, v10, s95
	v_lshrrev_b32_e32 v14, 16, v14
	v_and_or_b32 v10, v10, s96, v14
	v_or_b32_e32 v14, v8, v88
	v_mul_u32_u24_e32 v14, 0xa00, v14
	v_lshlrev_b32_e32 v68, 1, v14
	v_lshl_add_u64 v[30:31], v[4:5], 0, v[68:69]
	global_store_dwordx4 v[30:31], v[10:13], off
	v_bfe_u32 v14, v29, 16, 1
	v_add3_u32 v14, v29, v14, s95
	v_bfe_u32 v11, v17, 16, 1
	v_bfe_u32 v10, v15, 16, 1
	v_add3_u32 v11, v17, v11, s95
	v_add3_u32 v10, v15, v10, s95
	v_lshrrev_b32_e32 v11, 16, v11
	v_and_or_b32 v13, v10, s96, v11
	v_bfe_u32 v11, v21, 16, 1
	v_bfe_u32 v10, v19, 16, 1
	v_add3_u32 v11, v21, v11, s95
	v_add3_u32 v10, v19, v10, s95
	v_lshrrev_b32_e32 v11, 16, v11
	v_and_or_b32 v12, v10, s96, v11
	v_bfe_u32 v11, v25, 16, 1
	v_bfe_u32 v10, v23, 16, 1
	v_add3_u32 v11, v25, v11, s95
	v_add3_u32 v10, v23, v10, s95
	v_lshrrev_b32_e32 v11, 16, v11
	v_and_or_b32 v11, v10, s96, v11
	v_bfe_u32 v10, v27, 16, 1
	v_add3_u32 v10, v27, v10, s95
	v_lshrrev_b32_e32 v14, 16, v14
	v_and_or_b32 v10, v10, s96, v14
	v_or_b32_e32 v14, v8, v89
	v_mul_u32_u24_e32 v16, 0xa00, v14
	v_lshlrev_b32_e32 v68, 1, v16
	ds_read2_b32 v[16:17], v9 offset0:166 offset1:174
	ds_read2_b32 v[14:15], v9 offset0:231 offset1:239
	v_lshl_add_u64 v[18:19], v[4:5], 0, v[68:69]
	ds_read2_b32 v[20:21], v9 offset0:36 offset1:44
	global_store_dwordx4 v[18:19], v[10:13], off
	ds_read2_b32 v[18:19], v9 offset0:101 offset1:109
	ds_read2_b32 v[24:25], v86 offset0:162 offset1:170
	s_waitcnt lgkmcnt(4)
	v_bfe_u32 v11, v16, 16, 1
	s_waitcnt lgkmcnt(3)
	v_bfe_u32 v10, v14, 16, 1
	v_add3_u32 v11, v16, v11, s95
	v_add3_u32 v10, v14, v10, s95
	v_lshrrev_b32_e32 v11, 16, v11
	ds_read2_b32 v[22:23], v86 offset0:227 offset1:235
	v_and_or_b32 v13, v10, s96, v11
	s_waitcnt lgkmcnt(3)
	v_bfe_u32 v11, v20, 16, 1
	ds_read2_b32 v[28:29], v86 offset0:32 offset1:40
	s_waitcnt lgkmcnt(3)
	v_bfe_u32 v10, v18, 16, 1
	v_add3_u32 v11, v20, v11, s95
	ds_read2_b32 v[26:27], v86 offset0:97 offset1:105
	v_add3_u32 v10, v18, v10, s95
	v_lshrrev_b32_e32 v11, 16, v11
	v_and_or_b32 v12, v10, s96, v11
	s_waitcnt lgkmcnt(3)
	v_bfe_u32 v11, v24, 16, 1
	s_waitcnt lgkmcnt(2)
	v_bfe_u32 v10, v22, 16, 1
	v_add3_u32 v11, v24, v11, s95
	v_add3_u32 v10, v22, v10, s95
	v_lshrrev_b32_e32 v11, 16, v11
	s_waitcnt lgkmcnt(1)
	v_bfe_u32 v14, v28, 16, 1
	v_and_or_b32 v11, v10, s96, v11
	s_waitcnt lgkmcnt(0)
	v_bfe_u32 v10, v26, 16, 1
	v_add3_u32 v14, v28, v14, s95
	v_add3_u32 v10, v26, v10, s95
	v_lshrrev_b32_e32 v14, 16, v14
	v_and_or_b32 v10, v10, s96, v14
	v_or_b32_e32 v14, v8, v90
	v_mul_u32_u24_e32 v14, 0xa00, v14
	v_lshlrev_b32_e32 v68, 1, v14
	v_lshl_add_u64 v[30:31], v[4:5], 0, v[68:69]
	global_store_dwordx4 v[30:31], v[10:13], off
	v_bfe_u32 v14, v29, 16, 1
	v_add3_u32 v14, v29, v14, s95
	v_bfe_u32 v11, v17, 16, 1
	v_bfe_u32 v10, v15, 16, 1
	v_add3_u32 v11, v17, v11, s95
	v_add3_u32 v10, v15, v10, s95
	v_lshrrev_b32_e32 v11, 16, v11
	v_and_or_b32 v13, v10, s96, v11
	v_bfe_u32 v11, v21, 16, 1
	v_bfe_u32 v10, v19, 16, 1
	v_add3_u32 v11, v21, v11, s95
	v_add3_u32 v10, v19, v10, s95
	v_lshrrev_b32_e32 v11, 16, v11
	v_and_or_b32 v12, v10, s96, v11
	v_bfe_u32 v11, v25, 16, 1
	v_bfe_u32 v10, v23, 16, 1
	v_add3_u32 v11, v25, v11, s95
	v_add3_u32 v10, v23, v10, s95
	v_lshrrev_b32_e32 v11, 16, v11
	v_and_or_b32 v11, v10, s96, v11
	v_bfe_u32 v10, v27, 16, 1
	v_add3_u32 v10, v27, v10, s95
	v_lshrrev_b32_e32 v14, 16, v14
	v_and_or_b32 v10, v10, s96, v14
	v_or_b32_e32 v14, v8, v91
	v_mul_u32_u24_e32 v16, 0xa00, v14
	v_lshlrev_b32_e32 v68, 1, v16
	ds_read2_b32 v[16:17], v9 offset0:182 offset1:190
	ds_read2_b32 v[14:15], v9 offset0:247 offset1:255
	v_lshl_add_u64 v[18:19], v[4:5], 0, v[68:69]
	ds_read2_b32 v[20:21], v9 offset0:52 offset1:60
	global_store_dwordx4 v[18:19], v[10:13], off
	ds_read2_b32 v[18:19], v9 offset0:117 offset1:125
	ds_read2_b32 v[24:25], v86 offset0:178 offset1:186
	s_waitcnt lgkmcnt(4)
	v_bfe_u32 v11, v16, 16, 1
	s_waitcnt lgkmcnt(3)
	v_bfe_u32 v10, v14, 16, 1
	v_add3_u32 v11, v16, v11, s95
	v_add3_u32 v10, v14, v10, s95
	v_lshrrev_b32_e32 v9, 16, v11
	ds_read2_b32 v[22:23], v86 offset0:243 offset1:251
	v_and_or_b32 v13, v10, s96, v9
	s_waitcnt lgkmcnt(3)
	v_bfe_u32 v10, v20, 16, 1
	s_waitcnt lgkmcnt(2)
	v_bfe_u32 v9, v18, 16, 1
	v_add3_u32 v10, v20, v10, s95
	ds_read2_b32 v[28:29], v86 offset0:48 offset1:56
	v_add3_u32 v9, v18, v9, s95
	v_lshrrev_b32_e32 v10, 16, v10
	ds_read2_b32 v[26:27], v86 offset0:113 offset1:121
	v_and_or_b32 v12, v9, s96, v10
	s_waitcnt lgkmcnt(3)
	v_bfe_u32 v10, v24, 16, 1
	s_waitcnt lgkmcnt(2)
	v_bfe_u32 v9, v22, 16, 1
	v_add3_u32 v10, v24, v10, s95
	v_add3_u32 v9, v22, v9, s95
	v_lshrrev_b32_e32 v10, 16, v10
	v_and_or_b32 v11, v9, s96, v10
	s_waitcnt lgkmcnt(1)
	v_bfe_u32 v10, v28, 16, 1
	s_waitcnt lgkmcnt(0)
	v_bfe_u32 v9, v26, 16, 1
	v_add3_u32 v10, v28, v10, s95
	v_add3_u32 v9, v26, v9, s95
	v_lshrrev_b32_e32 v10, 16, v10
	v_and_or_b32 v10, v9, s96, v10
	v_or_b32_e32 v9, v8, v92
	v_mul_u32_u24_e32 v9, 0xa00, v9
	v_lshlrev_b32_e32 v68, 1, v9
	v_lshl_add_u64 v[30:31], v[4:5], 0, v[68:69]
	global_store_dwordx4 v[30:31], v[10:13], off
	v_bfe_u32 v9, v15, 16, 1
	v_add3_u32 v9, v15, v9, s95
	v_bfe_u32 v10, v17, 16, 1
	v_add3_u32 v10, v17, v10, s95
	v_lshrrev_b32_e32 v10, 16, v10
	v_and_or_b32 v13, v9, s96, v10
	v_bfe_u32 v10, v21, 16, 1
	v_bfe_u32 v9, v19, 16, 1
	v_add3_u32 v10, v21, v10, s95
	v_add3_u32 v9, v19, v9, s95
	v_lshrrev_b32_e32 v10, 16, v10
	v_and_or_b32 v12, v9, s96, v10
	v_bfe_u32 v10, v25, 16, 1
	v_bfe_u32 v9, v23, 16, 1
	v_add3_u32 v10, v25, v10, s95
	v_add3_u32 v9, v23, v9, s95
	v_lshrrev_b32_e32 v10, 16, v10
	v_and_or_b32 v11, v9, s96, v10
	v_bfe_u32 v10, v29, 16, 1
	v_or_b32_e32 v8, v8, v93
	v_bfe_u32 v9, v27, 16, 1
	v_add3_u32 v10, v29, v10, s95
	v_mul_u32_u24_e32 v8, 0xa00, v8
	v_add3_u32 v9, v27, v9, s95
	v_lshrrev_b32_e32 v10, 16, v10
	v_lshlrev_b32_e32 v68, 1, v8
	v_and_or_b32 v10, v9, s96, v10
	v_lshl_add_u64 v[4:5], v[4:5], 0, v[68:69]
	global_store_dwordx4 v[4:5], v[10:13], off
	s_waitcnt lgkmcnt(0)

.LBB0_26:
	v_lshlrev_b32_e32 v11, 1, v81
	v_and_b32_e32 v11, 0x1c0, v11
	v_lshlrev_b32_e32 v10, 6, v81
	v_or_b32_e32 v12, v11, v83
	v_lshl_add_u64 v[8:9], s[40:41], 0, v[4:5]
	v_and_b32_e32 v10, 0x7c0, v10
	v_lshlrev_b32_e32 v68, 13, v12
	v_lshl_add_u64 v[8:9], v[8:9], 0, v[68:69]
	v_lshlrev_b32_e32 v68, 2, v10
	v_lshl_add_u64 v[8:9], v[8:9], 0, v[68:69]
	v_mov_b32_e32 v73, v69
	v_lshl_add_u64 v[8:9], v[8:9], 0, v[72:73]
	v_add_co_u32_e32 v16, vcc, s78, v8
	v_lshlrev_b32_e32 v68, 1, v11
	s_nop 0
	v_addc_co_u32_e32 v17, vcc, 0, v9, vcc
	v_add_co_u32_e32 v20, vcc, s79, v8
	global_load_dwordx4 v[12:15], v[8:9], off nt
	s_nop 0
	global_load_dwordx4 v[16:19], v[16:17], off nt
	v_addc_co_u32_e32 v21, vcc, 0, v9, vcc
	v_add_co_u32_e32 v24, vcc, s82, v8
	v_add_u32_e32 v11, 0x400, v86
	s_nop 0
	v_addc_co_u32_e32 v25, vcc, 0, v9, vcc
	v_add_co_u32_e32 v28, vcc, s83, v8
	global_load_dwordx4 v[20:23], v[20:21], off nt
	s_nop 0
	global_load_dwordx4 v[24:27], v[24:25], off nt
	v_addc_co_u32_e32 v29, vcc, 0, v9, vcc
	v_add_co_u32_e32 v32, vcc, s84, v8
	s_nop 1
	v_addc_co_u32_e32 v33, vcc, 0, v9, vcc
	v_add_co_u32_e32 v36, vcc, s85, v8
	global_load_dwordx4 v[28:31], v[28:29], off nt
	s_nop 0
	global_load_dwordx4 v[32:35], v[32:33], off nt
	v_addc_co_u32_e32 v37, vcc, 0, v9, vcc
	v_add_co_u32_e32 v40, vcc, s86, v8
	s_nop 1
	v_addc_co_u32_e32 v41, vcc, 0, v9, vcc
	global_load_dwordx4 v[36:39], v[36:37], off nt
	s_nop 0
	global_load_dwordx4 v[40:43], v[40:41], off nt
	v_add_co_u32_e32 v44, vcc, s87, v8
	s_nop 1
	v_addc_co_u32_e32 v45, vcc, 0, v9, vcc
	v_add_co_u32_e32 v48, vcc, s88, v8
	s_nop 1
	v_addc_co_u32_e32 v49, vcc, 0, v9, vcc
	global_load_dwordx4 v[44:47], v[44:45], off nt
	s_nop 0
	global_load_dwordx4 v[48:51], v[48:49], off nt
	v_add_co_u32_e32 v52, vcc, s89, v8
	s_nop 1
	v_addc_co_u32_e32 v53, vcc, 0, v9, vcc
	v_add_co_u32_e32 v56, vcc, s90, v8
	s_nop 1
	v_addc_co_u32_e32 v57, vcc, 0, v9, vcc
	global_load_dwordx4 v[52:55], v[52:53], off nt
	s_nop 0
	global_load_dwordx4 v[56:59], v[56:57], off nt
	v_add_co_u32_e32 v60, vcc, s91, v8
	s_nop 1
	v_addc_co_u32_e32 v61, vcc, 0, v9, vcc
	v_add_co_u32_e32 v64, vcc, s92, v8
	s_nop 1
	v_addc_co_u32_e32 v65, vcc, 0, v9, vcc
	global_load_dwordx4 v[60:63], v[60:61], off nt
	s_nop 0
	global_load_dwordx4 v[76:79], v[64:65], off nt
	v_add_co_u32_e32 v64, vcc, s93, v8
	s_nop 1
	v_addc_co_u32_e32 v65, vcc, 0, v9, vcc
	global_load_dwordx4 v[116:119], v[64:65], off nt
	v_add_co_u32_e32 v8, vcc, s94, v8
	s_nop 1
	v_addc_co_u32_e32 v9, vcc, 0, v9, vcc
	global_load_dwordx4 v[120:123], v[8:9], off nt
	v_add_u32_e32 v8, 0x1458, v84
	s_waitcnt vmcnt(15)
	ds_write2_b32 v84, v12, v13 offset1:1
	ds_write2_b32 v84, v14, v15 offset0:2 offset1:3
	s_waitcnt vmcnt(14)
	ds_write2_b32 v103, v16, v17 offset1:1
	ds_write2_b32 v104, v18, v19 offset1:1
	s_waitcnt vmcnt(13)
	ds_write2_b32 v105, v20, v21 offset1:1
	ds_write2_b32 v106, v22, v23 offset1:1
	s_waitcnt vmcnt(12)
	ds_write2_b32 v107, v24, v25 offset1:1
	ds_write2_b32 v108, v26, v27 offset1:1
	s_waitcnt vmcnt(11)
	ds_write2_b32 v109, v28, v29 offset1:1
	ds_write2_b32 v110, v30, v31 offset1:1
	s_waitcnt vmcnt(10)
	ds_write2_b32 v111, v32, v33 offset1:1
	ds_write2_b32 v8, v34, v35 offset1:1
	v_add_u32_e32 v8, 0x1860, v84
	s_waitcnt vmcnt(9)
	ds_write2_b32 v8, v36, v37 offset1:1
	v_add_u32_e32 v8, 0x1868, v84
	ds_write2_b32 v8, v38, v39 offset1:1
	v_add_u32_e32 v8, 0x1c70, v84
	s_waitcnt vmcnt(8)
	ds_write2_b32 v8, v40, v41 offset1:1
	v_add_u32_e32 v8, 0x1c78, v84
	ds_write2_b32 v8, v42, v43 offset1:1
	v_add_u32_e32 v8, 0x2080, v84
	s_waitcnt vmcnt(7)
	ds_write2_b32 v8, v44, v45 offset1:1
	v_add_u32_e32 v8, 0x2088, v84
	ds_write2_b32 v8, v46, v47 offset1:1
	v_add_u32_e32 v8, 0x2490, v84
	s_waitcnt vmcnt(6)
	ds_write2_b32 v8, v48, v49 offset1:1
	v_add_u32_e32 v8, 0x2498, v84
	ds_write2_b32 v8, v50, v51 offset1:1
	v_add_u32_e32 v8, 0x28a0, v84
	s_waitcnt vmcnt(5)
	ds_write2_b32 v8, v52, v53 offset1:1
	v_add_u32_e32 v8, 0x28a8, v84
	ds_write2_b32 v8, v54, v55 offset1:1
	v_add_u32_e32 v8, 0x2cb0, v84
	s_waitcnt vmcnt(4)
	ds_write2_b32 v8, v56, v57 offset1:1
	v_add_u32_e32 v8, 0x2cb8, v84
	ds_write2_b32 v8, v58, v59 offset1:1
	v_add_u32_e32 v8, 0x30c0, v84
	s_waitcnt vmcnt(3)
	ds_write2_b32 v8, v60, v61 offset1:1
	v_add_u32_e32 v8, 0x30c8, v84
	ds_write2_b32 v8, v62, v63 offset1:1
	v_add_u32_e32 v8, 0x34d0, v84
	s_waitcnt vmcnt(2)
	ds_write2_b32 v8, v76, v77 offset1:1
	v_add_u32_e32 v8, 0x34d8, v84
	ds_write2_b32 v8, v78, v79 offset1:1
	v_add_u32_e32 v8, 0x38e0, v84
	s_waitcnt vmcnt(1)
	ds_write2_b32 v8, v116, v117 offset1:1
	v_add_u32_e32 v8, 0x38e8, v84
	ds_write2_b32 v8, v118, v119 offset1:1
	v_add_u32_e32 v8, 0x3cf0, v84
	s_waitcnt vmcnt(0)
	ds_write2_b32 v8, v120, v121 offset1:1
	v_add_u32_e32 v8, 0x3cf8, v84
	ds_write2_b32 v8, v122, v123 offset1:1
	s_waitcnt lgkmcnt(0)
	ds_read2_b32 v[18:19], v11 offset0:134 offset1:142
	ds_read2_b32 v[16:17], v11 offset0:199 offset1:207
	ds_read2_b32 v[22:23], v11 offset0:4 offset1:12
	ds_read2_b32 v[20:21], v11 offset0:69 offset1:77
	ds_read2_b32 v[26:27], v86 offset0:130 offset1:138
	s_waitcnt lgkmcnt(4)
	v_bfe_u32 v13, v18, 16, 1
	s_waitcnt lgkmcnt(3)
	v_bfe_u32 v12, v16, 16, 1
	v_add3_u32 v13, v18, v13, s95
	v_add3_u32 v12, v16, v12, s95
	v_lshrrev_b32_e32 v13, 16, v13
	ds_read2_b32 v[24:25], v86 offset0:195 offset1:203
	v_and_or_b32 v15, v12, s96, v13
	s_waitcnt lgkmcnt(3)
	v_bfe_u32 v13, v22, 16, 1
	ds_read2_b32 v[30:31], v86 offset1:8
	s_waitcnt lgkmcnt(3)
	v_bfe_u32 v12, v20, 16, 1
	v_add3_u32 v13, v22, v13, s95
	ds_read2_b32 v[28:29], v86 offset0:65 offset1:73
	v_add3_u32 v12, v20, v12, s95
	v_lshrrev_b32_e32 v13, 16, v13
	v_and_or_b32 v14, v12, s96, v13
	s_waitcnt lgkmcnt(3)
	v_bfe_u32 v13, v26, 16, 1
	s_waitcnt lgkmcnt(2)
	v_bfe_u32 v12, v24, 16, 1
	v_add3_u32 v13, v26, v13, s95
	v_add3_u32 v12, v24, v12, s95
	v_lshrrev_b32_e32 v13, 16, v13
	s_waitcnt lgkmcnt(1)
	v_bfe_u32 v16, v30, 16, 1
	v_and_or_b32 v13, v12, s96, v13
	s_waitcnt lgkmcnt(0)
	v_bfe_u32 v12, v28, 16, 1
	v_add3_u32 v16, v30, v16, s95
	v_add3_u32 v12, v28, v12, s95
	v_lshrrev_b32_e32 v16, 16, v16
	v_and_or_b32 v12, v12, s96, v16
	v_or_b32_e32 v16, v10, v85
	v_lshl_add_u64 v[8:9], v[2:3], 0, v[68:69]
	v_lshlrev_b32_e32 v68, 1, v70
	v_mul_u32_u24_e32 v16, 0xa00, v16
	v_lshl_add_u64 v[8:9], v[8:9], 0, v[68:69]
	v_lshlrev_b32_e32 v68, 1, v16
	v_lshl_add_u64 v[32:33], v[8:9], 0, v[68:69]
	global_store_dwordx4 v[32:33], v[12:15], off offset:2048
	v_bfe_u32 v16, v31, 16, 1
	v_add3_u32 v16, v31, v16, s95
	v_bfe_u32 v13, v19, 16, 1
	v_bfe_u32 v12, v17, 16, 1
	v_add3_u32 v13, v19, v13, s95
	v_add3_u32 v12, v17, v12, s95
	v_lshrrev_b32_e32 v13, 16, v13
	v_and_or_b32 v15, v12, s96, v13
	v_bfe_u32 v13, v23, 16, 1
	v_bfe_u32 v12, v21, 16, 1
	v_add3_u32 v13, v23, v13, s95
	v_add3_u32 v12, v21, v12, s95
	v_lshrrev_b32_e32 v13, 16, v13
	v_and_or_b32 v14, v12, s96, v13
	v_bfe_u32 v13, v27, 16, 1
	v_bfe_u32 v12, v25, 16, 1
	v_add3_u32 v13, v27, v13, s95
	v_add3_u32 v12, v25, v12, s95
	v_lshrrev_b32_e32 v13, 16, v13
	v_and_or_b32 v13, v12, s96, v13
	v_bfe_u32 v12, v29, 16, 1
	v_add3_u32 v12, v29, v12, s95
	v_lshrrev_b32_e32 v16, 16, v16
	v_and_or_b32 v12, v12, s96, v16
	v_or_b32_e32 v16, v10, v87
	v_mul_u32_u24_e32 v18, 0xa00, v16
	v_lshlrev_b32_e32 v68, 1, v18
	ds_read2_b32 v[18:19], v11 offset0:150 offset1:158
	ds_read2_b32 v[16:17], v11 offset0:215 offset1:223
	v_lshl_add_u64 v[20:21], v[8:9], 0, v[68:69]
	ds_read2_b32 v[22:23], v11 offset0:20 offset1:28
	global_store_dwordx4 v[20:21], v[12:15], off offset:2048
	ds_read2_b32 v[20:21], v11 offset0:85 offset1:93
	ds_read2_b32 v[26:27], v86 offset0:146 offset1:154
	s_waitcnt lgkmcnt(4)
	v_bfe_u32 v13, v18, 16, 1
	s_waitcnt lgkmcnt(3)
	v_bfe_u32 v12, v16, 16, 1
	v_add3_u32 v13, v18, v13, s95
	v_add3_u32 v12, v16, v12, s95
	v_lshrrev_b32_e32 v13, 16, v13
	ds_read2_b32 v[24:25], v86 offset0:211 offset1:219
	v_and_or_b32 v15, v12, s96, v13
	s_waitcnt lgkmcnt(3)
	v_bfe_u32 v13, v22, 16, 1
	ds_read2_b32 v[30:31], v86 offset0:16 offset1:24
	s_waitcnt lgkmcnt(3)
	v_bfe_u32 v12, v20, 16, 1
	v_add3_u32 v13, v22, v13, s95
	ds_read2_b32 v[28:29], v86 offset0:81 offset1:89
	v_add3_u32 v12, v20, v12, s95
	v_lshrrev_b32_e32 v13, 16, v13
	v_and_or_b32 v14, v12, s96, v13
	s_waitcnt lgkmcnt(3)
	v_bfe_u32 v13, v26, 16, 1
	s_waitcnt lgkmcnt(2)
	v_bfe_u32 v12, v24, 16, 1
	v_add3_u32 v13, v26, v13, s95
	v_add3_u32 v12, v24, v12, s95
	v_lshrrev_b32_e32 v13, 16, v13
	s_waitcnt lgkmcnt(1)
	v_bfe_u32 v16, v30, 16, 1
	v_and_or_b32 v13, v12, s96, v13
	s_waitcnt lgkmcnt(0)
	v_bfe_u32 v12, v28, 16, 1
	v_add3_u32 v16, v30, v16, s95
	v_add3_u32 v12, v28, v12, s95
	v_lshrrev_b32_e32 v16, 16, v16
	v_and_or_b32 v12, v12, s96, v16
	v_or_b32_e32 v16, v10, v88
	v_mul_u32_u24_e32 v16, 0xa00, v16
	v_lshlrev_b32_e32 v68, 1, v16
	v_lshl_add_u64 v[32:33], v[8:9], 0, v[68:69]
	global_store_dwordx4 v[32:33], v[12:15], off offset:2048
	v_bfe_u32 v16, v31, 16, 1
	v_add3_u32 v16, v31, v16, s95
	v_bfe_u32 v13, v19, 16, 1
	v_bfe_u32 v12, v17, 16, 1
	v_add3_u32 v13, v19, v13, s95
	v_add3_u32 v12, v17, v12, s95
	v_lshrrev_b32_e32 v13, 16, v13
	v_and_or_b32 v15, v12, s96, v13
	v_bfe_u32 v13, v23, 16, 1
	v_bfe_u32 v12, v21, 16, 1
	v_add3_u32 v13, v23, v13, s95
	v_add3_u32 v12, v21, v12, s95
	v_lshrrev_b32_e32 v13, 16, v13
	v_and_or_b32 v14, v12, s96, v13
	v_bfe_u32 v13, v27, 16, 1
	v_bfe_u32 v12, v25, 16, 1
	v_add3_u32 v13, v27, v13, s95
	v_add3_u32 v12, v25, v12, s95
	v_lshrrev_b32_e32 v13, 16, v13
	v_and_or_b32 v13, v12, s96, v13
	v_bfe_u32 v12, v29, 16, 1
	v_add3_u32 v12, v29, v12, s95
	v_lshrrev_b32_e32 v16, 16, v16
	v_and_or_b32 v12, v12, s96, v16
	v_or_b32_e32 v16, v10, v89
	v_mul_u32_u24_e32 v18, 0xa00, v16
	v_lshlrev_b32_e32 v68, 1, v18
	ds_read2_b32 v[18:19], v11 offset0:166 offset1:174
	ds_read2_b32 v[16:17], v11 offset0:231 offset1:239
	v_lshl_add_u64 v[20:21], v[8:9], 0, v[68:69]
	ds_read2_b32 v[22:23], v11 offset0:36 offset1:44
	global_store_dwordx4 v[20:21], v[12:15], off offset:2048
	ds_read2_b32 v[20:21], v11 offset0:101 offset1:109
	ds_read2_b32 v[26:27], v86 offset0:162 offset1:170
	s_waitcnt lgkmcnt(4)
	v_bfe_u32 v13, v18, 16, 1
	s_waitcnt lgkmcnt(3)
	v_bfe_u32 v12, v16, 16, 1
	v_add3_u32 v13, v18, v13, s95
	v_add3_u32 v12, v16, v12, s95
	v_lshrrev_b32_e32 v13, 16, v13
	ds_read2_b32 v[24:25], v86 offset0:227 offset1:235
	v_and_or_b32 v15, v12, s96, v13
	s_waitcnt lgkmcnt(3)
	v_bfe_u32 v13, v22, 16, 1
	ds_read2_b32 v[30:31], v86 offset0:32 offset1:40
	s_waitcnt lgkmcnt(3)
	v_bfe_u32 v12, v20, 16, 1
	v_add3_u32 v13, v22, v13, s95
	ds_read2_b32 v[28:29], v86 offset0:97 offset1:105
	v_add3_u32 v12, v20, v12, s95
	v_lshrrev_b32_e32 v13, 16, v13
	v_and_or_b32 v14, v12, s96, v13
	s_waitcnt lgkmcnt(3)
	v_bfe_u32 v13, v26, 16, 1
	s_waitcnt lgkmcnt(2)
	v_bfe_u32 v12, v24, 16, 1
	v_add3_u32 v13, v26, v13, s95
	v_add3_u32 v12, v24, v12, s95
	v_lshrrev_b32_e32 v13, 16, v13
	s_waitcnt lgkmcnt(1)
	v_bfe_u32 v16, v30, 16, 1
	v_and_or_b32 v13, v12, s96, v13
	s_waitcnt lgkmcnt(0)
	v_bfe_u32 v12, v28, 16, 1
	v_add3_u32 v16, v30, v16, s95
	v_add3_u32 v12, v28, v12, s95
	v_lshrrev_b32_e32 v16, 16, v16
	v_and_or_b32 v12, v12, s96, v16
	v_or_b32_e32 v16, v10, v90
	v_mul_u32_u24_e32 v16, 0xa00, v16
	v_lshlrev_b32_e32 v68, 1, v16
	v_lshl_add_u64 v[32:33], v[8:9], 0, v[68:69]
	global_store_dwordx4 v[32:33], v[12:15], off offset:2048
	v_bfe_u32 v16, v31, 16, 1
	v_add3_u32 v16, v31, v16, s95
	v_bfe_u32 v13, v19, 16, 1
	v_bfe_u32 v12, v17, 16, 1
	v_add3_u32 v13, v19, v13, s95
	v_add3_u32 v12, v17, v12, s95
	v_lshrrev_b32_e32 v13, 16, v13
	v_and_or_b32 v15, v12, s96, v13
	v_bfe_u32 v13, v23, 16, 1
	v_bfe_u32 v12, v21, 16, 1
	v_add3_u32 v13, v23, v13, s95
	v_add3_u32 v12, v21, v12, s95
	v_lshrrev_b32_e32 v13, 16, v13
	v_and_or_b32 v14, v12, s96, v13
	v_bfe_u32 v13, v27, 16, 1
	v_bfe_u32 v12, v25, 16, 1
	v_add3_u32 v13, v27, v13, s95
	v_add3_u32 v12, v25, v12, s95
	v_lshrrev_b32_e32 v13, 16, v13
	v_and_or_b32 v13, v12, s96, v13
	v_bfe_u32 v12, v29, 16, 1
	v_add3_u32 v12, v29, v12, s95
	v_lshrrev_b32_e32 v16, 16, v16
	v_and_or_b32 v12, v12, s96, v16
	v_or_b32_e32 v16, v10, v91
	v_mul_u32_u24_e32 v18, 0xa00, v16
	v_lshlrev_b32_e32 v68, 1, v18
	ds_read2_b32 v[18:19], v11 offset0:182 offset1:190
	ds_read2_b32 v[16:17], v11 offset0:247 offset1:255
	v_lshl_add_u64 v[20:21], v[8:9], 0, v[68:69]
	ds_read2_b32 v[22:23], v11 offset0:52 offset1:60
	global_store_dwordx4 v[20:21], v[12:15], off offset:2048
	ds_read2_b32 v[20:21], v11 offset0:117 offset1:125
	ds_read2_b32 v[26:27], v86 offset0:178 offset1:186
	s_waitcnt lgkmcnt(4)
	v_bfe_u32 v13, v18, 16, 1
	s_waitcnt lgkmcnt(3)
	v_bfe_u32 v12, v16, 16, 1
	v_add3_u32 v13, v18, v13, s95
	v_add3_u32 v12, v16, v12, s95
	v_lshrrev_b32_e32 v11, 16, v13
	ds_read2_b32 v[24:25], v86 offset0:243 offset1:251
	v_and_or_b32 v15, v12, s96, v11
	s_waitcnt lgkmcnt(3)
	v_bfe_u32 v12, v22, 16, 1
	s_waitcnt lgkmcnt(2)
	v_bfe_u32 v11, v20, 16, 1
	v_add3_u32 v12, v22, v12, s95
	ds_read2_b32 v[30:31], v86 offset0:48 offset1:56
	v_add3_u32 v11, v20, v11, s95
	v_lshrrev_b32_e32 v12, 16, v12
	ds_read2_b32 v[28:29], v86 offset0:113 offset1:121
	v_and_or_b32 v14, v11, s96, v12
	s_waitcnt lgkmcnt(3)
	v_bfe_u32 v12, v26, 16, 1
	s_waitcnt lgkmcnt(2)
	v_bfe_u32 v11, v24, 16, 1
	v_add3_u32 v12, v26, v12, s95
	v_add3_u32 v11, v24, v11, s95
	v_lshrrev_b32_e32 v12, 16, v12
	v_and_or_b32 v13, v11, s96, v12
	s_waitcnt lgkmcnt(1)
	v_bfe_u32 v12, v30, 16, 1
	s_waitcnt lgkmcnt(0)
	v_bfe_u32 v11, v28, 16, 1
	v_add3_u32 v12, v30, v12, s95
	v_add3_u32 v11, v28, v11, s95
	v_lshrrev_b32_e32 v12, 16, v12
	v_and_or_b32 v12, v11, s96, v12
	v_or_b32_e32 v11, v10, v92
	v_mul_u32_u24_e32 v11, 0xa00, v11
	v_lshlrev_b32_e32 v68, 1, v11
	v_lshl_add_u64 v[32:33], v[8:9], 0, v[68:69]
	global_store_dwordx4 v[32:33], v[12:15], off offset:2048
	v_bfe_u32 v11, v17, 16, 1
	v_add3_u32 v11, v17, v11, s95
	v_bfe_u32 v12, v19, 16, 1
	v_add3_u32 v12, v19, v12, s95
	v_lshrrev_b32_e32 v12, 16, v12
	v_and_or_b32 v15, v11, s96, v12
	v_bfe_u32 v12, v23, 16, 1
	v_bfe_u32 v11, v21, 16, 1
	v_add3_u32 v12, v23, v12, s95
	v_add3_u32 v11, v21, v11, s95
	v_lshrrev_b32_e32 v12, 16, v12
	v_and_or_b32 v14, v11, s96, v12
	v_bfe_u32 v12, v27, 16, 1
	v_bfe_u32 v11, v25, 16, 1
	v_add3_u32 v12, v27, v12, s95
	v_add3_u32 v11, v25, v11, s95
	v_lshrrev_b32_e32 v12, 16, v12
	v_and_or_b32 v13, v11, s96, v12
	v_bfe_u32 v12, v31, 16, 1
	v_or_b32_e32 v10, v10, v93
	v_bfe_u32 v11, v29, 16, 1
	v_add3_u32 v12, v31, v12, s95
	v_mul_u32_u24_e32 v10, 0xa00, v10
	v_add3_u32 v11, v29, v11, s95
	v_lshrrev_b32_e32 v12, 16, v12
	v_lshlrev_b32_e32 v68, 1, v10
	v_and_or_b32 v12, v11, s96, v12
	v_lshl_add_u64 v[8:9], v[8:9], 0, v[68:69]
	global_store_dwordx4 v[8:9], v[12:15], off offset:2048
	s_waitcnt lgkmcnt(0)
	s_or_b64 exec, exec, s[4:5]
	s_and_b64 exec, exec, s[2:3]
	s_cbranch_execz .LBB0_95

.LBB0_31:
	v_lshl_add_u64 v[8:9], v[6:7], 2, s[42:43]
	v_lshlrev_b32_e32 v7, 1, v81
	v_and_b32_e32 v7, 0x3c0, v7
	v_lshlrev_b32_e32 v6, 6, v81
	v_or_b32_e32 v10, v7, v83
	v_and_b32_e32 v6, 0x7c0, v6
	v_lshlrev_b32_e32 v68, 13, v10
	v_lshl_add_u64 v[8:9], v[8:9], 0, v[68:69]
	v_lshlrev_b32_e32 v68, 2, v6
	v_lshl_add_u64 v[8:9], v[8:9], 0, v[68:69]
	v_mov_b32_e32 v73, v69
	v_lshl_add_u64 v[64:65], v[8:9], 0, v[72:73]
	v_add_co_u32_e32 v12, vcc, s78, v64
	v_lshlrev_b32_e32 v68, 1, v7
	s_nop 0
	v_addc_co_u32_e32 v13, vcc, 0, v65, vcc
	v_add_co_u32_e32 v16, vcc, s79, v64
	global_load_dwordx4 v[8:11], v[64:65], off nt
	s_nop 0
	global_load_dwordx4 v[12:15], v[12:13], off nt
	v_addc_co_u32_e32 v17, vcc, 0, v65, vcc
	v_add_co_u32_e32 v20, vcc, s82, v64
	v_add_u32_e32 v7, 0x400, v86
	s_nop 0
	v_addc_co_u32_e32 v21, vcc, 0, v65, vcc
	v_add_co_u32_e32 v24, vcc, s83, v64
	global_load_dwordx4 v[16:19], v[16:17], off nt
	s_nop 0
	global_load_dwordx4 v[20:23], v[20:21], off nt
	v_addc_co_u32_e32 v25, vcc, 0, v65, vcc
	v_add_co_u32_e32 v28, vcc, s84, v64
	v_lshl_add_u64 v[2:3], v[2:3], 0, v[68:69]
	s_nop 0
	v_addc_co_u32_e32 v29, vcc, 0, v65, vcc
	v_add_co_u32_e32 v32, vcc, s85, v64
	global_load_dwordx4 v[24:27], v[24:25], off nt
	s_nop 0
	global_load_dwordx4 v[28:31], v[28:29], off nt
	v_addc_co_u32_e32 v33, vcc, 0, v65, vcc
	v_add_co_u32_e32 v36, vcc, s86, v64
	v_lshlrev_b32_e32 v68, 1, v70
	s_nop 0
	v_addc_co_u32_e32 v37, vcc, 0, v65, vcc
	global_load_dwordx4 v[32:35], v[32:33], off nt
	s_nop 0
	global_load_dwordx4 v[36:39], v[36:37], off nt
	v_add_co_u32_e32 v40, vcc, s87, v64
	v_lshl_add_u64 v[2:3], v[2:3], 0, v[68:69]
	s_nop 0
	v_addc_co_u32_e32 v41, vcc, 0, v65, vcc
	v_add_co_u32_e32 v44, vcc, s88, v64
	s_nop 1
	v_addc_co_u32_e32 v45, vcc, 0, v65, vcc
	global_load_dwordx4 v[40:43], v[40:41], off nt
	s_nop 0
	global_load_dwordx4 v[44:47], v[44:45], off nt
	v_add_co_u32_e32 v48, vcc, s89, v64
	s_nop 1
	v_addc_co_u32_e32 v49, vcc, 0, v65, vcc
	v_add_co_u32_e32 v52, vcc, s90, v64
	s_nop 1
	v_addc_co_u32_e32 v53, vcc, 0, v65, vcc
	global_load_dwordx4 v[48:51], v[48:49], off nt
	s_nop 0
	global_load_dwordx4 v[52:55], v[52:53], off nt
	v_add_co_u32_e32 v56, vcc, s91, v64
	s_nop 1
	v_addc_co_u32_e32 v57, vcc, 0, v65, vcc
	v_add_co_u32_e32 v60, vcc, s92, v64
	s_nop 1
	v_addc_co_u32_e32 v61, vcc, 0, v65, vcc
	global_load_dwordx4 v[56:59], v[56:57], off nt
	s_nop 0
	global_load_dwordx4 v[60:63], v[60:61], off nt
	v_add_co_u32_e32 v76, vcc, s93, v64
	s_nop 1
	v_addc_co_u32_e32 v77, vcc, 0, v65, vcc
	global_load_dwordx4 v[76:79], v[76:77], off nt
	v_add_co_u32_e32 v64, vcc, s94, v64
	s_nop 1
	v_addc_co_u32_e32 v65, vcc, 0, v65, vcc
	global_load_dwordx4 v[116:119], v[64:65], off nt
	s_waitcnt vmcnt(15)
	ds_write2_b32 v84, v8, v9 offset1:1
	ds_write2_b32 v84, v10, v11 offset0:2 offset1:3
	s_waitcnt vmcnt(14)
	ds_write2_b32 v103, v12, v13 offset1:1
	ds_write2_b32 v104, v14, v15 offset1:1
	s_waitcnt vmcnt(13)
	ds_write2_b32 v105, v16, v17 offset1:1
	ds_write2_b32 v106, v18, v19 offset1:1
	s_waitcnt vmcnt(12)
	ds_write2_b32 v107, v20, v21 offset1:1
	ds_write2_b32 v108, v22, v23 offset1:1
	s_waitcnt vmcnt(11)
	ds_write2_b32 v109, v24, v25 offset1:1
	ds_write2_b32 v110, v26, v27 offset1:1
	s_waitcnt vmcnt(10)
	ds_write2_b32 v111, v28, v29 offset1:1
	v_add_u32_e32 v8, 0x1458, v84
	ds_write2_b32 v8, v30, v31 offset1:1
	v_add_u32_e32 v8, 0x1860, v84
	s_waitcnt vmcnt(9)
	ds_write2_b32 v8, v32, v33 offset1:1
	v_add_u32_e32 v8, 0x1868, v84
	ds_write2_b32 v8, v34, v35 offset1:1
	v_add_u32_e32 v8, 0x1c70, v84
	s_waitcnt vmcnt(8)
	ds_write2_b32 v8, v36, v37 offset1:1
	v_add_u32_e32 v8, 0x1c78, v84
	ds_write2_b32 v8, v38, v39 offset1:1
	v_add_u32_e32 v8, 0x2080, v84
	s_waitcnt vmcnt(7)
	ds_write2_b32 v8, v40, v41 offset1:1
	v_add_u32_e32 v8, 0x2088, v84
	ds_write2_b32 v8, v42, v43 offset1:1
	v_add_u32_e32 v8, 0x2490, v84
	s_waitcnt vmcnt(6)
	ds_write2_b32 v8, v44, v45 offset1:1
	v_add_u32_e32 v8, 0x2498, v84
	ds_write2_b32 v8, v46, v47 offset1:1
	v_add_u32_e32 v8, 0x28a0, v84
	s_waitcnt vmcnt(5)
	ds_write2_b32 v8, v48, v49 offset1:1
	v_add_u32_e32 v8, 0x28a8, v84
	ds_write2_b32 v8, v50, v51 offset1:1
	v_add_u32_e32 v8, 0x2cb0, v84
	s_waitcnt vmcnt(4)
	ds_write2_b32 v8, v52, v53 offset1:1
	v_add_u32_e32 v8, 0x2cb8, v84
	ds_write2_b32 v8, v54, v55 offset1:1
	v_add_u32_e32 v8, 0x30c0, v84
	s_waitcnt vmcnt(3)
	ds_write2_b32 v8, v56, v57 offset1:1
	v_add_u32_e32 v8, 0x30c8, v84
	ds_write2_b32 v8, v58, v59 offset1:1
	v_add_u32_e32 v8, 0x34d0, v84
	s_waitcnt vmcnt(2)
	ds_write2_b32 v8, v60, v61 offset1:1
	v_add_u32_e32 v8, 0x34d8, v84
	ds_write2_b32 v8, v62, v63 offset1:1
	v_add_u32_e32 v8, 0x38e0, v84
	s_waitcnt vmcnt(1)
	ds_write2_b32 v8, v76, v77 offset1:1
	v_add_u32_e32 v8, 0x38e8, v84
	ds_write2_b32 v8, v78, v79 offset1:1
	v_add_u32_e32 v8, 0x3cf0, v84
	s_waitcnt vmcnt(0)
	ds_write2_b32 v8, v116, v117 offset1:1
	v_add_u32_e32 v8, 0x3cf8, v84
	ds_write2_b32 v8, v118, v119 offset1:1
	s_waitcnt lgkmcnt(0)
	ds_read2_b32 v[14:15], v7 offset0:134 offset1:142
	ds_read2_b32 v[12:13], v7 offset0:199 offset1:207
	ds_read2_b32 v[18:19], v7 offset0:4 offset1:12
	ds_read2_b32 v[16:17], v7 offset0:69 offset1:77
	ds_read2_b32 v[22:23], v86 offset0:130 offset1:138
	s_waitcnt lgkmcnt(4)
	v_bfe_u32 v9, v14, 16, 1
	s_waitcnt lgkmcnt(3)
	v_bfe_u32 v8, v12, 16, 1
	v_add3_u32 v9, v14, v9, s95
	v_add3_u32 v8, v12, v8, s95
	v_lshrrev_b32_e32 v9, 16, v9
	ds_read2_b32 v[20:21], v86 offset0:195 offset1:203
	v_and_or_b32 v11, v8, s96, v9
	s_waitcnt lgkmcnt(3)
	v_bfe_u32 v9, v18, 16, 1
	ds_read2_b32 v[26:27], v86 offset1:8
	s_waitcnt lgkmcnt(3)
	v_bfe_u32 v8, v16, 16, 1
	v_add3_u32 v9, v18, v9, s95
	ds_read2_b32 v[24:25], v86 offset0:65 offset1:73
	v_add3_u32 v8, v16, v8, s95
	v_lshrrev_b32_e32 v9, 16, v9
	v_and_or_b32 v10, v8, s96, v9
	s_waitcnt lgkmcnt(3)
	v_bfe_u32 v9, v22, 16, 1
	s_waitcnt lgkmcnt(2)
	v_bfe_u32 v8, v20, 16, 1
	v_add3_u32 v9, v22, v9, s95
	v_add3_u32 v8, v20, v8, s95
	v_lshrrev_b32_e32 v9, 16, v9
	s_waitcnt lgkmcnt(1)
	v_bfe_u32 v12, v26, 16, 1
	v_and_or_b32 v9, v8, s96, v9
	s_waitcnt lgkmcnt(0)
	v_bfe_u32 v8, v24, 16, 1
	v_add3_u32 v12, v26, v12, s95
	v_add3_u32 v8, v24, v8, s95
	v_lshrrev_b32_e32 v12, 16, v12
	v_and_or_b32 v8, v8, s96, v12
	v_or_b32_e32 v12, v6, v85
	v_mul_u32_u24_e32 v12, 0xa00, v12
	v_lshlrev_b32_e32 v68, 1, v12
	v_lshl_add_u64 v[28:29], v[2:3], 0, v[68:69]
	global_store_dwordx4 v[28:29], v[8:11], off offset:3072
	v_bfe_u32 v12, v27, 16, 1
	v_add3_u32 v12, v27, v12, s95
	v_bfe_u32 v9, v15, 16, 1
	v_bfe_u32 v8, v13, 16, 1
	v_add3_u32 v9, v15, v9, s95
	v_add3_u32 v8, v13, v8, s95
	v_lshrrev_b32_e32 v9, 16, v9
	v_and_or_b32 v11, v8, s96, v9
	v_bfe_u32 v9, v19, 16, 1
	v_bfe_u32 v8, v17, 16, 1
	v_add3_u32 v9, v19, v9, s95
	v_add3_u32 v8, v17, v8, s95
	v_lshrrev_b32_e32 v9, 16, v9
	v_and_or_b32 v10, v8, s96, v9
	v_bfe_u32 v9, v23, 16, 1
	v_bfe_u32 v8, v21, 16, 1
	v_add3_u32 v9, v23, v9, s95
	v_add3_u32 v8, v21, v8, s95
	v_lshrrev_b32_e32 v9, 16, v9
	v_and_or_b32 v9, v8, s96, v9
	v_bfe_u32 v8, v25, 16, 1
	v_add3_u32 v8, v25, v8, s95
	v_lshrrev_b32_e32 v12, 16, v12
	v_and_or_b32 v8, v8, s96, v12
	v_or_b32_e32 v12, v6, v87
	v_mul_u32_u24_e32 v14, 0xa00, v12
	v_lshlrev_b32_e32 v68, 1, v14
	ds_read2_b32 v[14:15], v7 offset0:150 offset1:158
	ds_read2_b32 v[12:13], v7 offset0:215 offset1:223
	v_lshl_add_u64 v[16:17], v[2:3], 0, v[68:69]
	ds_read2_b32 v[18:19], v7 offset0:20 offset1:28
	global_store_dwordx4 v[16:17], v[8:11], off offset:3072
	ds_read2_b32 v[16:17], v7 offset0:85 offset1:93
	ds_read2_b32 v[22:23], v86 offset0:146 offset1:154
	s_waitcnt lgkmcnt(4)
	v_bfe_u32 v9, v14, 16, 1
	s_waitcnt lgkmcnt(3)
	v_bfe_u32 v8, v12, 16, 1
	v_add3_u32 v9, v14, v9, s95
	v_add3_u32 v8, v12, v8, s95
	v_lshrrev_b32_e32 v9, 16, v9
	ds_read2_b32 v[20:21], v86 offset0:211 offset1:219
	v_and_or_b32 v11, v8, s96, v9
	s_waitcnt lgkmcnt(3)
	v_bfe_u32 v9, v18, 16, 1
	ds_read2_b32 v[26:27], v86 offset0:16 offset1:24
	s_waitcnt lgkmcnt(3)
	v_bfe_u32 v8, v16, 16, 1
	v_add3_u32 v9, v18, v9, s95
	ds_read2_b32 v[24:25], v86 offset0:81 offset1:89
	v_add3_u32 v8, v16, v8, s95
	v_lshrrev_b32_e32 v9, 16, v9
	v_and_or_b32 v10, v8, s96, v9
	s_waitcnt lgkmcnt(3)
	v_bfe_u32 v9, v22, 16, 1
	s_waitcnt lgkmcnt(2)
	v_bfe_u32 v8, v20, 16, 1
	v_add3_u32 v9, v22, v9, s95
	v_add3_u32 v8, v20, v8, s95
	v_lshrrev_b32_e32 v9, 16, v9
	s_waitcnt lgkmcnt(1)
	v_bfe_u32 v12, v26, 16, 1
	v_and_or_b32 v9, v8, s96, v9
	s_waitcnt lgkmcnt(0)
	v_bfe_u32 v8, v24, 16, 1
	v_add3_u32 v12, v26, v12, s95
	v_add3_u32 v8, v24, v8, s95
	v_lshrrev_b32_e32 v12, 16, v12
	v_and_or_b32 v8, v8, s96, v12
	v_or_b32_e32 v12, v6, v88
	v_mul_u32_u24_e32 v12, 0xa00, v12
	v_lshlrev_b32_e32 v68, 1, v12
	v_lshl_add_u64 v[28:29], v[2:3], 0, v[68:69]
	global_store_dwordx4 v[28:29], v[8:11], off offset:3072
	v_bfe_u32 v12, v27, 16, 1
	v_add3_u32 v12, v27, v12, s95
	v_bfe_u32 v9, v15, 16, 1
	v_bfe_u32 v8, v13, 16, 1
	v_add3_u32 v9, v15, v9, s95
	v_add3_u32 v8, v13, v8, s95
	v_lshrrev_b32_e32 v9, 16, v9
	v_and_or_b32 v11, v8, s96, v9
	v_bfe_u32 v9, v19, 16, 1
	v_bfe_u32 v8, v17, 16, 1
	v_add3_u32 v9, v19, v9, s95
	v_add3_u32 v8, v17, v8, s95
	v_lshrrev_b32_e32 v9, 16, v9
	v_and_or_b32 v10, v8, s96, v9
	v_bfe_u32 v9, v23, 16, 1
	v_bfe_u32 v8, v21, 16, 1
	v_add3_u32 v9, v23, v9, s95
	v_add3_u32 v8, v21, v8, s95
	v_lshrrev_b32_e32 v9, 16, v9
	v_and_or_b32 v9, v8, s96, v9
	v_bfe_u32 v8, v25, 16, 1
	v_add3_u32 v8, v25, v8, s95
	v_lshrrev_b32_e32 v12, 16, v12
	v_and_or_b32 v8, v8, s96, v12
	v_or_b32_e32 v12, v6, v89
	v_mul_u32_u24_e32 v14, 0xa00, v12
	v_lshlrev_b32_e32 v68, 1, v14
	ds_read2_b32 v[14:15], v7 offset0:166 offset1:174
	ds_read2_b32 v[12:13], v7 offset0:231 offset1:239
	v_lshl_add_u64 v[16:17], v[2:3], 0, v[68:69]
	ds_read2_b32 v[18:19], v7 offset0:36 offset1:44
	global_store_dwordx4 v[16:17], v[8:11], off offset:3072
	ds_read2_b32 v[16:17], v7 offset0:101 offset1:109
	ds_read2_b32 v[22:23], v86 offset0:162 offset1:170
	s_waitcnt lgkmcnt(4)
	v_bfe_u32 v9, v14, 16, 1
	s_waitcnt lgkmcnt(3)
	v_bfe_u32 v8, v12, 16, 1
	v_add3_u32 v9, v14, v9, s95
	v_add3_u32 v8, v12, v8, s95
	v_lshrrev_b32_e32 v9, 16, v9
	ds_read2_b32 v[20:21], v86 offset0:227 offset1:235
	v_and_or_b32 v11, v8, s96, v9
	s_waitcnt lgkmcnt(3)
	v_bfe_u32 v9, v18, 16, 1
	ds_read2_b32 v[26:27], v86 offset0:32 offset1:40
	s_waitcnt lgkmcnt(3)
	v_bfe_u32 v8, v16, 16, 1
	v_add3_u32 v9, v18, v9, s95
	ds_read2_b32 v[24:25], v86 offset0:97 offset1:105
	v_add3_u32 v8, v16, v8, s95
	v_lshrrev_b32_e32 v9, 16, v9
	v_and_or_b32 v10, v8, s96, v9
	s_waitcnt lgkmcnt(3)
	v_bfe_u32 v9, v22, 16, 1
	s_waitcnt lgkmcnt(2)
	v_bfe_u32 v8, v20, 16, 1
	v_add3_u32 v9, v22, v9, s95
	v_add3_u32 v8, v20, v8, s95
	v_lshrrev_b32_e32 v9, 16, v9
	s_waitcnt lgkmcnt(1)
	v_bfe_u32 v12, v26, 16, 1
	v_and_or_b32 v9, v8, s96, v9
	s_waitcnt lgkmcnt(0)
	v_bfe_u32 v8, v24, 16, 1
	v_add3_u32 v12, v26, v12, s95
	v_add3_u32 v8, v24, v8, s95
	v_lshrrev_b32_e32 v12, 16, v12
	v_and_or_b32 v8, v8, s96, v12
	v_or_b32_e32 v12, v6, v90
	v_mul_u32_u24_e32 v12, 0xa00, v12
	v_lshlrev_b32_e32 v68, 1, v12
	v_lshl_add_u64 v[28:29], v[2:3], 0, v[68:69]
	global_store_dwordx4 v[28:29], v[8:11], off offset:3072
	v_bfe_u32 v12, v27, 16, 1
	v_add3_u32 v12, v27, v12, s95
	v_bfe_u32 v9, v15, 16, 1
	v_bfe_u32 v8, v13, 16, 1
	v_add3_u32 v9, v15, v9, s95
	v_add3_u32 v8, v13, v8, s95
	v_lshrrev_b32_e32 v9, 16, v9
	v_and_or_b32 v11, v8, s96, v9
	v_bfe_u32 v9, v19, 16, 1
	v_bfe_u32 v8, v17, 16, 1
	v_add3_u32 v9, v19, v9, s95
	v_add3_u32 v8, v17, v8, s95
	v_lshrrev_b32_e32 v9, 16, v9
	v_and_or_b32 v10, v8, s96, v9
	v_bfe_u32 v9, v23, 16, 1
	v_bfe_u32 v8, v21, 16, 1
	v_add3_u32 v9, v23, v9, s95
	v_add3_u32 v8, v21, v8, s95
	v_lshrrev_b32_e32 v9, 16, v9
	v_and_or_b32 v9, v8, s96, v9
	v_bfe_u32 v8, v25, 16, 1
	v_add3_u32 v8, v25, v8, s95
	v_lshrrev_b32_e32 v12, 16, v12
	v_and_or_b32 v8, v8, s96, v12
	v_or_b32_e32 v12, v6, v91
	v_mul_u32_u24_e32 v14, 0xa00, v12
	v_lshlrev_b32_e32 v68, 1, v14
	ds_read2_b32 v[14:15], v7 offset0:182 offset1:190
	ds_read2_b32 v[12:13], v7 offset0:247 offset1:255
	v_lshl_add_u64 v[16:17], v[2:3], 0, v[68:69]
	ds_read2_b32 v[18:19], v7 offset0:52 offset1:60
	global_store_dwordx4 v[16:17], v[8:11], off offset:3072
	ds_read2_b32 v[16:17], v7 offset0:117 offset1:125
	ds_read2_b32 v[22:23], v86 offset0:178 offset1:186
	s_waitcnt lgkmcnt(4)
	v_bfe_u32 v9, v14, 16, 1
	s_waitcnt lgkmcnt(3)
	v_bfe_u32 v8, v12, 16, 1
	v_add3_u32 v9, v14, v9, s95
	v_add3_u32 v8, v12, v8, s95
	v_lshrrev_b32_e32 v7, 16, v9
	ds_read2_b32 v[20:21], v86 offset0:243 offset1:251
	v_and_or_b32 v11, v8, s96, v7
	s_waitcnt lgkmcnt(3)
	v_bfe_u32 v8, v18, 16, 1
	s_waitcnt lgkmcnt(2)
	v_bfe_u32 v7, v16, 16, 1
	v_add3_u32 v8, v18, v8, s95
	ds_read2_b32 v[26:27], v86 offset0:48 offset1:56
	v_add3_u32 v7, v16, v7, s95
	v_lshrrev_b32_e32 v8, 16, v8
	ds_read2_b32 v[24:25], v86 offset0:113 offset1:121
	v_and_or_b32 v10, v7, s96, v8
	s_waitcnt lgkmcnt(3)
	v_bfe_u32 v8, v22, 16, 1
	s_waitcnt lgkmcnt(2)
	v_bfe_u32 v7, v20, 16, 1
	v_add3_u32 v8, v22, v8, s95
	v_add3_u32 v7, v20, v7, s95
	v_lshrrev_b32_e32 v8, 16, v8
	v_and_or_b32 v9, v7, s96, v8
	s_waitcnt lgkmcnt(1)
	v_bfe_u32 v8, v26, 16, 1
	s_waitcnt lgkmcnt(0)
	v_bfe_u32 v7, v24, 16, 1
	v_add3_u32 v8, v26, v8, s95
	v_add3_u32 v7, v24, v7, s95
	v_lshrrev_b32_e32 v8, 16, v8
	v_and_or_b32 v8, v7, s96, v8
	v_or_b32_e32 v7, v6, v92
	v_mul_u32_u24_e32 v7, 0xa00, v7
	v_lshlrev_b32_e32 v68, 1, v7
	v_lshl_add_u64 v[28:29], v[2:3], 0, v[68:69]
	global_store_dwordx4 v[28:29], v[8:11], off offset:3072
	v_bfe_u32 v7, v13, 16, 1
	v_add3_u32 v7, v13, v7, s95
	v_bfe_u32 v8, v15, 16, 1
	v_add3_u32 v8, v15, v8, s95
	v_lshrrev_b32_e32 v8, 16, v8
	v_and_or_b32 v11, v7, s96, v8
	v_bfe_u32 v8, v19, 16, 1
	v_bfe_u32 v7, v17, 16, 1
	v_add3_u32 v8, v19, v8, s95
	v_add3_u32 v7, v17, v7, s95
	v_lshrrev_b32_e32 v8, 16, v8
	v_and_or_b32 v10, v7, s96, v8
	v_bfe_u32 v8, v23, 16, 1
	v_bfe_u32 v7, v21, 16, 1
	v_add3_u32 v8, v23, v8, s95
	v_add3_u32 v7, v21, v7, s95
	v_lshrrev_b32_e32 v8, 16, v8
	v_and_or_b32 v9, v7, s96, v8
	v_bfe_u32 v8, v27, 16, 1
	v_or_b32_e32 v6, v6, v93
	v_bfe_u32 v7, v25, 16, 1
	v_add3_u32 v8, v27, v8, s95
	v_mul_u32_u24_e32 v6, 0xa00, v6
	v_add3_u32 v7, v25, v7, s95
	v_lshrrev_b32_e32 v8, 16, v8
	v_lshlrev_b32_e32 v68, 1, v6
	v_and_or_b32 v8, v7, s96, v8
	v_lshl_add_u64 v[2:3], v[2:3], 0, v[68:69]
	global_store_dwordx4 v[2:3], v[8:11], off offset:3072
	s_waitcnt lgkmcnt(0)
	s_or_b64 exec, exec, s[4:5]
	s_and_b64 exec, exec, s[2:3]
	s_cbranch_execz .LBB0_95

.LBB0_36:
	v_lshlrev_b32_e32 v7, 1, v81
	v_and_b32_e32 v7, 0x7c0, v7
	v_lshlrev_b32_e32 v6, 6, v81
	v_or_b32_e32 v8, v7, v83
	v_lshl_add_u64 v[2:3], v[4:5], 2, s[44:45]
	v_and_b32_e32 v6, 0x7c0, v6
	v_lshlrev_b32_e32 v68, 13, v8
	v_lshl_add_u64 v[2:3], v[2:3], 0, v[68:69]
	v_lshlrev_b32_e32 v68, 2, v6
	v_lshl_add_u64 v[2:3], v[2:3], 0, v[68:69]
	v_mov_b32_e32 v73, v69
	v_lshl_add_u64 v[2:3], v[2:3], 0, v[72:73]
	v_add_co_u32_e32 v12, vcc, s78, v2
	v_lshlrev_b32_e32 v68, 1, v7
	s_nop 0
	v_addc_co_u32_e32 v13, vcc, 0, v3, vcc
	v_add_co_u32_e32 v16, vcc, s79, v2
	global_load_dwordx4 v[8:11], v[2:3], off nt
	s_nop 0
	global_load_dwordx4 v[12:15], v[12:13], off nt
	v_addc_co_u32_e32 v17, vcc, 0, v3, vcc
	v_add_co_u32_e32 v20, vcc, s82, v2
	v_add_u32_e32 v7, 0x400, v86
	s_nop 0
	v_addc_co_u32_e32 v21, vcc, 0, v3, vcc
	v_add_co_u32_e32 v24, vcc, s83, v2
	global_load_dwordx4 v[16:19], v[16:17], off nt
	s_nop 0
	global_load_dwordx4 v[20:23], v[20:21], off nt
	v_addc_co_u32_e32 v25, vcc, 0, v3, vcc
	v_add_co_u32_e32 v28, vcc, s84, v2
	s_nop 1
	v_addc_co_u32_e32 v29, vcc, 0, v3, vcc
	v_add_co_u32_e32 v32, vcc, s85, v2
	global_load_dwordx4 v[24:27], v[24:25], off nt
	s_nop 0
	global_load_dwordx4 v[28:31], v[28:29], off nt
	v_addc_co_u32_e32 v33, vcc, 0, v3, vcc
	v_add_co_u32_e32 v36, vcc, s86, v2
	s_nop 1
	v_addc_co_u32_e32 v37, vcc, 0, v3, vcc
	global_load_dwordx4 v[32:35], v[32:33], off nt
	s_nop 0
	global_load_dwordx4 v[36:39], v[36:37], off nt
	v_add_co_u32_e32 v40, vcc, s87, v2
	s_nop 1
	v_addc_co_u32_e32 v41, vcc, 0, v3, vcc
	v_add_co_u32_e32 v44, vcc, s88, v2
	s_nop 1
	v_addc_co_u32_e32 v45, vcc, 0, v3, vcc
	global_load_dwordx4 v[40:43], v[40:41], off nt
	s_nop 0
	global_load_dwordx4 v[44:47], v[44:45], off nt
	v_add_co_u32_e32 v48, vcc, s89, v2
	s_nop 1
	v_addc_co_u32_e32 v49, vcc, 0, v3, vcc
	v_add_co_u32_e32 v52, vcc, s90, v2
	s_nop 1
	v_addc_co_u32_e32 v53, vcc, 0, v3, vcc
	global_load_dwordx4 v[48:51], v[48:49], off nt
	s_nop 0
	global_load_dwordx4 v[52:55], v[52:53], off nt
	v_add_co_u32_e32 v56, vcc, s91, v2
	s_nop 1
	v_addc_co_u32_e32 v57, vcc, 0, v3, vcc
	v_add_co_u32_e32 v60, vcc, s92, v2
	s_nop 1
	v_addc_co_u32_e32 v61, vcc, 0, v3, vcc
	global_load_dwordx4 v[56:59], v[56:57], off nt
	s_nop 0
	global_load_dwordx4 v[60:63], v[60:61], off nt
	v_add_co_u32_e32 v64, vcc, s93, v2
	s_nop 1
	v_addc_co_u32_e32 v65, vcc, 0, v3, vcc
	global_load_dwordx4 v[76:79], v[64:65], off nt
	v_add_co_u32_e32 v2, vcc, s94, v2
	s_nop 1
	v_addc_co_u32_e32 v3, vcc, 0, v3, vcc
	global_load_dwordx4 v[116:119], v[2:3], off nt
	v_lshl_add_u64 v[2:3], v[4:5], 1, s[28:29]
	v_add_u32_e32 v4, 0x1458, v84
	v_lshl_add_u64 v[2:3], v[2:3], 0, v[68:69]
	v_lshlrev_b32_e32 v68, 1, v70
	s_waitcnt vmcnt(15)
	ds_write2_b32 v84, v8, v9 offset1:1
	ds_write2_b32 v84, v10, v11 offset0:2 offset1:3
	s_waitcnt vmcnt(14)
	ds_write2_b32 v103, v12, v13 offset1:1
	ds_write2_b32 v104, v14, v15 offset1:1
	s_waitcnt vmcnt(13)
	ds_write2_b32 v105, v16, v17 offset1:1
	ds_write2_b32 v106, v18, v19 offset1:1
	s_waitcnt vmcnt(12)
	ds_write2_b32 v107, v20, v21 offset1:1
	ds_write2_b32 v108, v22, v23 offset1:1
	s_waitcnt vmcnt(11)
	ds_write2_b32 v109, v24, v25 offset1:1
	ds_write2_b32 v110, v26, v27 offset1:1
	s_waitcnt vmcnt(10)
	ds_write2_b32 v111, v28, v29 offset1:1
	ds_write2_b32 v4, v30, v31 offset1:1
	v_add_u32_e32 v4, 0x1860, v84
	v_lshl_add_u64 v[2:3], v[2:3], 0, v[68:69]
	s_waitcnt vmcnt(9)
	ds_write2_b32 v4, v32, v33 offset1:1
	v_add_u32_e32 v4, 0x1868, v84
	ds_write2_b32 v4, v34, v35 offset1:1
	v_add_u32_e32 v4, 0x1c70, v84
	s_waitcnt vmcnt(8)
	ds_write2_b32 v4, v36, v37 offset1:1
	v_add_u32_e32 v4, 0x1c78, v84
	ds_write2_b32 v4, v38, v39 offset1:1
	v_add_u32_e32 v4, 0x2080, v84
	s_waitcnt vmcnt(7)
	ds_write2_b32 v4, v40, v41 offset1:1
	v_add_u32_e32 v4, 0x2088, v84
	ds_write2_b32 v4, v42, v43 offset1:1
	v_add_u32_e32 v4, 0x2490, v84
	s_waitcnt vmcnt(6)
	ds_write2_b32 v4, v44, v45 offset1:1
	v_add_u32_e32 v4, 0x2498, v84
	ds_write2_b32 v4, v46, v47 offset1:1
	v_add_u32_e32 v4, 0x28a0, v84
	s_waitcnt vmcnt(5)
	ds_write2_b32 v4, v48, v49 offset1:1
	v_add_u32_e32 v4, 0x28a8, v84
	ds_write2_b32 v4, v50, v51 offset1:1
	v_add_u32_e32 v4, 0x2cb0, v84
	s_waitcnt vmcnt(4)
	ds_write2_b32 v4, v52, v53 offset1:1
	v_add_u32_e32 v4, 0x2cb8, v84
	ds_write2_b32 v4, v54, v55 offset1:1
	v_add_u32_e32 v4, 0x30c0, v84
	s_waitcnt vmcnt(3)
	ds_write2_b32 v4, v56, v57 offset1:1
	v_add_u32_e32 v4, 0x30c8, v84
	ds_write2_b32 v4, v58, v59 offset1:1
	v_add_u32_e32 v4, 0x34d0, v84
	s_waitcnt vmcnt(2)
	ds_write2_b32 v4, v60, v61 offset1:1
	v_add_u32_e32 v4, 0x34d8, v84
	ds_write2_b32 v4, v62, v63 offset1:1
	v_add_u32_e32 v4, 0x38e0, v84
	s_waitcnt vmcnt(1)
	ds_write2_b32 v4, v76, v77 offset1:1
	v_add_u32_e32 v4, 0x38e8, v84
	ds_write2_b32 v4, v78, v79 offset1:1
	v_add_u32_e32 v4, 0x3cf0, v84
	s_waitcnt vmcnt(0)
	ds_write2_b32 v4, v116, v117 offset1:1
	v_add_u32_e32 v4, 0x3cf8, v84
	ds_write2_b32 v4, v118, v119 offset1:1
	s_waitcnt lgkmcnt(0)
	ds_read2_b32 v[4:5], v7 offset0:199 offset1:207
	ds_read2_b32 v[12:13], v7 offset0:134 offset1:142
	ds_read2_b32 v[16:17], v7 offset0:4 offset1:12
	ds_read2_b32 v[14:15], v7 offset0:69 offset1:77
	ds_read2_b32 v[20:21], v86 offset0:130 offset1:138
	s_waitcnt lgkmcnt(4)
	v_bfe_u32 v8, v4, 16, 1
	v_add3_u32 v4, v4, v8, s95
	s_waitcnt lgkmcnt(3)
	v_bfe_u32 v8, v12, 16, 1
	v_add3_u32 v8, v12, v8, s95
	v_lshrrev_b32_e32 v8, 16, v8
	ds_read2_b32 v[18:19], v86 offset0:195 offset1:203
	v_and_or_b32 v11, v4, s96, v8
	s_waitcnt lgkmcnt(3)
	v_bfe_u32 v8, v16, 16, 1
	s_waitcnt lgkmcnt(2)
	v_bfe_u32 v4, v14, 16, 1
	v_add3_u32 v8, v16, v8, s95
	ds_read2_b32 v[24:25], v86 offset1:8
	v_add3_u32 v4, v14, v4, s95
	v_lshrrev_b32_e32 v8, 16, v8
	ds_read2_b32 v[22:23], v86 offset0:65 offset1:73
	v_and_or_b32 v10, v4, s96, v8
	s_waitcnt lgkmcnt(3)
	v_bfe_u32 v8, v20, 16, 1
	s_waitcnt lgkmcnt(2)
	v_bfe_u32 v4, v18, 16, 1
	v_add3_u32 v8, v20, v8, s95
	v_add3_u32 v4, v18, v4, s95
	v_lshrrev_b32_e32 v8, 16, v8
	v_and_or_b32 v9, v4, s96, v8
	s_waitcnt lgkmcnt(1)
	v_bfe_u32 v8, v24, 16, 1
	s_waitcnt lgkmcnt(0)
	v_bfe_u32 v4, v22, 16, 1
	v_add3_u32 v8, v24, v8, s95
	v_add3_u32 v4, v22, v4, s95
	v_lshrrev_b32_e32 v8, 16, v8
	v_and_or_b32 v8, v4, s96, v8
	v_or_b32_e32 v4, v6, v85
	v_lshlrev_b32_e32 v68, 12, v4
	v_bfe_u32 v4, v5, 16, 1
	v_add3_u32 v4, v5, v4, s95
	v_bfe_u32 v5, v13, 16, 1
	v_add3_u32 v5, v13, v5, s95
	v_lshl_add_u64 v[26:27], v[2:3], 0, v[68:69]
	v_lshrrev_b32_e32 v5, 16, v5
	global_store_dwordx4 v[26:27], v[8:11], off
	v_or_b32_e32 v12, v6, v87
	v_lshlrev_b32_e32 v68, 12, v12
	v_and_or_b32 v11, v4, s96, v5
	v_bfe_u32 v5, v17, 16, 1
	v_bfe_u32 v4, v15, 16, 1
	v_add3_u32 v5, v17, v5, s95
	v_add3_u32 v4, v15, v4, s95
	v_lshrrev_b32_e32 v5, 16, v5
	v_and_or_b32 v10, v4, s96, v5
	v_bfe_u32 v5, v21, 16, 1
	v_bfe_u32 v4, v19, 16, 1
	v_add3_u32 v5, v21, v5, s95
	v_add3_u32 v4, v19, v4, s95
	v_lshrrev_b32_e32 v5, 16, v5
	v_and_or_b32 v9, v4, s96, v5
	v_bfe_u32 v5, v25, 16, 1
	v_bfe_u32 v4, v23, 16, 1
	v_add3_u32 v5, v25, v5, s95
	v_add3_u32 v4, v23, v4, s95
	v_lshrrev_b32_e32 v5, 16, v5
	v_and_or_b32 v8, v4, s96, v5
	ds_read2_b32 v[4:5], v7 offset0:215 offset1:223
	ds_read2_b32 v[12:13], v7 offset0:150 offset1:158
	v_lshl_add_u64 v[14:15], v[2:3], 0, v[68:69]
	ds_read2_b32 v[16:17], v7 offset0:20 offset1:28
	global_store_dwordx4 v[14:15], v[8:11], off
	ds_read2_b32 v[14:15], v7 offset0:85 offset1:93
	ds_read2_b32 v[20:21], v86 offset0:146 offset1:154
	s_waitcnt lgkmcnt(4)
	v_bfe_u32 v8, v4, 16, 1
	v_add3_u32 v4, v4, v8, s95
	s_waitcnt lgkmcnt(3)
	v_bfe_u32 v8, v12, 16, 1
	v_add3_u32 v8, v12, v8, s95
	v_lshrrev_b32_e32 v8, 16, v8
	ds_read2_b32 v[18:19], v86 offset0:211 offset1:219
	v_and_or_b32 v11, v4, s96, v8
	s_waitcnt lgkmcnt(3)
	v_bfe_u32 v8, v16, 16, 1
	s_waitcnt lgkmcnt(2)
	v_bfe_u32 v4, v14, 16, 1
	v_add3_u32 v8, v16, v8, s95
	ds_read2_b32 v[24:25], v86 offset0:16 offset1:24
	v_add3_u32 v4, v14, v4, s95
	v_lshrrev_b32_e32 v8, 16, v8
	ds_read2_b32 v[22:23], v86 offset0:81 offset1:89
	v_and_or_b32 v10, v4, s96, v8
	s_waitcnt lgkmcnt(3)
	v_bfe_u32 v8, v20, 16, 1
	s_waitcnt lgkmcnt(2)
	v_bfe_u32 v4, v18, 16, 1
	v_add3_u32 v8, v20, v8, s95
	v_add3_u32 v4, v18, v4, s95
	v_lshrrev_b32_e32 v8, 16, v8
	v_and_or_b32 v9, v4, s96, v8
	s_waitcnt lgkmcnt(1)
	v_bfe_u32 v8, v24, 16, 1
	s_waitcnt lgkmcnt(0)
	v_bfe_u32 v4, v22, 16, 1
	v_add3_u32 v8, v24, v8, s95
	v_add3_u32 v4, v22, v4, s95
	v_lshrrev_b32_e32 v8, 16, v8
	v_and_or_b32 v8, v4, s96, v8
	v_or_b32_e32 v4, v6, v88
	v_lshlrev_b32_e32 v68, 12, v4
	v_bfe_u32 v4, v5, 16, 1
	v_add3_u32 v4, v5, v4, s95
	v_bfe_u32 v5, v13, 16, 1
	v_add3_u32 v5, v13, v5, s95
	v_lshl_add_u64 v[26:27], v[2:3], 0, v[68:69]
	v_lshrrev_b32_e32 v5, 16, v5
	global_store_dwordx4 v[26:27], v[8:11], off
	v_or_b32_e32 v12, v6, v89
	v_lshlrev_b32_e32 v68, 12, v12
	v_and_or_b32 v11, v4, s96, v5
	v_bfe_u32 v5, v17, 16, 1
	v_bfe_u32 v4, v15, 16, 1
	v_add3_u32 v5, v17, v5, s95
	v_add3_u32 v4, v15, v4, s95
	v_lshrrev_b32_e32 v5, 16, v5
	v_and_or_b32 v10, v4, s96, v5
	v_bfe_u32 v5, v21, 16, 1
	v_bfe_u32 v4, v19, 16, 1
	v_add3_u32 v5, v21, v5, s95
	v_add3_u32 v4, v19, v4, s95
	v_lshrrev_b32_e32 v5, 16, v5
	v_and_or_b32 v9, v4, s96, v5
	v_bfe_u32 v5, v25, 16, 1
	v_bfe_u32 v4, v23, 16, 1
	v_add3_u32 v5, v25, v5, s95
	v_add3_u32 v4, v23, v4, s95
	v_lshrrev_b32_e32 v5, 16, v5
	v_and_or_b32 v8, v4, s96, v5
	ds_read2_b32 v[4:5], v7 offset0:231 offset1:239
	ds_read2_b32 v[12:13], v7 offset0:166 offset1:174
	v_lshl_add_u64 v[14:15], v[2:3], 0, v[68:69]
	ds_read2_b32 v[16:17], v7 offset0:36 offset1:44
	global_store_dwordx4 v[14:15], v[8:11], off
	ds_read2_b32 v[14:15], v7 offset0:101 offset1:109
	ds_read2_b32 v[20:21], v86 offset0:162 offset1:170
	s_waitcnt lgkmcnt(4)
	v_bfe_u32 v8, v4, 16, 1
	v_add3_u32 v4, v4, v8, s95
	s_waitcnt lgkmcnt(3)
	v_bfe_u32 v8, v12, 16, 1
	v_add3_u32 v8, v12, v8, s95
	v_lshrrev_b32_e32 v8, 16, v8
	ds_read2_b32 v[18:19], v86 offset0:227 offset1:235
	v_and_or_b32 v11, v4, s96, v8
	s_waitcnt lgkmcnt(3)
	v_bfe_u32 v8, v16, 16, 1
	s_waitcnt lgkmcnt(2)
	v_bfe_u32 v4, v14, 16, 1
	v_add3_u32 v8, v16, v8, s95
	ds_read2_b32 v[24:25], v86 offset0:32 offset1:40
	v_add3_u32 v4, v14, v4, s95
	v_lshrrev_b32_e32 v8, 16, v8
	ds_read2_b32 v[22:23], v86 offset0:97 offset1:105
	v_and_or_b32 v10, v4, s96, v8
	s_waitcnt lgkmcnt(3)
	v_bfe_u32 v8, v20, 16, 1
	s_waitcnt lgkmcnt(2)
	v_bfe_u32 v4, v18, 16, 1
	v_add3_u32 v8, v20, v8, s95
	v_add3_u32 v4, v18, v4, s95
	v_lshrrev_b32_e32 v8, 16, v8
	v_and_or_b32 v9, v4, s96, v8
	s_waitcnt lgkmcnt(1)
	v_bfe_u32 v8, v24, 16, 1
	s_waitcnt lgkmcnt(0)
	v_bfe_u32 v4, v22, 16, 1
	v_add3_u32 v8, v24, v8, s95
	v_add3_u32 v4, v22, v4, s95
	v_lshrrev_b32_e32 v8, 16, v8
	v_and_or_b32 v8, v4, s96, v8
	v_or_b32_e32 v4, v6, v90
	v_lshlrev_b32_e32 v68, 12, v4
	v_bfe_u32 v4, v5, 16, 1
	v_add3_u32 v4, v5, v4, s95
	v_bfe_u32 v5, v13, 16, 1
	v_add3_u32 v5, v13, v5, s95
	v_lshl_add_u64 v[26:27], v[2:3], 0, v[68:69]
	v_lshrrev_b32_e32 v5, 16, v5
	global_store_dwordx4 v[26:27], v[8:11], off
	v_or_b32_e32 v12, v6, v91
	v_lshlrev_b32_e32 v68, 12, v12
	v_and_or_b32 v11, v4, s96, v5
	v_bfe_u32 v5, v17, 16, 1
	v_bfe_u32 v4, v15, 16, 1
	v_add3_u32 v5, v17, v5, s95
	v_add3_u32 v4, v15, v4, s95
	v_lshrrev_b32_e32 v5, 16, v5
	v_and_or_b32 v10, v4, s96, v5
	v_bfe_u32 v5, v21, 16, 1
	v_bfe_u32 v4, v19, 16, 1
	v_add3_u32 v5, v21, v5, s95
	v_add3_u32 v4, v19, v4, s95
	v_lshrrev_b32_e32 v5, 16, v5
	v_and_or_b32 v9, v4, s96, v5
	v_bfe_u32 v5, v25, 16, 1
	v_bfe_u32 v4, v23, 16, 1
	v_add3_u32 v5, v25, v5, s95
	v_add3_u32 v4, v23, v4, s95
	v_lshrrev_b32_e32 v5, 16, v5
	v_and_or_b32 v8, v4, s96, v5
	ds_read2_b32 v[4:5], v7 offset0:247 offset1:255
	ds_read2_b32 v[12:13], v7 offset0:182 offset1:190
	v_lshl_add_u64 v[14:15], v[2:3], 0, v[68:69]
	ds_read2_b32 v[16:17], v7 offset0:52 offset1:60
	global_store_dwordx4 v[14:15], v[8:11], off
	ds_read2_b32 v[14:15], v7 offset0:117 offset1:125
	ds_read2_b32 v[20:21], v86 offset0:178 offset1:186
	s_waitcnt lgkmcnt(4)
	v_bfe_u32 v8, v4, 16, 1
	v_add3_u32 v4, v4, v8, s95
	s_waitcnt lgkmcnt(3)
	v_bfe_u32 v8, v12, 16, 1
	v_add3_u32 v8, v12, v8, s95
	v_lshrrev_b32_e32 v7, 16, v8
	ds_read2_b32 v[18:19], v86 offset0:243 offset1:251
	v_and_or_b32 v11, v4, s96, v7
	s_waitcnt lgkmcnt(3)
	v_bfe_u32 v7, v16, 16, 1
	s_waitcnt lgkmcnt(2)
	v_bfe_u32 v4, v14, 16, 1
	v_add3_u32 v7, v16, v7, s95
	ds_read2_b32 v[24:25], v86 offset0:48 offset1:56
	v_add3_u32 v4, v14, v4, s95
	v_lshrrev_b32_e32 v7, 16, v7
	ds_read2_b32 v[22:23], v86 offset0:113 offset1:121
	v_and_or_b32 v10, v4, s96, v7
	s_waitcnt lgkmcnt(3)
	v_bfe_u32 v7, v20, 16, 1
	s_waitcnt lgkmcnt(2)
	v_bfe_u32 v4, v18, 16, 1
	v_add3_u32 v7, v20, v7, s95
	v_add3_u32 v4, v18, v4, s95
	v_lshrrev_b32_e32 v7, 16, v7
	v_and_or_b32 v9, v4, s96, v7
	s_waitcnt lgkmcnt(1)
	v_bfe_u32 v7, v24, 16, 1
	s_waitcnt lgkmcnt(0)
	v_bfe_u32 v4, v22, 16, 1
	v_add3_u32 v7, v24, v7, s95
	v_add3_u32 v4, v22, v4, s95
	v_lshrrev_b32_e32 v7, 16, v7
	v_and_or_b32 v8, v4, s96, v7
	v_or_b32_e32 v4, v6, v92
	v_lshlrev_b32_e32 v68, 12, v4
	v_bfe_u32 v4, v5, 16, 1
	v_add3_u32 v4, v5, v4, s95
	v_bfe_u32 v5, v13, 16, 1
	v_add3_u32 v5, v13, v5, s95
	v_lshl_add_u64 v[26:27], v[2:3], 0, v[68:69]
	v_lshrrev_b32_e32 v5, 16, v5
	global_store_dwordx4 v[26:27], v[8:11], off
	s_nop 1
	v_and_or_b32 v11, v4, s96, v5
	v_bfe_u32 v5, v17, 16, 1
	v_bfe_u32 v4, v15, 16, 1
	v_add3_u32 v5, v17, v5, s95
	v_add3_u32 v4, v15, v4, s95
	v_lshrrev_b32_e32 v5, 16, v5
	v_and_or_b32 v10, v4, s96, v5
	v_bfe_u32 v5, v21, 16, 1
	v_bfe_u32 v4, v19, 16, 1
	v_add3_u32 v5, v21, v5, s95
	v_add3_u32 v4, v19, v4, s95
	v_lshrrev_b32_e32 v5, 16, v5
	v_and_or_b32 v9, v4, s96, v5
	v_bfe_u32 v5, v25, 16, 1
	v_bfe_u32 v4, v23, 16, 1
	v_add3_u32 v5, v25, v5, s95
	v_add3_u32 v4, v23, v4, s95
	v_lshrrev_b32_e32 v5, 16, v5
	v_and_or_b32 v8, v4, s96, v5
	v_or_b32_e32 v4, v6, v93
	v_lshlrev_b32_e32 v68, 12, v4
	v_lshl_add_u64 v[2:3], v[2:3], 0, v[68:69]
	global_store_dwordx4 v[2:3], v[8:11], off
	s_waitcnt lgkmcnt(0)
	s_or_b64 exec, exec, s[4:5]
	s_and_b64 exec, exec, s[2:3]
	s_cbranch_execz .LBB0_95

.LBB0_41:
	v_lshlrev_b32_e32 v4, 6, v81
	v_and_b32_e32 v115, 0x1fc0, v4
	v_lshrrev_b32_e32 v4, 1, v81
	v_and_b32_e32 v116, 0x7c0, v4
	v_or_b32_e32 v80, v116, v83
	v_lshl_add_u64 v[2:3], v[76:77], 2, s[48:49]
	v_lshlrev_b32_e32 v68, 15, v80
	v_lshl_add_u64 v[2:3], v[2:3], 0, v[68:69]
	v_lshlrev_b32_e32 v68, 2, v115
	v_lshl_add_u64 v[2:3], v[2:3], 0, v[68:69]
	v_mov_b32_e32 v73, v69
	v_lshl_add_u64 v[2:3], v[2:3], 0, v[72:73]
	v_add_co_u32_e32 v4, vcc, s83, v2
	s_mov_b32 s4, 0x80000
	s_nop 0
	v_addc_co_u32_e32 v5, vcc, 0, v3, vcc
	global_load_dwordx4 v[62:65], v[2:3], off nt
	global_load_dwordx4 v[58:61], v[4:5], off nt
	v_add_co_u32_e32 v4, vcc, s87, v2
	v_lshlrev_b64 v[78:79], 13, v[74:75]
	s_nop 0
	v_addc_co_u32_e32 v5, vcc, 0, v3, vcc
	v_add_co_u32_e32 v6, vcc, s91, v2
	v_cndmask_b32_e64 v68, 0, 1, s[70:71]
	s_nop 0
	v_addc_co_u32_e32 v7, vcc, 0, v3, vcc
	global_load_dwordx4 v[54:57], v[4:5], off nt
	global_load_dwordx4 v[50:53], v[6:7], off nt
	v_add_co_u32_e32 v4, vcc, s4, v2
	s_mov_b32 s4, 0xa0000
	s_nop 0
	v_addc_co_u32_e32 v5, vcc, 0, v3, vcc
	v_add_co_u32_e32 v6, vcc, s4, v2
	s_mov_b32 s4, 0xc0000
	s_nop 0
	v_addc_co_u32_e32 v7, vcc, 0, v3, vcc
	global_load_dwordx4 v[46:49], v[4:5], off nt
	global_load_dwordx4 v[42:45], v[6:7], off nt
	v_add_co_u32_e32 v4, vcc, s4, v2
	s_mov_b32 s4, 0xe0000
	s_nop 0
	v_addc_co_u32_e32 v5, vcc, 0, v3, vcc
	v_add_co_u32_e32 v6, vcc, s4, v2
	s_mov_b32 s4, 0x100000
	s_nop 0
	v_addc_co_u32_e32 v7, vcc, 0, v3, vcc
	global_load_dwordx4 v[38:41], v[4:5], off nt
	global_load_dwordx4 v[34:37], v[6:7], off nt
	v_add_co_u32_e32 v4, vcc, s4, v2
	s_mov_b32 s4, 0x120000
	s_nop 0
	v_addc_co_u32_e32 v5, vcc, 0, v3, vcc
	v_add_co_u32_e32 v6, vcc, s4, v2
	s_mov_b32 s4, 0x140000
	s_nop 0
	v_addc_co_u32_e32 v7, vcc, 0, v3, vcc
	global_load_dwordx4 v[30:33], v[4:5], off nt
	global_load_dwordx4 v[26:29], v[6:7], off nt
	v_add_co_u32_e32 v4, vcc, s4, v2
	s_mov_b32 s4, 0x160000
	s_nop 0
	v_addc_co_u32_e32 v5, vcc, 0, v3, vcc
	v_add_co_u32_e32 v6, vcc, s4, v2
	s_mov_b32 s4, 0x180000
	s_nop 0
	v_addc_co_u32_e32 v7, vcc, 0, v3, vcc
	global_load_dwordx4 v[22:25], v[4:5], off nt
	global_load_dwordx4 v[18:21], v[6:7], off nt
	v_add_co_u32_e32 v4, vcc, s4, v2
	s_mov_b64 s[30:31], s[34:35]
	s_nop 0
	v_addc_co_u32_e32 v5, vcc, 0, v3, vcc
	v_add_co_u32_e32 v6, vcc, 0x1a0000, v2
	s_mov_b64 s[34:35], s[52:53]
	s_nop 0
	v_addc_co_u32_e32 v7, vcc, 0, v3, vcc
	global_load_dwordx4 v[14:17], v[4:5], off nt
	global_load_dwordx4 v[10:13], v[6:7], off nt
	v_add_co_u32_e32 v4, vcc, 0x1c0000, v2
	s_mov_b64 s[52:53], s[0:1]
	s_nop 0
	v_addc_co_u32_e32 v5, vcc, 0, v3, vcc
	v_add_co_u32_e32 v2, vcc, 0x1e0000, v2
	v_lshl_add_u64 v[78:79], s[46:47], 0, v[78:79]
	s_nop 0
	v_addc_co_u32_e32 v3, vcc, 0, v3, vcc
	global_load_dwordx4 v[6:9], v[4:5], off nt
	s_nop 0
	global_load_dwordx4 v[2:5], v[2:3], off nt
	v_cmp_ne_u32_e64 s[4:5], 1, v68
	s_mov_b64 s[0:1], s[70:71]
	s_andn2_b64 vcc, exec, s[70:71]
	v_lshlrev_b32_e32 v68, 2, v80
	s_cbranch_vccnz .LBB0_79
	v_lshl_add_u64 v[118:119], v[78:79], 0, v[68:69]
	global_load_dword v120, v[118:119], off
	global_load_dword v80, v[118:119], off offset:16
	s_waitcnt vmcnt(1)
	v_pk_mul_f32 v[118:119], v[62:63], v[120:121] op_sel_hi:[1,0]
	v_pk_mul_f32 v[120:121], v[64:65], v[120:121] op_sel_hi:[1,0]
	ds_write2_b32 v84, v118, v119 offset1:1
	ds_write2_b32 v84, v120, v121 offset0:2 offset1:3
	s_cbranch_execnz .LBB0_44

.LBB0_70:
	v_lshlrev_b32_e32 v5, 1, v81
	v_and_b32_e32 v5, 0x1fc0, v5
	v_lshlrev_b32_e32 v4, 6, v81
	v_or_b32_e32 v6, v5, v83
	v_lshl_add_u64 v[2:3], v[76:77], 2, s[50:51]
	v_and_b32_e32 v4, 0x7c0, v4
	v_lshlrev_b32_e32 v68, 13, v6
	v_lshl_add_u64 v[2:3], v[2:3], 0, v[68:69]
	v_lshlrev_b32_e32 v68, 2, v4
	v_lshl_add_u64 v[2:3], v[2:3], 0, v[68:69]
	v_mov_b32_e32 v73, v69
	v_lshl_add_u64 v[2:3], v[2:3], 0, v[72:73]
	v_add_co_u32_e32 v10, vcc, s78, v2
	v_lshlrev_b32_e32 v68, 1, v5
	s_nop 0
	v_addc_co_u32_e32 v11, vcc, 0, v3, vcc
	v_add_co_u32_e32 v14, vcc, s79, v2
	global_load_dwordx4 v[6:9], v[2:3], off nt
	s_nop 0
	global_load_dwordx4 v[10:13], v[10:11], off nt
	v_addc_co_u32_e32 v15, vcc, 0, v3, vcc
	v_add_co_u32_e32 v18, vcc, s82, v2
	v_add_u32_e32 v5, 0x400, v86
	s_nop 0
	v_addc_co_u32_e32 v19, vcc, 0, v3, vcc
	v_add_co_u32_e32 v22, vcc, s83, v2
	global_load_dwordx4 v[14:17], v[14:15], off nt
	s_nop 0
	global_load_dwordx4 v[18:21], v[18:19], off nt
	v_addc_co_u32_e32 v23, vcc, 0, v3, vcc
	v_add_co_u32_e32 v26, vcc, s84, v2
	s_nop 1
	v_addc_co_u32_e32 v27, vcc, 0, v3, vcc
	v_add_co_u32_e32 v30, vcc, s85, v2
	global_load_dwordx4 v[22:25], v[22:23], off nt
	s_nop 0
	global_load_dwordx4 v[26:29], v[26:27], off nt
	v_addc_co_u32_e32 v31, vcc, 0, v3, vcc
	v_add_co_u32_e32 v34, vcc, s86, v2
	s_nop 1
	v_addc_co_u32_e32 v35, vcc, 0, v3, vcc
	global_load_dwordx4 v[30:33], v[30:31], off nt
	s_nop 0
	global_load_dwordx4 v[34:37], v[34:35], off nt
	v_add_co_u32_e32 v38, vcc, s87, v2
	s_nop 1
	v_addc_co_u32_e32 v39, vcc, 0, v3, vcc
	v_add_co_u32_e32 v42, vcc, s88, v2
	s_nop 1
	v_addc_co_u32_e32 v43, vcc, 0, v3, vcc
	global_load_dwordx4 v[38:41], v[38:39], off nt
	s_nop 0
	global_load_dwordx4 v[42:45], v[42:43], off nt
	v_add_co_u32_e32 v46, vcc, s89, v2
	s_nop 1
	v_addc_co_u32_e32 v47, vcc, 0, v3, vcc
	v_add_co_u32_e32 v50, vcc, s90, v2
	s_nop 1
	v_addc_co_u32_e32 v51, vcc, 0, v3, vcc
	global_load_dwordx4 v[46:49], v[46:47], off nt
	s_nop 0
	global_load_dwordx4 v[50:53], v[50:51], off nt
	v_add_co_u32_e32 v54, vcc, s91, v2
	s_nop 1
	v_addc_co_u32_e32 v55, vcc, 0, v3, vcc
	v_add_co_u32_e32 v58, vcc, s92, v2
	s_nop 1
	v_addc_co_u32_e32 v59, vcc, 0, v3, vcc
	global_load_dwordx4 v[54:57], v[54:55], off nt
	s_nop 0
	global_load_dwordx4 v[58:61], v[58:59], off nt
	v_add_co_u32_e32 v62, vcc, s93, v2
	s_nop 1
	v_addc_co_u32_e32 v63, vcc, 0, v3, vcc
	global_load_dwordx4 v[62:65], v[62:63], off nt
	v_add_co_u32_e32 v2, vcc, s94, v2
	s_nop 1
	v_addc_co_u32_e32 v3, vcc, 0, v3, vcc
	global_load_dwordx4 v[116:119], v[2:3], off nt
	v_lshl_add_u64 v[2:3], v[76:77], 1, s[34:35]
	v_lshl_add_u64 v[2:3], v[2:3], 0, v[68:69]
	v_lshlrev_b32_e32 v68, 1, v70
	v_lshl_add_u64 v[2:3], v[2:3], 0, v[68:69]
	s_waitcnt vmcnt(15)
	ds_write2_b32 v84, v6, v7 offset1:1
	ds_write2_b32 v84, v8, v9 offset0:2 offset1:3
	s_waitcnt vmcnt(14)
	ds_write2_b32 v103, v10, v11 offset1:1
	ds_write2_b32 v104, v12, v13 offset1:1
	s_waitcnt vmcnt(13)
	ds_write2_b32 v105, v14, v15 offset1:1
	ds_write2_b32 v106, v16, v17 offset1:1
	s_waitcnt vmcnt(12)
	ds_write2_b32 v107, v18, v19 offset1:1
	ds_write2_b32 v108, v20, v21 offset1:1
	s_waitcnt vmcnt(11)
	ds_write2_b32 v109, v22, v23 offset1:1
	ds_write2_b32 v110, v24, v25 offset1:1
	s_waitcnt vmcnt(10)
	ds_write2_b32 v111, v26, v27 offset1:1
	v_add_u32_e32 v6, 0x1458, v84
	ds_write2_b32 v6, v28, v29 offset1:1
	v_add_u32_e32 v6, 0x1860, v84
	s_waitcnt vmcnt(9)
	ds_write2_b32 v6, v30, v31 offset1:1
	v_add_u32_e32 v6, 0x1868, v84
	ds_write2_b32 v6, v32, v33 offset1:1
	v_add_u32_e32 v6, 0x1c70, v84
	s_waitcnt vmcnt(8)
	ds_write2_b32 v6, v34, v35 offset1:1
	v_add_u32_e32 v6, 0x1c78, v84
	ds_write2_b32 v6, v36, v37 offset1:1
	v_add_u32_e32 v6, 0x2080, v84
	s_waitcnt vmcnt(7)
	ds_write2_b32 v6, v38, v39 offset1:1
	v_add_u32_e32 v6, 0x2088, v84
	ds_write2_b32 v6, v40, v41 offset1:1
	v_add_u32_e32 v6, 0x2490, v84
	s_waitcnt vmcnt(6)
	ds_write2_b32 v6, v42, v43 offset1:1
	v_add_u32_e32 v6, 0x2498, v84
	ds_write2_b32 v6, v44, v45 offset1:1
	v_add_u32_e32 v6, 0x28a0, v84
	s_waitcnt vmcnt(5)
	ds_write2_b32 v6, v46, v47 offset1:1
	v_add_u32_e32 v6, 0x28a8, v84
	ds_write2_b32 v6, v48, v49 offset1:1
	v_add_u32_e32 v6, 0x2cb0, v84
	s_waitcnt vmcnt(4)
	ds_write2_b32 v6, v50, v51 offset1:1
	v_add_u32_e32 v6, 0x2cb8, v84
	ds_write2_b32 v6, v52, v53 offset1:1
	v_add_u32_e32 v6, 0x30c0, v84
	s_waitcnt vmcnt(3)
	ds_write2_b32 v6, v54, v55 offset1:1
	v_add_u32_e32 v6, 0x30c8, v84
	ds_write2_b32 v6, v56, v57 offset1:1
	v_add_u32_e32 v6, 0x34d0, v84
	s_waitcnt vmcnt(2)
	ds_write2_b32 v6, v58, v59 offset1:1
	v_add_u32_e32 v6, 0x34d8, v84
	ds_write2_b32 v6, v60, v61 offset1:1
	v_add_u32_e32 v6, 0x38e0, v84
	s_waitcnt vmcnt(1)
	ds_write2_b32 v6, v62, v63 offset1:1
	v_add_u32_e32 v6, 0x38e8, v84
	ds_write2_b32 v6, v64, v65 offset1:1
	v_add_u32_e32 v6, 0x3cf0, v84
	s_waitcnt vmcnt(0)
	ds_write2_b32 v6, v116, v117 offset1:1
	v_add_u32_e32 v6, 0x3cf8, v84
	ds_write2_b32 v6, v118, v119 offset1:1
	s_waitcnt lgkmcnt(0)
	ds_read2_b32 v[12:13], v5 offset0:134 offset1:142
	ds_read2_b32 v[10:11], v5 offset0:199 offset1:207
	ds_read2_b32 v[16:17], v5 offset0:4 offset1:12
	ds_read2_b32 v[14:15], v5 offset0:69 offset1:77
	ds_read2_b32 v[20:21], v86 offset0:130 offset1:138
	s_waitcnt lgkmcnt(4)
	v_bfe_u32 v7, v12, 16, 1
	s_waitcnt lgkmcnt(3)
	v_bfe_u32 v6, v10, 16, 1
	v_add3_u32 v7, v12, v7, s95
	v_add3_u32 v6, v10, v6, s95
	v_lshrrev_b32_e32 v7, 16, v7
	ds_read2_b32 v[18:19], v86 offset0:195 offset1:203
	v_and_or_b32 v9, v6, s96, v7
	s_waitcnt lgkmcnt(3)
	v_bfe_u32 v7, v16, 16, 1
	ds_read2_b32 v[24:25], v86 offset1:8
	s_waitcnt lgkmcnt(3)
	v_bfe_u32 v6, v14, 16, 1
	v_add3_u32 v7, v16, v7, s95
	ds_read2_b32 v[22:23], v86 offset0:65 offset1:73
	v_add3_u32 v6, v14, v6, s95
	v_lshrrev_b32_e32 v7, 16, v7
	v_and_or_b32 v8, v6, s96, v7
	s_waitcnt lgkmcnt(3)
	v_bfe_u32 v7, v20, 16, 1
	s_waitcnt lgkmcnt(2)
	v_bfe_u32 v6, v18, 16, 1
	v_add3_u32 v7, v20, v7, s95
	v_add3_u32 v6, v18, v6, s95
	v_lshrrev_b32_e32 v7, 16, v7
	s_waitcnt lgkmcnt(1)
	v_bfe_u32 v10, v24, 16, 1
	v_and_or_b32 v7, v6, s96, v7
	s_waitcnt lgkmcnt(0)
	v_bfe_u32 v6, v22, 16, 1
	v_add3_u32 v10, v24, v10, s95
	v_add3_u32 v6, v22, v6, s95
	v_lshrrev_b32_e32 v10, 16, v10
	v_and_or_b32 v6, v6, s96, v10
	v_or_b32_e32 v10, v4, v85
	v_lshlrev_b32_e32 v68, 14, v10
	v_lshl_add_u64 v[26:27], v[2:3], 0, v[68:69]
	global_store_dwordx4 v[26:27], v[6:9], off
	v_bfe_u32 v10, v25, 16, 1
	v_add3_u32 v10, v25, v10, s95
	v_bfe_u32 v7, v13, 16, 1
	v_bfe_u32 v6, v11, 16, 1
	v_add3_u32 v7, v13, v7, s95
	v_add3_u32 v6, v11, v6, s95
	v_lshrrev_b32_e32 v7, 16, v7
	v_and_or_b32 v9, v6, s96, v7
	v_bfe_u32 v7, v17, 16, 1
	v_bfe_u32 v6, v15, 16, 1
	v_add3_u32 v7, v17, v7, s95
	v_add3_u32 v6, v15, v6, s95
	v_lshrrev_b32_e32 v7, 16, v7
	v_and_or_b32 v8, v6, s96, v7
	v_bfe_u32 v7, v21, 16, 1
	v_bfe_u32 v6, v19, 16, 1
	v_add3_u32 v7, v21, v7, s95
	v_add3_u32 v6, v19, v6, s95
	v_lshrrev_b32_e32 v7, 16, v7
	v_and_or_b32 v7, v6, s96, v7
	v_bfe_u32 v6, v23, 16, 1
	v_or_b32_e32 v12, v4, v87
	v_add3_u32 v6, v23, v6, s95
	v_lshrrev_b32_e32 v10, 16, v10
	v_lshlrev_b32_e32 v68, 14, v12
	ds_read2_b32 v[12:13], v5 offset0:150 offset1:158
	v_and_or_b32 v6, v6, s96, v10
	ds_read2_b32 v[10:11], v5 offset0:215 offset1:223
	v_lshl_add_u64 v[14:15], v[2:3], 0, v[68:69]
	ds_read2_b32 v[16:17], v5 offset0:20 offset1:28
	global_store_dwordx4 v[14:15], v[6:9], off
	ds_read2_b32 v[14:15], v5 offset0:85 offset1:93
	ds_read2_b32 v[20:21], v86 offset0:146 offset1:154
	s_waitcnt lgkmcnt(4)
	v_bfe_u32 v7, v12, 16, 1
	s_waitcnt lgkmcnt(3)
	v_bfe_u32 v6, v10, 16, 1
	v_add3_u32 v7, v12, v7, s95
	v_add3_u32 v6, v10, v6, s95
	v_lshrrev_b32_e32 v7, 16, v7
	ds_read2_b32 v[18:19], v86 offset0:211 offset1:219
	v_and_or_b32 v9, v6, s96, v7
	s_waitcnt lgkmcnt(3)
	v_bfe_u32 v7, v16, 16, 1
	ds_read2_b32 v[24:25], v86 offset0:16 offset1:24
	s_waitcnt lgkmcnt(3)
	v_bfe_u32 v6, v14, 16, 1
	v_add3_u32 v7, v16, v7, s95
	ds_read2_b32 v[22:23], v86 offset0:81 offset1:89
	v_add3_u32 v6, v14, v6, s95
	v_lshrrev_b32_e32 v7, 16, v7
	v_and_or_b32 v8, v6, s96, v7
	s_waitcnt lgkmcnt(3)
	v_bfe_u32 v7, v20, 16, 1
	s_waitcnt lgkmcnt(2)
	v_bfe_u32 v6, v18, 16, 1
	v_add3_u32 v7, v20, v7, s95
	v_add3_u32 v6, v18, v6, s95
	v_lshrrev_b32_e32 v7, 16, v7
	s_waitcnt lgkmcnt(1)
	v_bfe_u32 v10, v24, 16, 1
	v_and_or_b32 v7, v6, s96, v7
	s_waitcnt lgkmcnt(0)
	v_bfe_u32 v6, v22, 16, 1
	v_add3_u32 v10, v24, v10, s95
	v_add3_u32 v6, v22, v6, s95
	v_lshrrev_b32_e32 v10, 16, v10
	v_and_or_b32 v6, v6, s96, v10
	v_or_b32_e32 v10, v4, v88
	v_lshlrev_b32_e32 v68, 14, v10
	v_lshl_add_u64 v[26:27], v[2:3], 0, v[68:69]
	global_store_dwordx4 v[26:27], v[6:9], off
	v_bfe_u32 v10, v25, 16, 1
	v_add3_u32 v10, v25, v10, s95
	v_bfe_u32 v7, v13, 16, 1
	v_bfe_u32 v6, v11, 16, 1
	v_add3_u32 v7, v13, v7, s95
	v_add3_u32 v6, v11, v6, s95
	v_lshrrev_b32_e32 v7, 16, v7
	v_and_or_b32 v9, v6, s96, v7
	v_bfe_u32 v7, v17, 16, 1
	v_bfe_u32 v6, v15, 16, 1
	v_add3_u32 v7, v17, v7, s95
	v_add3_u32 v6, v15, v6, s95
	v_lshrrev_b32_e32 v7, 16, v7
	v_and_or_b32 v8, v6, s96, v7
	v_bfe_u32 v7, v21, 16, 1
	v_bfe_u32 v6, v19, 16, 1
	v_add3_u32 v7, v21, v7, s95
	v_add3_u32 v6, v19, v6, s95
	v_lshrrev_b32_e32 v7, 16, v7
	v_and_or_b32 v7, v6, s96, v7
	v_bfe_u32 v6, v23, 16, 1
	v_or_b32_e32 v12, v4, v89
	v_add3_u32 v6, v23, v6, s95
	v_lshrrev_b32_e32 v10, 16, v10
	v_lshlrev_b32_e32 v68, 14, v12
	ds_read2_b32 v[12:13], v5 offset0:166 offset1:174
	v_and_or_b32 v6, v6, s96, v10
	ds_read2_b32 v[10:11], v5 offset0:231 offset1:239
	v_lshl_add_u64 v[14:15], v[2:3], 0, v[68:69]
	ds_read2_b32 v[16:17], v5 offset0:36 offset1:44
	global_store_dwordx4 v[14:15], v[6:9], off
	ds_read2_b32 v[14:15], v5 offset0:101 offset1:109
	ds_read2_b32 v[20:21], v86 offset0:162 offset1:170
	s_waitcnt lgkmcnt(4)
	v_bfe_u32 v7, v12, 16, 1
	s_waitcnt lgkmcnt(3)
	v_bfe_u32 v6, v10, 16, 1
	v_add3_u32 v7, v12, v7, s95
	v_add3_u32 v6, v10, v6, s95
	v_lshrrev_b32_e32 v7, 16, v7
	ds_read2_b32 v[18:19], v86 offset0:227 offset1:235
	v_and_or_b32 v9, v6, s96, v7
	s_waitcnt lgkmcnt(3)
	v_bfe_u32 v7, v16, 16, 1
	ds_read2_b32 v[24:25], v86 offset0:32 offset1:40
	s_waitcnt lgkmcnt(3)
	v_bfe_u32 v6, v14, 16, 1
	v_add3_u32 v7, v16, v7, s95
	ds_read2_b32 v[22:23], v86 offset0:97 offset1:105
	v_add3_u32 v6, v14, v6, s95
	v_lshrrev_b32_e32 v7, 16, v7
	v_and_or_b32 v8, v6, s96, v7
	s_waitcnt lgkmcnt(3)
	v_bfe_u32 v7, v20, 16, 1
	s_waitcnt lgkmcnt(2)
	v_bfe_u32 v6, v18, 16, 1
	v_add3_u32 v7, v20, v7, s95
	v_add3_u32 v6, v18, v6, s95
	v_lshrrev_b32_e32 v7, 16, v7
	s_waitcnt lgkmcnt(1)
	v_bfe_u32 v10, v24, 16, 1
	v_and_or_b32 v7, v6, s96, v7
	s_waitcnt lgkmcnt(0)
	v_bfe_u32 v6, v22, 16, 1
	v_add3_u32 v10, v24, v10, s95
	v_add3_u32 v6, v22, v6, s95
	v_lshrrev_b32_e32 v10, 16, v10
	v_and_or_b32 v6, v6, s96, v10
	v_or_b32_e32 v10, v4, v90
	v_lshlrev_b32_e32 v68, 14, v10
	v_lshl_add_u64 v[26:27], v[2:3], 0, v[68:69]
	global_store_dwordx4 v[26:27], v[6:9], off
	v_bfe_u32 v10, v25, 16, 1
	v_add3_u32 v10, v25, v10, s95
	v_bfe_u32 v7, v13, 16, 1
	v_bfe_u32 v6, v11, 16, 1
	v_add3_u32 v7, v13, v7, s95
	v_add3_u32 v6, v11, v6, s95
	v_lshrrev_b32_e32 v7, 16, v7
	v_and_or_b32 v9, v6, s96, v7
	v_bfe_u32 v7, v17, 16, 1
	v_bfe_u32 v6, v15, 16, 1
	v_add3_u32 v7, v17, v7, s95
	v_add3_u32 v6, v15, v6, s95
	v_lshrrev_b32_e32 v7, 16, v7
	v_and_or_b32 v8, v6, s96, v7
	v_bfe_u32 v7, v21, 16, 1
	v_bfe_u32 v6, v19, 16, 1
	v_add3_u32 v7, v21, v7, s95
	v_add3_u32 v6, v19, v6, s95
	v_lshrrev_b32_e32 v7, 16, v7
	v_and_or_b32 v7, v6, s96, v7
	v_bfe_u32 v6, v23, 16, 1
	v_or_b32_e32 v12, v4, v91
	v_add3_u32 v6, v23, v6, s95
	v_lshrrev_b32_e32 v10, 16, v10
	v_lshlrev_b32_e32 v68, 14, v12
	ds_read2_b32 v[12:13], v5 offset0:182 offset1:190
	v_and_or_b32 v6, v6, s96, v10
	ds_read2_b32 v[10:11], v5 offset0:247 offset1:255
	v_lshl_add_u64 v[14:15], v[2:3], 0, v[68:69]
	ds_read2_b32 v[16:17], v5 offset0:52 offset1:60
	global_store_dwordx4 v[14:15], v[6:9], off
	ds_read2_b32 v[14:15], v5 offset0:117 offset1:125
	ds_read2_b32 v[20:21], v86 offset0:178 offset1:186
	s_waitcnt lgkmcnt(4)
	v_bfe_u32 v7, v12, 16, 1
	s_waitcnt lgkmcnt(3)
	v_bfe_u32 v6, v10, 16, 1
	v_add3_u32 v7, v12, v7, s95
	v_add3_u32 v6, v10, v6, s95
	v_lshrrev_b32_e32 v5, 16, v7
	ds_read2_b32 v[18:19], v86 offset0:243 offset1:251
	v_and_or_b32 v9, v6, s96, v5
	s_waitcnt lgkmcnt(3)
	v_bfe_u32 v6, v16, 16, 1
	s_waitcnt lgkmcnt(2)
	v_bfe_u32 v5, v14, 16, 1
	v_add3_u32 v6, v16, v6, s95
	ds_read2_b32 v[24:25], v86 offset0:48 offset1:56
	v_add3_u32 v5, v14, v5, s95
	v_lshrrev_b32_e32 v6, 16, v6
	ds_read2_b32 v[22:23], v86 offset0:113 offset1:121
	v_and_or_b32 v8, v5, s96, v6
	s_waitcnt lgkmcnt(3)
	v_bfe_u32 v6, v20, 16, 1
	s_waitcnt lgkmcnt(2)
	v_bfe_u32 v5, v18, 16, 1
	v_add3_u32 v6, v20, v6, s95
	v_add3_u32 v5, v18, v5, s95
	v_lshrrev_b32_e32 v6, 16, v6
	v_and_or_b32 v7, v5, s96, v6
	s_waitcnt lgkmcnt(1)
	v_bfe_u32 v6, v24, 16, 1
	s_waitcnt lgkmcnt(0)
	v_bfe_u32 v5, v22, 16, 1
	v_add3_u32 v6, v24, v6, s95
	v_add3_u32 v5, v22, v5, s95
	v_lshrrev_b32_e32 v6, 16, v6
	v_and_or_b32 v6, v5, s96, v6
	v_or_b32_e32 v5, v4, v92
	v_lshlrev_b32_e32 v68, 14, v5
	v_lshl_add_u64 v[26:27], v[2:3], 0, v[68:69]
	global_store_dwordx4 v[26:27], v[6:9], off
	v_bfe_u32 v5, v11, 16, 1
	v_add3_u32 v5, v11, v5, s95
	v_bfe_u32 v6, v13, 16, 1
	v_add3_u32 v6, v13, v6, s95
	v_lshrrev_b32_e32 v6, 16, v6
	v_and_or_b32 v9, v5, s96, v6
	v_bfe_u32 v6, v17, 16, 1
	v_bfe_u32 v5, v15, 16, 1
	v_add3_u32 v6, v17, v6, s95
	v_add3_u32 v5, v15, v5, s95
	v_lshrrev_b32_e32 v6, 16, v6
	v_and_or_b32 v8, v5, s96, v6
	v_bfe_u32 v6, v21, 16, 1
	v_bfe_u32 v5, v19, 16, 1
	v_add3_u32 v6, v21, v6, s95
	v_add3_u32 v5, v19, v5, s95
	v_lshrrev_b32_e32 v6, 16, v6
	v_and_or_b32 v7, v5, s96, v6
	v_bfe_u32 v6, v25, 16, 1
	v_bfe_u32 v5, v23, 16, 1
	v_add3_u32 v6, v25, v6, s95
	v_or_b32_e32 v4, v4, v93
	v_add3_u32 v5, v23, v5, s95
	v_lshrrev_b32_e32 v6, 16, v6
	v_lshlrev_b32_e32 v68, 14, v4
	v_and_or_b32 v6, v5, s96, v6
	v_lshl_add_u64 v[2:3], v[2:3], 0, v[68:69]
	global_store_dwordx4 v[2:3], v[6:9], off
	s_waitcnt lgkmcnt(0)
	s_or_b64 exec, exec, s[4:5]
	s_and_b64 exec, exec, s[2:3]
	s_cbranch_execz .LBB0_95
.LBB0_71:
	v_cmp_lt_u32_e64 s[2:3], s58, v81
	s_and_saveexec_b64 s[4:5], s[2:3]
	s_xor_b64 s[4:5], exec, s[4:5]
	v_add_u32_e32 v81, 0xffffff00, v81
	s_or_saveexec_b64 s[4:5], s[4:5]
	v_lshlrev_b32_e32 v4, 1, v74
	v_lshlrev_b64 v[2:3], 20, v[74:75]
	v_ashrrev_i32_e32 v5, 31, v4
	s_xor_b64 exec, exec, s[4:5]
	s_cbranch_execz .LBB0_75
	v_lshrrev_b32_e32 v80, 2, v81
	v_lshl_add_u64 v[6:7], v[2:3], 2, s[20:21]
	v_lshl_or_b32 v68, v80, 16, v94
	v_lshlrev_b32_e32 v8, 8, v81
	v_lshl_add_u64 v[6:7], v[6:7], 0, v[68:69]
	v_and_b32_e32 v68, 0x300, v8
	v_lshl_add_u64 v[6:7], v[6:7], 0, v[68:69]
	v_mov_b32_e32 v73, v69
	v_lshl_add_u64 v[76:77], v[6:7], 0, v[72:73]
	s_movk_i32 s30, 0x2000
	v_add_co_u32_e32 v14, vcc, s30, v76
	s_movk_i32 s30, 0x4000
	s_nop 0
	v_addc_co_u32_e32 v15, vcc, 0, v77, vcc
	v_add_co_u32_e32 v30, vcc, s30, v76
	s_movk_i32 s30, 0x6000
	s_nop 0
	v_addc_co_u32_e32 v31, vcc, 0, v77, vcc
	v_add_co_u32_e32 v22, vcc, s78, v76
	global_load_dwordx4 v[6:9], v[76:77], off nt
	s_nop 0
	v_addc_co_u32_e32 v23, vcc, 0, v77, vcc
	v_add_co_u32_e32 v38, vcc, s30, v76
	s_mov_b32 s30, 0xa000
	s_nop 0
	v_addc_co_u32_e32 v39, vcc, 0, v77, vcc
	v_add_co_u32_e32 v46, vcc, s30, v76
	global_load_dwordx4 v[10:13], v[14:15], off offset:-4096 nt
	s_nop 0
	global_load_dwordx4 v[14:17], v[14:15], off nt
	s_nop 0
	global_load_dwordx4 v[18:21], v[22:23], off offset:-4096 nt
	s_nop 0
	global_load_dwordx4 v[22:25], v[22:23], off nt
	s_nop 0
	global_load_dwordx4 v[26:29], v[30:31], off offset:-4096 nt
	s_nop 0
	global_load_dwordx4 v[30:33], v[30:31], off nt
	s_nop 0
	global_load_dwordx4 v[34:37], v[38:39], off offset:-4096 nt
	s_nop 0
	global_load_dwordx4 v[38:41], v[38:39], off nt
	v_addc_co_u32_e32 v47, vcc, 0, v77, vcc
	global_load_dwordx4 v[42:45], v[46:47], off offset:-4096 nt
	s_nop 0
	global_load_dwordx4 v[46:49], v[46:47], off nt
	s_mov_b32 s30, 0xc000
	v_add_co_u32_e32 v54, vcc, s30, v76
	s_mov_b32 s30, 0xe000
	s_nop 0
	v_addc_co_u32_e32 v55, vcc, 0, v77, vcc
	global_load_dwordx4 v[50:53], v[54:55], off offset:-4096 nt
	s_nop 0
	global_load_dwordx4 v[54:57], v[54:55], off nt
	v_add_co_u32_e32 v62, vcc, s30, v76
	s_mov_b32 s30, 0xf000
	s_nop 0
	v_addc_co_u32_e32 v63, vcc, 0, v77, vcc
	global_load_dwordx4 v[58:61], v[62:63], off offset:-4096 nt
	s_nop 0
	global_load_dwordx4 v[62:65], v[62:63], off nt
	v_add_co_u32_e32 v76, vcc, s30, v76
	v_add_u32_e32 v73, 0x1458, v84
	s_nop 0
	v_addc_co_u32_e32 v77, vcc, 0, v77, vcc
	global_load_dwordx4 v[76:79], v[76:77], off nt
	v_add_u32_e32 v115, 0x1860, v84
	v_add_u32_e32 v116, 0x1868, v84
	v_add_u32_e32 v117, 0x1c70, v84
	v_add_u32_e32 v118, 0x1c78, v84
	v_add_u32_e32 v119, 0x2080, v84
	v_add_u32_e32 v120, 0x2088, v84
	v_add_u32_e32 v121, 0x2490, v84
	s_waitcnt vmcnt(15)
	ds_write2_b32 v84, v6, v7 offset1:1
	ds_write2_b32 v84, v8, v9 offset0:2 offset1:3
	s_waitcnt vmcnt(12)
	ds_write2_b32 v117, v18, v19 offset1:1
	ds_write2_b32 v118, v20, v21 offset1:1
	s_waitcnt vmcnt(11)
	ds_write2_b32 v119, v22, v23 offset1:1
	ds_write2_b32 v120, v24, v25 offset1:1
	ds_write2_b32 v103, v10, v11 offset1:1
	ds_write2_b32 v104, v12, v13 offset1:1
	ds_write2_b32 v105, v14, v15 offset1:1
	ds_write2_b32 v106, v16, v17 offset1:1
	s_waitcnt vmcnt(10)
	ds_write2_b32 v107, v26, v27 offset1:1
	ds_write2_b32 v108, v28, v29 offset1:1
	s_waitcnt vmcnt(9)
	ds_write2_b32 v109, v30, v31 offset1:1
	ds_write2_b32 v110, v32, v33 offset1:1
	s_waitcnt vmcnt(8)
	ds_write2_b32 v111, v34, v35 offset1:1
	ds_write2_b32 v73, v36, v37 offset1:1
	s_waitcnt vmcnt(7)
	ds_write2_b32 v115, v38, v39 offset1:1
	ds_write2_b32 v116, v40, v41 offset1:1
	s_waitcnt vmcnt(6)
	ds_write2_b32 v121, v42, v43 offset1:1
	v_add_u32_e32 v6, 0x2498, v84
	ds_write2_b32 v6, v44, v45 offset1:1
	v_add_u32_e32 v6, 0x28a0, v84
	s_waitcnt vmcnt(5)
	ds_write2_b32 v6, v46, v47 offset1:1
	v_add_u32_e32 v6, 0x28a8, v84
	ds_write2_b32 v6, v48, v49 offset1:1
	v_add_u32_e32 v6, 0x2cb0, v84
	s_waitcnt vmcnt(4)
	ds_write2_b32 v6, v50, v51 offset1:1
	v_add_u32_e32 v6, 0x2cb8, v84
	ds_write2_b32 v6, v52, v53 offset1:1
	v_add_u32_e32 v6, 0x30c0, v84
	s_waitcnt vmcnt(3)
	ds_write2_b32 v6, v54, v55 offset1:1
	v_add_u32_e32 v6, 0x30c8, v84
	ds_write2_b32 v6, v56, v57 offset1:1
	v_add_u32_e32 v6, 0x34d0, v84
	s_waitcnt vmcnt(2)
	ds_write2_b32 v6, v58, v59 offset1:1
	v_add_u32_e32 v6, 0x34d8, v84
	ds_write2_b32 v6, v60, v61 offset1:1
	v_add_u32_e32 v6, 0x38e0, v84
	s_waitcnt vmcnt(1)
	ds_write2_b32 v6, v62, v63 offset1:1
	v_add_u32_e32 v6, 0x38e8, v84
	ds_write2_b32 v6, v64, v65 offset1:1
	v_add_u32_e32 v6, 0x3cf0, v84
	s_waitcnt vmcnt(0)
	ds_write2_b32 v6, v76, v77 offset1:1
	v_add_u32_e32 v6, 0x3cf8, v84
	ds_write2_b32 v6, v78, v79 offset1:1
	s_waitcnt lgkmcnt(0)
	ds_read2_b32 v[12:13], v86 offset1:8
	ds_read2_b32 v[14:15], v86 offset0:65 offset1:73
	ds_read2_b32 v[16:17], v86 offset0:130 offset1:138
	ds_read2_b32 v[18:19], v86 offset0:195 offset1:203
	v_add_u32_e32 v30, 0x400, v86
	s_waitcnt lgkmcnt(3)
	v_bfe_u32 v8, v12, 16, 1
	v_add3_u32 v8, v12, v8, s95
	s_waitcnt lgkmcnt(2)
	v_bfe_u32 v9, v14, 16, 1
	ds_read2_b32 v[20:21], v30 offset0:4 offset1:12
	v_lshrrev_b32_e32 v8, 16, v8
	v_add3_u32 v9, v14, v9, s95
	ds_read2_b32 v[22:23], v30 offset0:69 offset1:77
	v_and_or_b32 v8, v9, s96, v8
	s_waitcnt lgkmcnt(3)
	v_bfe_u32 v9, v16, 16, 1
	v_add3_u32 v9, v16, v9, s95
	s_waitcnt lgkmcnt(2)
	v_bfe_u32 v10, v18, 16, 1
	ds_read2_b32 v[24:25], v30 offset0:134 offset1:142
	v_lshrrev_b32_e32 v9, 16, v9
	v_add3_u32 v10, v18, v10, s95
	ds_read2_b32 v[26:27], v30 offset0:199 offset1:207
	v_and_or_b32 v9, v10, s96, v9
	s_waitcnt lgkmcnt(3)
	v_bfe_u32 v10, v20, 16, 1
	v_add3_u32 v10, v20, v10, s95
	s_waitcnt lgkmcnt(2)
	v_bfe_u32 v11, v22, 16, 1
	v_lshrrev_b32_e32 v10, 16, v10
	v_add3_u32 v11, v22, v11, s95
	v_and_or_b32 v10, v11, s96, v10
	s_waitcnt lgkmcnt(1)
	v_bfe_u32 v11, v24, 16, 1
	v_add3_u32 v11, v24, v11, s95
	s_waitcnt lgkmcnt(0)
	v_bfe_u32 v12, v26, 16, 1
	v_lshrrev_b32_e32 v11, 16, v11
	v_add3_u32 v12, v26, v12, s95
	v_and_or_b32 v11, v12, s96, v11
	v_lshlrev_b32_e32 v12, 11, v80
	v_or3_b32 v31, v12, v68, v100
	v_lshlrev_b64 v[6:7], 21, v[4:5]
	v_or_b32_e32 v12, v31, v95
	v_lshl_add_u64 v[6:7], s[52:53], 0, v[6:7]
	v_lshlrev_b32_e32 v68, 4, v12
	v_lshl_add_u64 v[28:29], v[6:7], 0, v[68:69]
	global_store_dwordx4 v[28:29], v[8:11], off
	v_bfe_u32 v12, v27, 16, 1
	v_or_b32_e32 v14, v31, v96
	v_bfe_u32 v8, v13, 16, 1
	v_add3_u32 v8, v13, v8, s95
	v_bfe_u32 v9, v15, 16, 1
	v_lshrrev_b32_e32 v8, 16, v8
	v_add3_u32 v9, v15, v9, s95
	v_and_or_b32 v8, v9, s96, v8
	v_bfe_u32 v9, v17, 16, 1
	v_add3_u32 v9, v17, v9, s95
	v_bfe_u32 v10, v19, 16, 1
	v_lshrrev_b32_e32 v9, 16, v9
	v_add3_u32 v10, v19, v10, s95
	v_and_or_b32 v9, v10, s96, v9
	v_bfe_u32 v10, v21, 16, 1
	v_add3_u32 v10, v21, v10, s95
	v_bfe_u32 v11, v23, 16, 1
	v_lshrrev_b32_e32 v10, 16, v10
	v_add3_u32 v11, v23, v11, s95
	v_and_or_b32 v10, v11, s96, v10
	v_bfe_u32 v11, v25, 16, 1
	v_add3_u32 v11, v25, v11, s95
	v_lshrrev_b32_e32 v11, 16, v11
	v_add3_u32 v12, v27, v12, s95
	v_lshlrev_b32_e32 v68, 4, v14
	v_and_or_b32 v11, v12, s96, v11
	ds_read2_b32 v[12:13], v86 offset0:16 offset1:24
	v_lshl_add_u64 v[14:15], v[6:7], 0, v[68:69]
	global_store_dwordx4 v[14:15], v[8:11], off
	ds_read2_b32 v[14:15], v86 offset0:81 offset1:89
	ds_read2_b32 v[16:17], v86 offset0:146 offset1:154
	ds_read2_b32 v[18:19], v86 offset0:211 offset1:219
	s_waitcnt lgkmcnt(3)
	v_bfe_u32 v8, v12, 16, 1
	v_add3_u32 v8, v12, v8, s95
	s_waitcnt lgkmcnt(2)
	v_bfe_u32 v9, v14, 16, 1
	ds_read2_b32 v[20:21], v30 offset0:20 offset1:28
	v_lshrrev_b32_e32 v8, 16, v8
	v_add3_u32 v9, v14, v9, s95
	ds_read2_b32 v[22:23], v30 offset0:85 offset1:93
	v_and_or_b32 v8, v9, s96, v8
	s_waitcnt lgkmcnt(3)
	v_bfe_u32 v9, v16, 16, 1
	v_add3_u32 v9, v16, v9, s95
	s_waitcnt lgkmcnt(2)
	v_bfe_u32 v10, v18, 16, 1
	ds_read2_b32 v[24:25], v30 offset0:150 offset1:158
	v_lshrrev_b32_e32 v9, 16, v9
	v_add3_u32 v10, v18, v10, s95
	ds_read2_b32 v[26:27], v30 offset0:215 offset1:223
	v_and_or_b32 v9, v10, s96, v9
	s_waitcnt lgkmcnt(3)
	v_bfe_u32 v10, v20, 16, 1
	v_add3_u32 v10, v20, v10, s95
	s_waitcnt lgkmcnt(2)
	v_bfe_u32 v11, v22, 16, 1
	v_lshrrev_b32_e32 v10, 16, v10
	v_add3_u32 v11, v22, v11, s95
	v_and_or_b32 v10, v11, s96, v10
	s_waitcnt lgkmcnt(1)
	v_bfe_u32 v11, v24, 16, 1
	v_add3_u32 v11, v24, v11, s95
	s_waitcnt lgkmcnt(0)
	v_bfe_u32 v12, v26, 16, 1
	v_or_b32_e32 v14, 64, v31
	v_lshrrev_b32_e32 v11, 16, v11
	v_add3_u32 v12, v26, v12, s95
	v_or_b32_e32 v68, v14, v95
	v_and_or_b32 v11, v12, s96, v11
	v_lshl_add_u64 v[28:29], v[68:69], 4, v[6:7]
	global_store_dwordx4 v[28:29], v[8:11], off
	v_bfe_u32 v12, v27, 16, 1
	v_add3_u32 v12, v27, v12, s95
	v_bfe_u32 v8, v13, 16, 1
	v_add3_u32 v8, v13, v8, s95
	v_bfe_u32 v9, v15, 16, 1
	v_lshrrev_b32_e32 v8, 16, v8
	v_add3_u32 v9, v15, v9, s95
	v_and_or_b32 v8, v9, s96, v8
	v_bfe_u32 v9, v17, 16, 1
	v_add3_u32 v9, v17, v9, s95
	v_bfe_u32 v10, v19, 16, 1
	v_lshrrev_b32_e32 v9, 16, v9
	v_add3_u32 v10, v19, v10, s95
	v_and_or_b32 v9, v10, s96, v9
	v_bfe_u32 v10, v21, 16, 1
	v_add3_u32 v10, v21, v10, s95
	v_bfe_u32 v11, v23, 16, 1
	v_lshrrev_b32_e32 v10, 16, v10
	v_add3_u32 v11, v23, v11, s95
	v_and_or_b32 v10, v11, s96, v10
	v_bfe_u32 v11, v25, 16, 1
	v_add3_u32 v11, v25, v11, s95
	v_lshrrev_b32_e32 v11, 16, v11
	v_or_b32_e32 v68, v14, v97
	v_and_or_b32 v11, v12, s96, v11
	ds_read2_b32 v[12:13], v86 offset0:32 offset1:40
	v_lshl_add_u64 v[14:15], v[68:69], 4, v[6:7]
	global_store_dwordx4 v[14:15], v[8:11], off
	ds_read2_b32 v[14:15], v86 offset0:97 offset1:105
	ds_read2_b32 v[16:17], v86 offset0:162 offset1:170
	ds_read2_b32 v[18:19], v86 offset0:227 offset1:235
	s_waitcnt lgkmcnt(3)
	v_bfe_u32 v8, v12, 16, 1
	v_add3_u32 v8, v12, v8, s95
	s_waitcnt lgkmcnt(2)
	v_bfe_u32 v9, v14, 16, 1
	ds_read2_b32 v[20:21], v30 offset0:36 offset1:44
	v_lshrrev_b32_e32 v8, 16, v8
	v_add3_u32 v9, v14, v9, s95
	ds_read2_b32 v[22:23], v30 offset0:101 offset1:109
	v_and_or_b32 v8, v9, s96, v8
	s_waitcnt lgkmcnt(3)
	v_bfe_u32 v9, v16, 16, 1
	v_add3_u32 v9, v16, v9, s95
	s_waitcnt lgkmcnt(2)
	v_bfe_u32 v10, v18, 16, 1
	ds_read2_b32 v[24:25], v30 offset0:166 offset1:174
	v_lshrrev_b32_e32 v9, 16, v9
	v_add3_u32 v10, v18, v10, s95
	ds_read2_b32 v[26:27], v30 offset0:231 offset1:239
	v_and_or_b32 v9, v10, s96, v9
	s_waitcnt lgkmcnt(3)
	v_bfe_u32 v10, v20, 16, 1
	v_add3_u32 v10, v20, v10, s95
	s_waitcnt lgkmcnt(2)
	v_bfe_u32 v11, v22, 16, 1
	v_lshrrev_b32_e32 v10, 16, v10
	v_add3_u32 v11, v22, v11, s95
	v_and_or_b32 v10, v11, s96, v10
	s_waitcnt lgkmcnt(1)
	v_bfe_u32 v11, v24, 16, 1
	v_add3_u32 v11, v24, v11, s95
	s_waitcnt lgkmcnt(0)
	v_bfe_u32 v12, v26, 16, 1
	v_or_b32_e32 v14, 0x80, v31
	v_lshrrev_b32_e32 v11, 16, v11
	v_add3_u32 v12, v26, v12, s95
	v_or_b32_e32 v68, v14, v95
	v_and_or_b32 v11, v12, s96, v11
	v_lshl_add_u64 v[28:29], v[68:69], 4, v[6:7]
	global_store_dwordx4 v[28:29], v[8:11], off
	v_bfe_u32 v12, v27, 16, 1
	v_add3_u32 v12, v27, v12, s95
	v_bfe_u32 v8, v13, 16, 1
	v_add3_u32 v8, v13, v8, s95
	v_bfe_u32 v9, v15, 16, 1
	v_lshrrev_b32_e32 v8, 16, v8
	v_add3_u32 v9, v15, v9, s95
	v_and_or_b32 v8, v9, s96, v8
	v_bfe_u32 v9, v17, 16, 1
	v_add3_u32 v9, v17, v9, s95
	v_bfe_u32 v10, v19, 16, 1
	v_lshrrev_b32_e32 v9, 16, v9
	v_add3_u32 v10, v19, v10, s95
	v_and_or_b32 v9, v10, s96, v9
	v_bfe_u32 v10, v21, 16, 1
	v_add3_u32 v10, v21, v10, s95
	v_bfe_u32 v11, v23, 16, 1
	v_lshrrev_b32_e32 v10, 16, v10
	v_add3_u32 v11, v23, v11, s95
	v_and_or_b32 v10, v11, s96, v10
	v_bfe_u32 v11, v25, 16, 1
	v_add3_u32 v11, v25, v11, s95
	v_lshrrev_b32_e32 v11, 16, v11
	v_or_b32_e32 v68, v14, v98
	v_and_or_b32 v11, v12, s96, v11
	ds_read2_b32 v[12:13], v86 offset0:48 offset1:56
	v_lshl_add_u64 v[14:15], v[68:69], 4, v[6:7]
	global_store_dwordx4 v[14:15], v[8:11], off
	ds_read2_b32 v[14:15], v86 offset0:113 offset1:121
	ds_read2_b32 v[16:17], v86 offset0:178 offset1:186
	ds_read2_b32 v[18:19], v86 offset0:243 offset1:251
	s_waitcnt lgkmcnt(3)
	v_bfe_u32 v8, v12, 16, 1
	v_add3_u32 v8, v12, v8, s95
	s_waitcnt lgkmcnt(2)
	v_bfe_u32 v9, v14, 16, 1
	ds_read2_b32 v[20:21], v30 offset0:52 offset1:60
	v_lshrrev_b32_e32 v8, 16, v8
	v_add3_u32 v9, v14, v9, s95
	ds_read2_b32 v[22:23], v30 offset0:117 offset1:125
	v_and_or_b32 v8, v9, s96, v8
	s_waitcnt lgkmcnt(3)
	v_bfe_u32 v9, v16, 16, 1
	v_add3_u32 v9, v16, v9, s95
	s_waitcnt lgkmcnt(2)
	v_bfe_u32 v10, v18, 16, 1
	ds_read2_b32 v[24:25], v30 offset0:182 offset1:190
	v_lshrrev_b32_e32 v9, 16, v9
	v_add3_u32 v10, v18, v10, s95
	ds_read2_b32 v[26:27], v30 offset0:247 offset1:255
	v_and_or_b32 v9, v10, s96, v9
	s_waitcnt lgkmcnt(3)
	v_bfe_u32 v10, v20, 16, 1
	v_add3_u32 v10, v20, v10, s95
	s_waitcnt lgkmcnt(2)
	v_bfe_u32 v11, v22, 16, 1
	v_lshrrev_b32_e32 v10, 16, v10
	v_add3_u32 v11, v22, v11, s95
	v_and_or_b32 v10, v11, s96, v10
	s_waitcnt lgkmcnt(1)
	v_bfe_u32 v11, v24, 16, 1
	v_add3_u32 v11, v24, v11, s95
	s_waitcnt lgkmcnt(0)
	v_bfe_u32 v12, v26, 16, 1
	v_lshrrev_b32_e32 v11, 16, v11
	v_add3_u32 v12, v26, v12, s95
	v_and_or_b32 v11, v12, s96, v11
	v_or_b32_e32 v12, 0xc0, v31
	v_or_b32_e32 v68, v12, v95
	v_lshl_add_u64 v[28:29], v[68:69], 4, v[6:7]
	global_store_dwordx4 v[28:29], v[8:11], off
	v_or_b32_e32 v68, v12, v99
	v_lshl_add_u64 v[6:7], v[68:69], 4, v[6:7]
	v_bfe_u32 v8, v13, 16, 1
	v_add3_u32 v8, v13, v8, s95
	v_bfe_u32 v9, v15, 16, 1
	v_lshrrev_b32_e32 v8, 16, v8
	v_add3_u32 v9, v15, v9, s95
	v_and_or_b32 v8, v9, s96, v8
	v_bfe_u32 v9, v17, 16, 1
	v_add3_u32 v9, v17, v9, s95
	v_bfe_u32 v10, v19, 16, 1
	v_lshrrev_b32_e32 v9, 16, v9
	v_add3_u32 v10, v19, v10, s95
	v_and_or_b32 v9, v10, s96, v9
	v_bfe_u32 v10, v21, 16, 1
	v_add3_u32 v10, v21, v10, s95
	v_bfe_u32 v11, v23, 16, 1
	v_lshrrev_b32_e32 v10, 16, v10
	v_add3_u32 v11, v23, v11, s95
	v_and_or_b32 v10, v11, s96, v10
	v_bfe_u32 v11, v25, 16, 1
	v_add3_u32 v11, v25, v11, s95
	v_bfe_u32 v13, v27, 16, 1
	v_lshrrev_b32_e32 v11, 16, v11
	v_add3_u32 v13, v27, v13, s95
	v_and_or_b32 v11, v13, s96, v11
	global_store_dwordx4 v[6:7], v[8:11], off
	s_waitcnt lgkmcnt(0)

.LBB0_88:
	v_lshlrev_b32_e32 v11, 5, v81
	v_and_b32_e32 v11, 0xc0, v11
	v_lshlrev_b32_e32 v10, 6, v81
	v_or_b32_e32 v12, v11, v83
	v_lshl_add_u64 v[8:9], v[6:7], 2, s[22:23]
	v_and_b32_e32 v10, 64, v10
	v_lshlrev_b32_e32 v68, 9, v12
	v_lshl_add_u64 v[8:9], v[8:9], 0, v[68:69]
	v_lshlrev_b32_e32 v68, 2, v10
	v_lshl_add_u64 v[8:9], v[8:9], 0, v[68:69]
	v_mov_b32_e32 v73, v69
	v_lshl_add_u64 v[8:9], v[8:9], 0, v[72:73]
	s_movk_i32 s2, 0x1000
	v_add_co_u32_e64 v24, s[2:3], s2, v8
	global_load_dwordx4 v[12:15], v[8:9], off nt
	global_load_dwordx4 v[16:19], v[8:9], off offset:2048 nt
	v_addc_co_u32_e64 v25, s[2:3], 0, v9, s[2:3]
	s_movk_i32 s2, 0x2000
	s_nop 0
	v_add_co_u32_e64 v32, s[2:3], s2, v8
	v_add_u32_e32 v68, 0x1c70, v84
	s_nop 0
	v_addc_co_u32_e64 v33, s[2:3], 0, v9, s[2:3]
	s_movk_i32 s2, 0x3000
	s_nop 0
	v_add_co_u32_e64 v36, s[2:3], s2, v8
	global_load_dwordx4 v[20:23], v[32:33], off offset:-4096 nt
	s_nop 0
	global_load_dwordx4 v[24:27], v[24:25], off offset:2048 nt
	s_nop 0
	global_load_dwordx4 v[28:31], v[32:33], off nt
	s_nop 0
	global_load_dwordx4 v[32:35], v[32:33], off offset:2048 nt
	v_addc_co_u32_e64 v37, s[2:3], 0, v9, s[2:3]
	s_movk_i32 s2, 0x4000
	s_nop 0
	v_add_co_u32_e64 v48, s[2:3], s2, v8
	v_add_u32_e32 v73, 0x1c78, v84
	s_nop 0
	v_addc_co_u32_e64 v49, s[2:3], 0, v9, s[2:3]
	s_movk_i32 s2, 0x6000
	s_nop 0
	v_add_co_u32_e64 v64, s[2:3], s2, v8
	global_load_dwordx4 v[36:39], v[36:37], off offset:2048 nt
	s_nop 0
	global_load_dwordx4 v[40:43], v[48:49], off offset:-4096 nt
	global_load_dwordx4 v[44:47], v[48:49], off nt
	v_addc_co_u32_e64 v65, s[2:3], 0, v9, s[2:3]
	global_load_dwordx4 v[48:51], v[48:49], off offset:2048 nt
	s_nop 0
	global_load_dwordx4 v[52:55], v[64:65], off offset:-4096 nt
	s_movk_i32 s2, 0x5000
	v_add_co_u32_e64 v56, s[2:3], s2, v8
	v_add_u32_e32 v78, 0x2080, v84
	s_nop 0
	v_addc_co_u32_e64 v57, s[2:3], 0, v9, s[2:3]
	global_load_dwordx4 v[56:59], v[56:57], off offset:2048 nt
	s_nop 0
	global_load_dwordx4 v[60:63], v[64:65], off nt
	global_load_dwordx4 v[74:77], v[64:65], off offset:2048 nt
	s_movk_i32 s2, 0x7000
	v_add_co_u32_e64 v8, s[2:3], s2, v8
	v_add_u32_e32 v64, 0x1860, v84
	s_nop 0
	v_addc_co_u32_e64 v9, s[2:3], 0, v9, s[2:3]
	global_load_dwordx4 v[116:119], v[8:9], off nt
	global_load_dwordx4 v[120:123], v[8:9], off offset:2048 nt
	v_lshlrev_b64 v[8:9], 16, v[4:5]
	v_add_u32_e32 v5, 0x1458, v84
	v_add_u32_e32 v65, 0x1868, v84
	v_add_u32_e32 v79, 0x2088, v84
	v_add_u32_e32 v80, 0x2490, v84
	v_add_u32_e32 v115, 0x2498, v84
	v_add_u32_e32 v124, 0x28a0, v84
	v_lshl_add_u64 v[8:9], s[0:1], 0, v[8:9]
	s_waitcnt vmcnt(15)
	ds_write2_b32 v84, v12, v13 offset1:1
	ds_write2_b32 v84, v14, v15 offset0:2 offset1:3
	s_waitcnt vmcnt(14)
	ds_write2_b32 v103, v16, v17 offset1:1
	ds_write2_b32 v104, v18, v19 offset1:1
	s_waitcnt vmcnt(13)
	ds_write2_b32 v105, v20, v21 offset1:1
	ds_write2_b32 v106, v22, v23 offset1:1
	s_waitcnt vmcnt(12)
	ds_write2_b32 v107, v24, v25 offset1:1
	ds_write2_b32 v108, v26, v27 offset1:1
	s_waitcnt vmcnt(11)
	ds_write2_b32 v109, v28, v29 offset1:1
	ds_write2_b32 v110, v30, v31 offset1:1
	s_waitcnt vmcnt(10)
	ds_write2_b32 v111, v32, v33 offset1:1
	ds_write2_b32 v5, v34, v35 offset1:1
	s_waitcnt vmcnt(8)
	ds_write2_b32 v64, v40, v41 offset1:1
	ds_write2_b32 v65, v42, v43 offset1:1
	ds_write2_b32 v68, v36, v37 offset1:1
	ds_write2_b32 v73, v38, v39 offset1:1
	s_waitcnt vmcnt(7)
	ds_write2_b32 v78, v44, v45 offset1:1
	ds_write2_b32 v79, v46, v47 offset1:1
	s_waitcnt vmcnt(6)
	ds_write2_b32 v80, v48, v49 offset1:1
	ds_write2_b32 v115, v50, v51 offset1:1
	s_waitcnt vmcnt(5)
	ds_write2_b32 v124, v52, v53 offset1:1
	v_add_u32_e32 v5, 0x28a8, v84
	ds_write2_b32 v5, v54, v55 offset1:1
	v_add_u32_e32 v5, 0x2cb0, v84
	v_lshlrev_b32_e32 v68, 1, v11
	s_waitcnt vmcnt(4)
	ds_write2_b32 v5, v56, v57 offset1:1
	v_add_u32_e32 v5, 0x2cb8, v84
	ds_write2_b32 v5, v58, v59 offset1:1
	v_add_u32_e32 v5, 0x30c0, v84
	s_waitcnt vmcnt(3)
	ds_write2_b32 v5, v60, v61 offset1:1
	v_add_u32_e32 v5, 0x30c8, v84
	ds_write2_b32 v5, v62, v63 offset1:1
	v_add_u32_e32 v5, 0x34d0, v84
	s_waitcnt vmcnt(2)
	ds_write2_b32 v5, v74, v75 offset1:1
	v_add_u32_e32 v5, 0x34d8, v84
	ds_write2_b32 v5, v76, v77 offset1:1
	v_add_u32_e32 v5, 0x38e0, v84
	s_waitcnt vmcnt(1)
	ds_write2_b32 v5, v116, v117 offset1:1
	v_add_u32_e32 v5, 0x38e8, v84
	ds_write2_b32 v5, v118, v119 offset1:1
	v_add_u32_e32 v5, 0x3cf0, v84
	s_waitcnt vmcnt(0)
	ds_write2_b32 v5, v120, v121 offset1:1
	v_add_u32_e32 v5, 0x3cf8, v84
	ds_write2_b32 v5, v122, v123 offset1:1
	s_waitcnt lgkmcnt(0)
	v_add_u32_e32 v5, 0x400, v86
	ds_read2_b32 v[18:19], v5 offset0:134 offset1:142
	ds_read2_b32 v[16:17], v5 offset0:199 offset1:207
	ds_read2_b32 v[22:23], v5 offset0:4 offset1:12
	ds_read2_b32 v[20:21], v5 offset0:69 offset1:77
	ds_read2_b32 v[26:27], v86 offset0:130 offset1:138
	s_waitcnt lgkmcnt(4)
	v_bfe_u32 v12, v18, 16, 1
	s_waitcnt lgkmcnt(3)
	v_bfe_u32 v11, v16, 16, 1
	v_add3_u32 v12, v18, v12, s95
	v_add3_u32 v11, v16, v11, s95
	v_lshrrev_b32_e32 v12, 16, v12
	ds_read2_b32 v[24:25], v86 offset0:195 offset1:203
	v_and_or_b32 v15, v11, s96, v12
	s_waitcnt lgkmcnt(3)
	v_bfe_u32 v12, v22, 16, 1
	s_waitcnt lgkmcnt(2)
	v_bfe_u32 v11, v20, 16, 1
	v_add3_u32 v12, v22, v12, s95
	ds_read2_b32 v[30:31], v86 offset1:8
	v_add3_u32 v11, v20, v11, s95
	v_lshrrev_b32_e32 v12, 16, v12
	ds_read2_b32 v[28:29], v86 offset0:65 offset1:73
	v_and_or_b32 v14, v11, s96, v12
	s_waitcnt lgkmcnt(3)
	v_bfe_u32 v12, v26, 16, 1
	s_waitcnt lgkmcnt(2)
	v_bfe_u32 v11, v24, 16, 1
	v_add3_u32 v12, v26, v12, s95
	v_add3_u32 v11, v24, v11, s95
	v_lshrrev_b32_e32 v12, 16, v12
	v_and_or_b32 v13, v11, s96, v12
	s_waitcnt lgkmcnt(1)
	v_bfe_u32 v12, v30, 16, 1
	s_waitcnt lgkmcnt(0)
	v_bfe_u32 v11, v28, 16, 1
	v_add3_u32 v12, v30, v12, s95
	v_add3_u32 v11, v28, v11, s95
	v_lshrrev_b32_e32 v12, 16, v12
	v_lshl_add_u64 v[8:9], v[8:9], 0, v[68:69]
	v_lshlrev_b32_e32 v68, 1, v70
	v_and_or_b32 v12, v11, s96, v12
	v_or_b32_e32 v11, v10, v85
	v_lshl_add_u64 v[8:9], v[8:9], 0, v[68:69]
	v_lshlrev_b32_e32 v68, 9, v11
	v_lshl_add_u64 v[32:33], v[8:9], 0, v[68:69]
	global_store_dwordx4 v[32:33], v[12:15], off
	v_bfe_u32 v11, v17, 16, 1
	v_add3_u32 v11, v17, v11, s95
	v_bfe_u32 v12, v19, 16, 1
	v_add3_u32 v12, v19, v12, s95
	v_lshrrev_b32_e32 v12, 16, v12
	v_and_or_b32 v15, v11, s96, v12
	v_bfe_u32 v12, v23, 16, 1
	v_bfe_u32 v11, v21, 16, 1
	v_add3_u32 v12, v23, v12, s95
	v_add3_u32 v11, v21, v11, s95
	v_lshrrev_b32_e32 v12, 16, v12
	v_and_or_b32 v14, v11, s96, v12
	v_bfe_u32 v12, v27, 16, 1
	v_bfe_u32 v11, v25, 16, 1
	v_add3_u32 v12, v27, v12, s95
	v_add3_u32 v11, v25, v11, s95
	v_lshrrev_b32_e32 v12, 16, v12
	v_and_or_b32 v13, v11, s96, v12
	v_bfe_u32 v12, v31, 16, 1
	v_bfe_u32 v11, v29, 16, 1
	v_add3_u32 v12, v31, v12, s95
	v_add3_u32 v11, v29, v11, s95
	v_lshrrev_b32_e32 v12, 16, v12
	ds_read2_b32 v[18:19], v5 offset0:150 offset1:158
	v_and_or_b32 v12, v11, s96, v12
	v_or_b32_e32 v11, v10, v87
	ds_read2_b32 v[16:17], v5 offset0:215 offset1:223
	v_lshlrev_b32_e32 v68, 9, v11
	v_lshl_add_u64 v[20:21], v[8:9], 0, v[68:69]
	ds_read2_b32 v[22:23], v5 offset0:20 offset1:28
	global_store_dwordx4 v[20:21], v[12:15], off
	ds_read2_b32 v[20:21], v5 offset0:85 offset1:93
	s_waitcnt lgkmcnt(2)
	v_bfe_u32 v11, v16, 16, 1
	v_bfe_u32 v12, v18, 16, 1
	v_add3_u32 v12, v18, v12, s95
	ds_read2_b32 v[26:27], v86 offset0:146 offset1:154
	v_add3_u32 v11, v16, v11, s95
	v_lshrrev_b32_e32 v12, 16, v12
	ds_read2_b32 v[24:25], v86 offset0:211 offset1:219
	v_and_or_b32 v15, v11, s96, v12
	s_waitcnt lgkmcnt(3)
	v_bfe_u32 v12, v22, 16, 1
	s_waitcnt lgkmcnt(2)
	v_bfe_u32 v11, v20, 16, 1
	v_add3_u32 v12, v22, v12, s95
	ds_read2_b32 v[30:31], v86 offset0:16 offset1:24
	v_add3_u32 v11, v20, v11, s95
	v_lshrrev_b32_e32 v12, 16, v12
	ds_read2_b32 v[28:29], v86 offset0:81 offset1:89
	v_and_or_b32 v14, v11, s96, v12
	s_waitcnt lgkmcnt(3)
	v_bfe_u32 v12, v26, 16, 1
	s_waitcnt lgkmcnt(2)
	v_bfe_u32 v11, v24, 16, 1
	v_add3_u32 v12, v26, v12, s95
	v_add3_u32 v11, v24, v11, s95
	v_lshrrev_b32_e32 v12, 16, v12
	v_and_or_b32 v13, v11, s96, v12
	s_waitcnt lgkmcnt(1)
	v_bfe_u32 v12, v30, 16, 1
	s_waitcnt lgkmcnt(0)
	v_bfe_u32 v11, v28, 16, 1
	v_add3_u32 v12, v30, v12, s95
	v_add3_u32 v11, v28, v11, s95
	v_lshrrev_b32_e32 v12, 16, v12
	v_and_or_b32 v12, v11, s96, v12
	v_or_b32_e32 v11, v10, v88
	v_lshlrev_b32_e32 v68, 9, v11
	v_lshl_add_u64 v[32:33], v[8:9], 0, v[68:69]
	global_store_dwordx4 v[32:33], v[12:15], off
	v_bfe_u32 v11, v17, 16, 1
	v_add3_u32 v11, v17, v11, s95
	v_bfe_u32 v12, v19, 16, 1
	v_add3_u32 v12, v19, v12, s95
	v_lshrrev_b32_e32 v12, 16, v12
	v_and_or_b32 v15, v11, s96, v12
	v_bfe_u32 v12, v23, 16, 1
	v_bfe_u32 v11, v21, 16, 1
	v_add3_u32 v12, v23, v12, s95
	v_add3_u32 v11, v21, v11, s95
	v_lshrrev_b32_e32 v12, 16, v12
	v_and_or_b32 v14, v11, s96, v12
	v_bfe_u32 v12, v27, 16, 1
	v_bfe_u32 v11, v25, 16, 1
	v_add3_u32 v12, v27, v12, s95
	v_add3_u32 v11, v25, v11, s95
	v_lshrrev_b32_e32 v12, 16, v12
	v_and_or_b32 v13, v11, s96, v12
	v_bfe_u32 v12, v31, 16, 1
	v_bfe_u32 v11, v29, 16, 1
	v_add3_u32 v12, v31, v12, s95
	v_add3_u32 v11, v29, v11, s95
	v_lshrrev_b32_e32 v12, 16, v12
	ds_read2_b32 v[18:19], v5 offset0:166 offset1:174
	v_and_or_b32 v12, v11, s96, v12
	v_or_b32_e32 v11, v10, v89
	ds_read2_b32 v[16:17], v5 offset0:231 offset1:239
	v_lshlrev_b32_e32 v68, 9, v11
	v_lshl_add_u64 v[20:21], v[8:9], 0, v[68:69]
	ds_read2_b32 v[22:23], v5 offset0:36 offset1:44
	global_store_dwordx4 v[20:21], v[12:15], off
	ds_read2_b32 v[20:21], v5 offset0:101 offset1:109
	s_waitcnt lgkmcnt(2)
	v_bfe_u32 v11, v16, 16, 1
	v_bfe_u32 v12, v18, 16, 1
	v_add3_u32 v12, v18, v12, s95
	ds_read2_b32 v[26:27], v86 offset0:162 offset1:170
	v_add3_u32 v11, v16, v11, s95
	v_lshrrev_b32_e32 v12, 16, v12
	ds_read2_b32 v[24:25], v86 offset0:227 offset1:235
	v_and_or_b32 v15, v11, s96, v12
	s_waitcnt lgkmcnt(3)
	v_bfe_u32 v12, v22, 16, 1
	s_waitcnt lgkmcnt(2)
	v_bfe_u32 v11, v20, 16, 1
	v_add3_u32 v12, v22, v12, s95
	ds_read2_b32 v[30:31], v86 offset0:32 offset1:40
	v_add3_u32 v11, v20, v11, s95
	v_lshrrev_b32_e32 v12, 16, v12
	ds_read2_b32 v[28:29], v86 offset0:97 offset1:105
	v_and_or_b32 v14, v11, s96, v12
	s_waitcnt lgkmcnt(3)
	v_bfe_u32 v12, v26, 16, 1
	s_waitcnt lgkmcnt(2)
	v_bfe_u32 v11, v24, 16, 1
	v_add3_u32 v12, v26, v12, s95
	v_add3_u32 v11, v24, v11, s95
	v_lshrrev_b32_e32 v12, 16, v12
	v_and_or_b32 v13, v11, s96, v12
	s_waitcnt lgkmcnt(1)
	v_bfe_u32 v12, v30, 16, 1
	s_waitcnt lgkmcnt(0)
	v_bfe_u32 v11, v28, 16, 1
	v_add3_u32 v12, v30, v12, s95
	v_add3_u32 v11, v28, v11, s95
	v_lshrrev_b32_e32 v12, 16, v12
	v_and_or_b32 v12, v11, s96, v12
	v_or_b32_e32 v11, v10, v90
	v_lshlrev_b32_e32 v68, 9, v11
	v_lshl_add_u64 v[32:33], v[8:9], 0, v[68:69]
	global_store_dwordx4 v[32:33], v[12:15], off
	v_bfe_u32 v11, v17, 16, 1
	v_add3_u32 v11, v17, v11, s95
	v_bfe_u32 v12, v19, 16, 1
	v_add3_u32 v12, v19, v12, s95
	v_lshrrev_b32_e32 v12, 16, v12
	v_and_or_b32 v15, v11, s96, v12
	v_bfe_u32 v12, v23, 16, 1
	v_bfe_u32 v11, v21, 16, 1
	v_add3_u32 v12, v23, v12, s95
	v_add3_u32 v11, v21, v11, s95
	v_lshrrev_b32_e32 v12, 16, v12
	v_and_or_b32 v14, v11, s96, v12
	v_bfe_u32 v12, v27, 16, 1
	v_bfe_u32 v11, v25, 16, 1
	v_add3_u32 v12, v27, v12, s95
	v_add3_u32 v11, v25, v11, s95
	v_lshrrev_b32_e32 v12, 16, v12
	v_and_or_b32 v13, v11, s96, v12
	v_bfe_u32 v12, v31, 16, 1
	v_bfe_u32 v11, v29, 16, 1
	v_add3_u32 v12, v31, v12, s95
	v_add3_u32 v11, v29, v11, s95
	v_lshrrev_b32_e32 v12, 16, v12
	ds_read2_b32 v[18:19], v5 offset0:182 offset1:190
	v_and_or_b32 v12, v11, s96, v12
	v_or_b32_e32 v11, v10, v91
	ds_read2_b32 v[16:17], v5 offset0:247 offset1:255
	v_lshlrev_b32_e32 v68, 9, v11
	v_lshl_add_u64 v[20:21], v[8:9], 0, v[68:69]
	ds_read2_b32 v[22:23], v5 offset0:52 offset1:60
	global_store_dwordx4 v[20:21], v[12:15], off
	ds_read2_b32 v[20:21], v5 offset0:117 offset1:125
	s_waitcnt lgkmcnt(2)
	v_bfe_u32 v11, v16, 16, 1
	v_bfe_u32 v12, v18, 16, 1
	v_add3_u32 v12, v18, v12, s95
	ds_read2_b32 v[26:27], v86 offset0:178 offset1:186
	v_add3_u32 v11, v16, v11, s95
	v_lshrrev_b32_e32 v5, 16, v12
	ds_read2_b32 v[24:25], v86 offset0:243 offset1:251
	v_and_or_b32 v15, v11, s96, v5
	s_waitcnt lgkmcnt(3)
	v_bfe_u32 v11, v22, 16, 1
	s_waitcnt lgkmcnt(2)
	v_bfe_u32 v5, v20, 16, 1
	v_add3_u32 v11, v22, v11, s95
	ds_read2_b32 v[30:31], v86 offset0:48 offset1:56
	v_add3_u32 v5, v20, v5, s95
	v_lshrrev_b32_e32 v11, 16, v11
	ds_read2_b32 v[28:29], v86 offset0:113 offset1:121
	v_and_or_b32 v14, v5, s96, v11
	s_waitcnt lgkmcnt(3)
	v_bfe_u32 v11, v26, 16, 1
	s_waitcnt lgkmcnt(2)
	v_bfe_u32 v5, v24, 16, 1
	v_add3_u32 v11, v26, v11, s95
	v_add3_u32 v5, v24, v5, s95
	v_lshrrev_b32_e32 v11, 16, v11
	v_and_or_b32 v13, v5, s96, v11
	s_waitcnt lgkmcnt(1)
	v_bfe_u32 v11, v30, 16, 1
	s_waitcnt lgkmcnt(0)
	v_bfe_u32 v5, v28, 16, 1
	v_add3_u32 v11, v30, v11, s95
	v_add3_u32 v5, v28, v5, s95
	v_lshrrev_b32_e32 v11, 16, v11
	v_and_or_b32 v12, v5, s96, v11
	v_or_b32_e32 v5, v10, v92
	v_bfe_u32 v11, v19, 16, 1
	v_lshlrev_b32_e32 v68, 9, v5
	v_bfe_u32 v5, v17, 16, 1
	v_add3_u32 v11, v19, v11, s95
	v_lshl_add_u64 v[32:33], v[8:9], 0, v[68:69]
	v_add3_u32 v5, v17, v5, s95
	v_lshrrev_b32_e32 v11, 16, v11
	global_store_dwordx4 v[32:33], v[12:15], off
	s_nop 1
	v_and_or_b32 v15, v5, s96, v11
	v_bfe_u32 v11, v23, 16, 1
	v_bfe_u32 v5, v21, 16, 1
	v_add3_u32 v11, v23, v11, s95
	v_add3_u32 v5, v21, v5, s95
	v_lshrrev_b32_e32 v11, 16, v11
	v_and_or_b32 v14, v5, s96, v11
	v_bfe_u32 v11, v27, 16, 1
	v_bfe_u32 v5, v25, 16, 1
	v_add3_u32 v11, v27, v11, s95
	v_add3_u32 v5, v25, v5, s95
	v_lshrrev_b32_e32 v11, 16, v11
	v_and_or_b32 v13, v5, s96, v11
	v_bfe_u32 v11, v31, 16, 1
	v_bfe_u32 v5, v29, 16, 1
	v_add3_u32 v11, v31, v11, s95
	v_add3_u32 v5, v29, v5, s95
	v_lshrrev_b32_e32 v11, 16, v11
	v_and_or_b32 v12, v5, s96, v11
	v_or_b32_e32 v5, v10, v93
	v_lshlrev_b32_e32 v68, 9, v5
	v_lshl_add_u64 v[8:9], v[8:9], 0, v[68:69]
	global_store_dwordx4 v[8:9], v[12:15], off
	s_waitcnt lgkmcnt(0)
	s_or_b64 exec, exec, s[4:5]
	s_and_b64 exec, exec, vcc
	s_cbranch_execz .LBB0_95
.LBB0_89:
	v_or_b32_e32 v4, 1, v4
	v_ashrrev_i32_e32 v5, 31, v4
	v_cmp_lt_u32_e64 s[2:3], s58, v81
	v_cmp_gt_u32_e32 vcc, s59, v81
	s_and_saveexec_b64 s[4:5], vcc
	s_xor_b64 s[4:5], exec, s[4:5]
	s_cbranch_execz .LBB0_91
	v_lshrrev_b32_e32 v78, 2, v81
	v_lshl_add_u64 v[2:3], v[2:3], 2, s[26:27]
	v_lshl_or_b32 v68, v78, 16, v94
	v_lshlrev_b32_e32 v8, 8, v81
	v_lshl_add_u64 v[2:3], v[2:3], 0, v[68:69]
	v_and_b32_e32 v68, 0x300, v8
	v_lshl_add_u64 v[2:3], v[2:3], 0, v[68:69]
	v_mov_b32_e32 v73, v69
	v_lshl_add_u64 v[2:3], v[2:3], 0, v[72:73]
	s_movk_i32 s30, 0x2000
	v_add_co_u32_e32 v16, vcc, s30, v2
	s_movk_i32 s30, 0x4000
	s_nop 0
	v_addc_co_u32_e32 v17, vcc, 0, v3, vcc
	v_add_co_u32_e32 v32, vcc, s30, v2
	s_movk_i32 s30, 0x6000
	s_nop 0
	v_addc_co_u32_e32 v33, vcc, 0, v3, vcc
	v_add_co_u32_e32 v24, vcc, s78, v2
	global_load_dwordx4 v[8:11], v[2:3], off nt
	s_nop 0
	v_addc_co_u32_e32 v25, vcc, 0, v3, vcc
	v_add_co_u32_e32 v40, vcc, s30, v2
	s_mov_b32 s30, 0xa000
	s_nop 0
	v_addc_co_u32_e32 v41, vcc, 0, v3, vcc
	v_add_co_u32_e32 v48, vcc, s30, v2
	global_load_dwordx4 v[12:15], v[16:17], off offset:-4096 nt
	s_nop 0
	global_load_dwordx4 v[16:19], v[16:17], off nt
	s_nop 0
	global_load_dwordx4 v[20:23], v[24:25], off offset:-4096 nt
	s_nop 0
	global_load_dwordx4 v[24:27], v[24:25], off nt
	s_nop 0
	global_load_dwordx4 v[28:31], v[32:33], off offset:-4096 nt
	s_nop 0
	global_load_dwordx4 v[32:35], v[32:33], off nt
	s_nop 0
	global_load_dwordx4 v[36:39], v[40:41], off offset:-4096 nt
	s_nop 0
	global_load_dwordx4 v[40:43], v[40:41], off nt
	v_addc_co_u32_e32 v49, vcc, 0, v3, vcc
	global_load_dwordx4 v[44:47], v[48:49], off offset:-4096 nt
	s_nop 0
	global_load_dwordx4 v[48:51], v[48:49], off nt
	s_mov_b32 s30, 0xc000
	v_add_co_u32_e32 v56, vcc, s30, v2
	s_mov_b32 s30, 0xe000
	s_nop 0
	v_addc_co_u32_e32 v57, vcc, 0, v3, vcc
	global_load_dwordx4 v[52:55], v[56:57], off offset:-4096 nt
	s_nop 0
	global_load_dwordx4 v[56:59], v[56:57], off nt
	v_add_co_u32_e32 v64, vcc, s30, v2
	s_mov_b32 s30, 0xf000
	s_nop 0
	v_addc_co_u32_e32 v65, vcc, 0, v3, vcc
	global_load_dwordx4 v[60:63], v[64:65], off offset:-4096 nt
	global_load_dwordx4 v[74:77], v[64:65], off nt
	v_add_co_u32_e32 v2, vcc, s30, v2
	v_add_u32_e32 v64, 0x1868, v84
	s_nop 0
	v_addc_co_u32_e32 v3, vcc, 0, v3, vcc
	global_load_dwordx4 v[116:119], v[2:3], off nt
	v_add_u32_e32 v2, 0x1458, v84
	v_add_u32_e32 v3, 0x1860, v84
	v_add_u32_e32 v65, 0x1c70, v84
	v_add_u32_e32 v73, 0x1c78, v84
	v_add_u32_e32 v79, 0x2080, v84
	v_add_u32_e32 v80, 0x2088, v84
	v_add_u32_e32 v115, 0x2490, v84
	s_waitcnt vmcnt(15)
	ds_write2_b32 v84, v8, v9 offset1:1
	ds_write2_b32 v84, v10, v11 offset0:2 offset1:3
	s_waitcnt vmcnt(12)
	ds_write2_b32 v65, v20, v21 offset1:1
	ds_write2_b32 v73, v22, v23 offset1:1
	s_waitcnt vmcnt(11)
	ds_write2_b32 v79, v24, v25 offset1:1
	ds_write2_b32 v80, v26, v27 offset1:1
	ds_write2_b32 v103, v12, v13 offset1:1
	ds_write2_b32 v104, v14, v15 offset1:1
	ds_write2_b32 v105, v16, v17 offset1:1
	ds_write2_b32 v106, v18, v19 offset1:1
	s_waitcnt vmcnt(10)
	ds_write2_b32 v107, v28, v29 offset1:1
	ds_write2_b32 v108, v30, v31 offset1:1
	s_waitcnt vmcnt(9)
	ds_write2_b32 v109, v32, v33 offset1:1
	ds_write2_b32 v110, v34, v35 offset1:1
	s_waitcnt vmcnt(8)
	ds_write2_b32 v111, v36, v37 offset1:1
	ds_write2_b32 v2, v38, v39 offset1:1
	s_waitcnt vmcnt(7)
	ds_write2_b32 v3, v40, v41 offset1:1
	ds_write2_b32 v64, v42, v43 offset1:1
	s_waitcnt vmcnt(6)
	ds_write2_b32 v115, v44, v45 offset1:1
	v_add_u32_e32 v2, 0x2498, v84
	ds_write2_b32 v2, v46, v47 offset1:1
	v_add_u32_e32 v2, 0x28a0, v84
	s_waitcnt vmcnt(5)
	ds_write2_b32 v2, v48, v49 offset1:1
	v_add_u32_e32 v2, 0x28a8, v84
	ds_write2_b32 v2, v50, v51 offset1:1
	v_add_u32_e32 v2, 0x2cb0, v84
	s_waitcnt vmcnt(4)
	ds_write2_b32 v2, v52, v53 offset1:1
	v_add_u32_e32 v2, 0x2cb8, v84
	ds_write2_b32 v2, v54, v55 offset1:1
	v_add_u32_e32 v2, 0x30c0, v84
	s_waitcnt vmcnt(3)
	ds_write2_b32 v2, v56, v57 offset1:1
	v_add_u32_e32 v2, 0x30c8, v84
	ds_write2_b32 v2, v58, v59 offset1:1
	v_add_u32_e32 v2, 0x34d0, v84
	s_waitcnt vmcnt(2)
	ds_write2_b32 v2, v60, v61 offset1:1
	v_add_u32_e32 v2, 0x34d8, v84
	ds_write2_b32 v2, v62, v63 offset1:1
	v_add_u32_e32 v2, 0x38e0, v84
	s_waitcnt vmcnt(1)
	ds_write2_b32 v2, v74, v75 offset1:1
	v_add_u32_e32 v2, 0x38e8, v84
	ds_write2_b32 v2, v76, v77 offset1:1
	v_add_u32_e32 v2, 0x3cf0, v84
	s_waitcnt vmcnt(0)
	ds_write2_b32 v2, v116, v117 offset1:1
	v_add_u32_e32 v2, 0x3cf8, v84
	ds_write2_b32 v2, v118, v119 offset1:1
	s_waitcnt lgkmcnt(0)
	ds_read2_b32 v[12:13], v86 offset1:8
	ds_read2_b32 v[14:15], v86 offset0:65 offset1:73
	ds_read2_b32 v[16:17], v86 offset0:130 offset1:138
	ds_read2_b32 v[18:19], v86 offset0:195 offset1:203
	v_add_u32_e32 v30, 0x400, v86
	s_waitcnt lgkmcnt(3)
	v_bfe_u32 v8, v12, 16, 1
	v_add3_u32 v8, v12, v8, s95
	s_waitcnt lgkmcnt(2)
	v_bfe_u32 v9, v14, 16, 1
	ds_read2_b32 v[20:21], v30 offset0:4 offset1:12
	v_lshrrev_b32_e32 v8, 16, v8
	v_add3_u32 v9, v14, v9, s95
	ds_read2_b32 v[22:23], v30 offset0:69 offset1:77
	v_and_or_b32 v8, v9, s96, v8
	s_waitcnt lgkmcnt(3)
	v_bfe_u32 v9, v16, 16, 1
	v_add3_u32 v9, v16, v9, s95
	s_waitcnt lgkmcnt(2)
	v_bfe_u32 v10, v18, 16, 1
	ds_read2_b32 v[24:25], v30 offset0:134 offset1:142
	v_lshrrev_b32_e32 v9, 16, v9
	v_add3_u32 v10, v18, v10, s95
	ds_read2_b32 v[26:27], v30 offset0:199 offset1:207
	v_and_or_b32 v9, v10, s96, v9
	s_waitcnt lgkmcnt(3)
	v_bfe_u32 v10, v20, 16, 1
	v_add3_u32 v10, v20, v10, s95
	s_waitcnt lgkmcnt(2)
	v_bfe_u32 v11, v22, 16, 1
	v_lshrrev_b32_e32 v10, 16, v10
	v_add3_u32 v11, v22, v11, s95
	v_and_or_b32 v10, v11, s96, v10
	s_waitcnt lgkmcnt(1)
	v_bfe_u32 v11, v24, 16, 1
	v_add3_u32 v11, v24, v11, s95
	s_waitcnt lgkmcnt(0)
	v_bfe_u32 v12, v26, 16, 1
	v_lshrrev_b32_e32 v11, 16, v11
	v_add3_u32 v12, v26, v12, s95
	v_and_or_b32 v11, v12, s96, v11
	v_lshlrev_b32_e32 v12, 11, v78
	v_or3_b32 v31, v12, v68, v100
	v_lshlrev_b64 v[2:3], 21, v[4:5]
	v_or_b32_e32 v12, v31, v95
	v_lshl_add_u64 v[2:3], s[52:53], 0, v[2:3]
	v_lshlrev_b32_e32 v68, 4, v12
	v_lshl_add_u64 v[28:29], v[2:3], 0, v[68:69]
	global_store_dwordx4 v[28:29], v[8:11], off
	v_bfe_u32 v12, v27, 16, 1
	v_or_b32_e32 v14, v31, v96
	v_bfe_u32 v8, v13, 16, 1
	v_add3_u32 v8, v13, v8, s95
	v_bfe_u32 v9, v15, 16, 1
	v_lshrrev_b32_e32 v8, 16, v8
	v_add3_u32 v9, v15, v9, s95
	v_and_or_b32 v8, v9, s96, v8
	v_bfe_u32 v9, v17, 16, 1
	v_add3_u32 v9, v17, v9, s95
	v_bfe_u32 v10, v19, 16, 1
	v_lshrrev_b32_e32 v9, 16, v9
	v_add3_u32 v10, v19, v10, s95
	v_and_or_b32 v9, v10, s96, v9
	v_bfe_u32 v10, v21, 16, 1
	v_add3_u32 v10, v21, v10, s95
	v_bfe_u32 v11, v23, 16, 1
	v_lshrrev_b32_e32 v10, 16, v10
	v_add3_u32 v11, v23, v11, s95
	v_and_or_b32 v10, v11, s96, v10
	v_bfe_u32 v11, v25, 16, 1
	v_add3_u32 v11, v25, v11, s95
	v_lshrrev_b32_e32 v11, 16, v11
	v_add3_u32 v12, v27, v12, s95
	v_lshlrev_b32_e32 v68, 4, v14
	v_and_or_b32 v11, v12, s96, v11
	ds_read2_b32 v[12:13], v86 offset0:16 offset1:24
	v_lshl_add_u64 v[14:15], v[2:3], 0, v[68:69]
	global_store_dwordx4 v[14:15], v[8:11], off
	ds_read2_b32 v[14:15], v86 offset0:81 offset1:89
	ds_read2_b32 v[16:17], v86 offset0:146 offset1:154
	ds_read2_b32 v[18:19], v86 offset0:211 offset1:219
	s_waitcnt lgkmcnt(3)
	v_bfe_u32 v8, v12, 16, 1
	v_add3_u32 v8, v12, v8, s95
	s_waitcnt lgkmcnt(2)
	v_bfe_u32 v9, v14, 16, 1
	ds_read2_b32 v[20:21], v30 offset0:20 offset1:28
	v_lshrrev_b32_e32 v8, 16, v8
	v_add3_u32 v9, v14, v9, s95
	ds_read2_b32 v[22:23], v30 offset0:85 offset1:93
	v_and_or_b32 v8, v9, s96, v8
	s_waitcnt lgkmcnt(3)
	v_bfe_u32 v9, v16, 16, 1
	v_add3_u32 v9, v16, v9, s95
	s_waitcnt lgkmcnt(2)
	v_bfe_u32 v10, v18, 16, 1
	ds_read2_b32 v[24:25], v30 offset0:150 offset1:158
	v_lshrrev_b32_e32 v9, 16, v9
	v_add3_u32 v10, v18, v10, s95
	ds_read2_b32 v[26:27], v30 offset0:215 offset1:223
	v_and_or_b32 v9, v10, s96, v9
	s_waitcnt lgkmcnt(3)
	v_bfe_u32 v10, v20, 16, 1
	v_add3_u32 v10, v20, v10, s95
	s_waitcnt lgkmcnt(2)
	v_bfe_u32 v11, v22, 16, 1
	v_lshrrev_b32_e32 v10, 16, v10
	v_add3_u32 v11, v22, v11, s95
	v_and_or_b32 v10, v11, s96, v10
	s_waitcnt lgkmcnt(1)
	v_bfe_u32 v11, v24, 16, 1
	v_add3_u32 v11, v24, v11, s95
	s_waitcnt lgkmcnt(0)
	v_bfe_u32 v12, v26, 16, 1
	v_or_b32_e32 v14, 64, v31
	v_lshrrev_b32_e32 v11, 16, v11
	v_add3_u32 v12, v26, v12, s95
	v_or_b32_e32 v68, v14, v95
	v_and_or_b32 v11, v12, s96, v11
	v_lshl_add_u64 v[28:29], v[68:69], 4, v[2:3]
	global_store_dwordx4 v[28:29], v[8:11], off
	v_bfe_u32 v12, v27, 16, 1
	v_add3_u32 v12, v27, v12, s95
	v_bfe_u32 v8, v13, 16, 1
	v_add3_u32 v8, v13, v8, s95
	v_bfe_u32 v9, v15, 16, 1
	v_lshrrev_b32_e32 v8, 16, v8
	v_add3_u32 v9, v15, v9, s95
	v_and_or_b32 v8, v9, s96, v8
	v_bfe_u32 v9, v17, 16, 1
	v_add3_u32 v9, v17, v9, s95
	v_bfe_u32 v10, v19, 16, 1
	v_lshrrev_b32_e32 v9, 16, v9
	v_add3_u32 v10, v19, v10, s95
	v_and_or_b32 v9, v10, s96, v9
	v_bfe_u32 v10, v21, 16, 1
	v_add3_u32 v10, v21, v10, s95
	v_bfe_u32 v11, v23, 16, 1
	v_lshrrev_b32_e32 v10, 16, v10
	v_add3_u32 v11, v23, v11, s95
	v_and_or_b32 v10, v11, s96, v10
	v_bfe_u32 v11, v25, 16, 1
	v_add3_u32 v11, v25, v11, s95
	v_lshrrev_b32_e32 v11, 16, v11
	v_or_b32_e32 v68, v14, v97
	v_and_or_b32 v11, v12, s96, v11
	ds_read2_b32 v[12:13], v86 offset0:32 offset1:40
	v_lshl_add_u64 v[14:15], v[68:69], 4, v[2:3]
	global_store_dwordx4 v[14:15], v[8:11], off
	ds_read2_b32 v[14:15], v86 offset0:97 offset1:105
	ds_read2_b32 v[16:17], v86 offset0:162 offset1:170
	ds_read2_b32 v[18:19], v86 offset0:227 offset1:235
	s_waitcnt lgkmcnt(3)
	v_bfe_u32 v8, v12, 16, 1
	v_add3_u32 v8, v12, v8, s95
	s_waitcnt lgkmcnt(2)
	v_bfe_u32 v9, v14, 16, 1
	ds_read2_b32 v[20:21], v30 offset0:36 offset1:44
	v_lshrrev_b32_e32 v8, 16, v8
	v_add3_u32 v9, v14, v9, s95
	ds_read2_b32 v[22:23], v30 offset0:101 offset1:109
	v_and_or_b32 v8, v9, s96, v8
	s_waitcnt lgkmcnt(3)
	v_bfe_u32 v9, v16, 16, 1
	v_add3_u32 v9, v16, v9, s95
	s_waitcnt lgkmcnt(2)
	v_bfe_u32 v10, v18, 16, 1
	ds_read2_b32 v[24:25], v30 offset0:166 offset1:174
	v_lshrrev_b32_e32 v9, 16, v9
	v_add3_u32 v10, v18, v10, s95
	ds_read2_b32 v[26:27], v30 offset0:231 offset1:239
	v_and_or_b32 v9, v10, s96, v9
	s_waitcnt lgkmcnt(3)
	v_bfe_u32 v10, v20, 16, 1
	v_add3_u32 v10, v20, v10, s95
	s_waitcnt lgkmcnt(2)
	v_bfe_u32 v11, v22, 16, 1
	v_lshrrev_b32_e32 v10, 16, v10
	v_add3_u32 v11, v22, v11, s95
	v_and_or_b32 v10, v11, s96, v10
	s_waitcnt lgkmcnt(1)
	v_bfe_u32 v11, v24, 16, 1
	v_add3_u32 v11, v24, v11, s95
	s_waitcnt lgkmcnt(0)
	v_bfe_u32 v12, v26, 16, 1
	v_or_b32_e32 v14, 0x80, v31
	v_lshrrev_b32_e32 v11, 16, v11
	v_add3_u32 v12, v26, v12, s95
	v_or_b32_e32 v68, v14, v95
	v_and_or_b32 v11, v12, s96, v11
	v_lshl_add_u64 v[28:29], v[68:69], 4, v[2:3]
	global_store_dwordx4 v[28:29], v[8:11], off
	v_bfe_u32 v12, v27, 16, 1
	v_add3_u32 v12, v27, v12, s95
	v_bfe_u32 v8, v13, 16, 1
	v_add3_u32 v8, v13, v8, s95
	v_bfe_u32 v9, v15, 16, 1
	v_lshrrev_b32_e32 v8, 16, v8
	v_add3_u32 v9, v15, v9, s95
	v_and_or_b32 v8, v9, s96, v8
	v_bfe_u32 v9, v17, 16, 1
	v_add3_u32 v9, v17, v9, s95
	v_bfe_u32 v10, v19, 16, 1
	v_lshrrev_b32_e32 v9, 16, v9
	v_add3_u32 v10, v19, v10, s95
	v_and_or_b32 v9, v10, s96, v9
	v_bfe_u32 v10, v21, 16, 1
	v_add3_u32 v10, v21, v10, s95
	v_bfe_u32 v11, v23, 16, 1
	v_lshrrev_b32_e32 v10, 16, v10
	v_add3_u32 v11, v23, v11, s95
	v_and_or_b32 v10, v11, s96, v10
	v_bfe_u32 v11, v25, 16, 1
	v_add3_u32 v11, v25, v11, s95
	v_lshrrev_b32_e32 v11, 16, v11
	v_or_b32_e32 v68, v14, v98
	v_and_or_b32 v11, v12, s96, v11
	ds_read2_b32 v[12:13], v86 offset0:48 offset1:56
	v_lshl_add_u64 v[14:15], v[68:69], 4, v[2:3]
	global_store_dwordx4 v[14:15], v[8:11], off
	ds_read2_b32 v[14:15], v86 offset0:113 offset1:121
	ds_read2_b32 v[16:17], v86 offset0:178 offset1:186
	ds_read2_b32 v[18:19], v86 offset0:243 offset1:251
	s_waitcnt lgkmcnt(3)
	v_bfe_u32 v8, v12, 16, 1
	v_add3_u32 v8, v12, v8, s95
	s_waitcnt lgkmcnt(2)
	v_bfe_u32 v9, v14, 16, 1
	ds_read2_b32 v[20:21], v30 offset0:52 offset1:60
	v_lshrrev_b32_e32 v8, 16, v8
	v_add3_u32 v9, v14, v9, s95
	ds_read2_b32 v[22:23], v30 offset0:117 offset1:125
	v_and_or_b32 v8, v9, s96, v8
	s_waitcnt lgkmcnt(3)
	v_bfe_u32 v9, v16, 16, 1
	v_add3_u32 v9, v16, v9, s95
	s_waitcnt lgkmcnt(2)
	v_bfe_u32 v10, v18, 16, 1
	ds_read2_b32 v[24:25], v30 offset0:182 offset1:190
	v_lshrrev_b32_e32 v9, 16, v9
	v_add3_u32 v10, v18, v10, s95
	ds_read2_b32 v[26:27], v30 offset0:247 offset1:255
	v_and_or_b32 v9, v10, s96, v9
	s_waitcnt lgkmcnt(3)
	v_bfe_u32 v10, v20, 16, 1
	v_add3_u32 v10, v20, v10, s95
	s_waitcnt lgkmcnt(2)
	v_bfe_u32 v11, v22, 16, 1
	v_lshrrev_b32_e32 v10, 16, v10
	v_add3_u32 v11, v22, v11, s95
	v_and_or_b32 v10, v11, s96, v10
	s_waitcnt lgkmcnt(1)
	v_bfe_u32 v11, v24, 16, 1
	v_add3_u32 v11, v24, v11, s95
	s_waitcnt lgkmcnt(0)
	v_bfe_u32 v12, v26, 16, 1
	v_lshrrev_b32_e32 v11, 16, v11
	v_add3_u32 v12, v26, v12, s95
	v_and_or_b32 v11, v12, s96, v11
	v_or_b32_e32 v12, 0xc0, v31
	v_or_b32_e32 v68, v12, v95
	v_lshl_add_u64 v[28:29], v[68:69], 4, v[2:3]
	global_store_dwordx4 v[28:29], v[8:11], off
	v_or_b32_e32 v68, v12, v99
	v_lshl_add_u64 v[2:3], v[68:69], 4, v[2:3]
	v_bfe_u32 v8, v13, 16, 1
	v_add3_u32 v8, v13, v8, s95
	v_bfe_u32 v9, v15, 16, 1
	v_lshrrev_b32_e32 v8, 16, v8
	v_add3_u32 v9, v15, v9, s95
	v_and_or_b32 v8, v9, s96, v8
	v_bfe_u32 v9, v17, 16, 1
	v_add3_u32 v9, v17, v9, s95
	v_bfe_u32 v10, v19, 16, 1
	v_lshrrev_b32_e32 v9, 16, v9
	v_add3_u32 v10, v19, v10, s95
	v_and_or_b32 v9, v10, s96, v9
	v_bfe_u32 v10, v21, 16, 1
	v_add3_u32 v10, v21, v10, s95
	v_bfe_u32 v11, v23, 16, 1
	v_lshrrev_b32_e32 v10, 16, v10
	v_add3_u32 v11, v23, v11, s95
	v_and_or_b32 v10, v11, s96, v10
	v_bfe_u32 v11, v25, 16, 1
	v_add3_u32 v11, v25, v11, s95
	v_bfe_u32 v13, v27, 16, 1
	v_lshrrev_b32_e32 v11, 16, v11
	v_add3_u32 v13, v27, v13, s95
	v_and_or_b32 v11, v13, s96, v11
	global_store_dwordx4 v[2:3], v[8:11], off
	s_waitcnt lgkmcnt(0)
.LBB0_91:
	s_andn2_saveexec_b64 s[4:5], s[4:5]
	v_add_u32_e32 v81, 0xffffff00, v81
	s_or_b64 exec, exec, s[4:5]
	v_cmp_gt_u32_e32 vcc, 8, v81
	s_and_b64 s[2:3], s[2:3], vcc
	s_and_b64 exec, exec, s[2:3]
	s_cbranch_execz .LBB0_95
	v_lshl_add_u64 v[2:3], v[6:7], 2, s[36:37]
	v_lshlrev_b32_e32 v7, 5, v81
	v_and_b32_e32 v7, 0xc0, v7
	v_lshlrev_b32_e32 v6, 6, v81
	v_or_b32_e32 v8, v7, v83
	v_and_b32_e32 v6, 64, v6
	v_lshlrev_b32_e32 v68, 9, v8
	v_lshl_add_u64 v[2:3], v[2:3], 0, v[68:69]
	v_lshlrev_b32_e32 v68, 2, v6
	v_lshl_add_u64 v[2:3], v[2:3], 0, v[68:69]
	v_mov_b32_e32 v73, v69
	v_lshl_add_u64 v[2:3], v[2:3], 0, v[72:73]
	s_movk_i32 s2, 0x1000
	v_add_co_u32_e32 v20, vcc, s2, v2
	s_movk_i32 s2, 0x2000
	s_nop 0
	v_addc_co_u32_e32 v21, vcc, 0, v3, vcc
	v_add_co_u32_e32 v28, vcc, s2, v2
	s_movk_i32 s2, 0x3000
	s_nop 0
	v_addc_co_u32_e32 v29, vcc, 0, v3, vcc
	v_add_co_u32_e32 v32, vcc, s2, v2
	s_movk_i32 s2, 0x4000
	s_nop 0
	v_addc_co_u32_e32 v33, vcc, 0, v3, vcc
	v_add_co_u32_e32 v44, vcc, s2, v2
	s_movk_i32 s2, 0x6000
	s_nop 0
	v_addc_co_u32_e32 v45, vcc, 0, v3, vcc
	v_add_co_u32_e32 v60, vcc, s2, v2
	global_load_dwordx4 v[8:11], v[2:3], off nt
	global_load_dwordx4 v[12:15], v[2:3], off offset:2048 nt
	global_load_dwordx4 v[16:19], v[28:29], off offset:-4096 nt
	s_nop 0
	global_load_dwordx4 v[20:23], v[20:21], off offset:2048 nt
	s_nop 0
	global_load_dwordx4 v[24:27], v[28:29], off nt
	s_nop 0
	global_load_dwordx4 v[28:31], v[28:29], off offset:2048 nt
	s_nop 0
	global_load_dwordx4 v[32:35], v[32:33], off offset:2048 nt
	s_nop 0
	global_load_dwordx4 v[36:39], v[44:45], off offset:-4096 nt
	global_load_dwordx4 v[40:43], v[44:45], off nt
	v_addc_co_u32_e32 v61, vcc, 0, v3, vcc
	global_load_dwordx4 v[44:47], v[44:45], off offset:2048 nt
	s_nop 0
	global_load_dwordx4 v[48:51], v[60:61], off offset:-4096 nt
	s_movk_i32 s2, 0x5000
	v_add_co_u32_e32 v52, vcc, s2, v2
	s_movk_i32 s2, 0x7000
	s_nop 0
	v_addc_co_u32_e32 v53, vcc, 0, v3, vcc
	global_load_dwordx4 v[52:55], v[52:53], off offset:2048 nt
	s_nop 0
	global_load_dwordx4 v[56:59], v[60:61], off nt
	s_nop 0
	global_load_dwordx4 v[60:63], v[60:61], off offset:2048 nt
	v_add_co_u32_e32 v2, vcc, s2, v2
	v_add_u32_e32 v64, 0x1868, v84
	s_nop 0
	v_addc_co_u32_e32 v3, vcc, 0, v3, vcc
	global_load_dwordx4 v[74:77], v[2:3], off nt
	global_load_dwordx4 v[78:81], v[2:3], off offset:2048 nt
	v_lshlrev_b64 v[2:3], 16, v[4:5]
	v_add_u32_e32 v4, 0x1458, v84
	v_add_u32_e32 v5, 0x1860, v84
	v_add_u32_e32 v65, 0x1c70, v84
	v_add_u32_e32 v68, 0x1c78, v84
	v_add_u32_e32 v73, 0x2080, v84
	v_add_u32_e32 v115, 0x2088, v84
	v_add_u32_e32 v116, 0x2490, v84
	v_add_u32_e32 v117, 0x2498, v84
	v_add_u32_e32 v118, 0x28a0, v84
	v_lshl_add_u64 v[2:3], s[0:1], 0, v[2:3]
	s_waitcnt vmcnt(15)
	ds_write2_b32 v84, v8, v9 offset1:1
	ds_write2_b32 v84, v10, v11 offset0:2 offset1:3
	s_waitcnt vmcnt(14)
	ds_write2_b32 v103, v12, v13 offset1:1
	ds_write2_b32 v104, v14, v15 offset1:1
	s_waitcnt vmcnt(13)
	ds_write2_b32 v105, v16, v17 offset1:1
	ds_write2_b32 v106, v18, v19 offset1:1
	s_waitcnt vmcnt(12)
	ds_write2_b32 v107, v20, v21 offset1:1
	ds_write2_b32 v108, v22, v23 offset1:1
	s_waitcnt vmcnt(11)
	ds_write2_b32 v109, v24, v25 offset1:1
	ds_write2_b32 v110, v26, v27 offset1:1
	s_waitcnt vmcnt(10)
	ds_write2_b32 v111, v28, v29 offset1:1
	ds_write2_b32 v4, v30, v31 offset1:1
	s_waitcnt vmcnt(8)
	ds_write2_b32 v5, v36, v37 offset1:1
	ds_write2_b32 v64, v38, v39 offset1:1
	ds_write2_b32 v65, v32, v33 offset1:1
	ds_write2_b32 v68, v34, v35 offset1:1
	s_waitcnt vmcnt(7)
	ds_write2_b32 v73, v40, v41 offset1:1
	ds_write2_b32 v115, v42, v43 offset1:1
	s_waitcnt vmcnt(6)
	ds_write2_b32 v116, v44, v45 offset1:1
	ds_write2_b32 v117, v46, v47 offset1:1
	s_waitcnt vmcnt(5)
	ds_write2_b32 v118, v48, v49 offset1:1
	v_add_u32_e32 v4, 0x28a8, v84
	ds_write2_b32 v4, v50, v51 offset1:1
	v_add_u32_e32 v4, 0x2cb0, v84
	v_lshlrev_b32_e32 v68, 1, v7
	s_waitcnt vmcnt(4)
	ds_write2_b32 v4, v52, v53 offset1:1
	v_add_u32_e32 v4, 0x2cb8, v84
	ds_write2_b32 v4, v54, v55 offset1:1
	v_add_u32_e32 v4, 0x30c0, v84
	s_waitcnt vmcnt(3)
	ds_write2_b32 v4, v56, v57 offset1:1
	v_add_u32_e32 v4, 0x30c8, v84
	ds_write2_b32 v4, v58, v59 offset1:1
	v_add_u32_e32 v4, 0x34d0, v84
	s_waitcnt vmcnt(2)
	ds_write2_b32 v4, v60, v61 offset1:1
	v_add_u32_e32 v4, 0x34d8, v84
	ds_write2_b32 v4, v62, v63 offset1:1
	v_add_u32_e32 v4, 0x38e0, v84
	s_waitcnt vmcnt(1)
	ds_write2_b32 v4, v74, v75 offset1:1
	v_add_u32_e32 v4, 0x38e8, v84
	ds_write2_b32 v4, v76, v77 offset1:1
	v_add_u32_e32 v4, 0x3cf0, v84
	s_waitcnt vmcnt(0)
	ds_write2_b32 v4, v78, v79 offset1:1
	v_add_u32_e32 v4, 0x3cf8, v84
	ds_write2_b32 v4, v80, v81 offset1:1
	s_waitcnt lgkmcnt(0)
	v_add_u32_e32 v7, 0x400, v86
	ds_read2_b32 v[4:5], v7 offset0:199 offset1:207
	ds_read2_b32 v[12:13], v7 offset0:134 offset1:142
	ds_read2_b32 v[16:17], v7 offset0:4 offset1:12
	ds_read2_b32 v[14:15], v7 offset0:69 offset1:77
	ds_read2_b32 v[20:21], v86 offset0:130 offset1:138
	s_waitcnt lgkmcnt(4)
	v_bfe_u32 v8, v4, 16, 1
	v_add3_u32 v4, v4, v8, s95
	s_waitcnt lgkmcnt(3)
	v_bfe_u32 v8, v12, 16, 1
	v_add3_u32 v8, v12, v8, s95
	v_lshrrev_b32_e32 v8, 16, v8
	ds_read2_b32 v[18:19], v86 offset0:195 offset1:203
	v_and_or_b32 v11, v4, s96, v8
	s_waitcnt lgkmcnt(3)
	v_bfe_u32 v8, v16, 16, 1
	s_waitcnt lgkmcnt(2)
	v_bfe_u32 v4, v14, 16, 1
	v_add3_u32 v8, v16, v8, s95
	ds_read2_b32 v[24:25], v86 offset1:8
	v_add3_u32 v4, v14, v4, s95
	v_lshrrev_b32_e32 v8, 16, v8
	ds_read2_b32 v[22:23], v86 offset0:65 offset1:73
	v_and_or_b32 v10, v4, s96, v8
	s_waitcnt lgkmcnt(3)
	v_bfe_u32 v8, v20, 16, 1
	s_waitcnt lgkmcnt(2)
	v_bfe_u32 v4, v18, 16, 1
	v_add3_u32 v8, v20, v8, s95
	v_add3_u32 v4, v18, v4, s95
	v_lshrrev_b32_e32 v8, 16, v8
	v_and_or_b32 v9, v4, s96, v8
	s_waitcnt lgkmcnt(1)
	v_bfe_u32 v8, v24, 16, 1
	s_waitcnt lgkmcnt(0)
	v_bfe_u32 v4, v22, 16, 1
	v_add3_u32 v8, v24, v8, s95
	v_add3_u32 v4, v22, v4, s95
	v_lshrrev_b32_e32 v8, 16, v8
	v_lshl_add_u64 v[2:3], v[2:3], 0, v[68:69]
	v_lshlrev_b32_e32 v68, 1, v70
	v_and_or_b32 v8, v4, s96, v8
	v_or_b32_e32 v4, v6, v85
	v_lshl_add_u64 v[2:3], v[2:3], 0, v[68:69]
	v_lshlrev_b32_e32 v68, 9, v4
	v_bfe_u32 v4, v5, 16, 1
	v_add3_u32 v4, v5, v4, s95
	v_bfe_u32 v5, v13, 16, 1
	v_add3_u32 v5, v13, v5, s95
	v_lshl_add_u64 v[26:27], v[2:3], 0, v[68:69]
	v_lshrrev_b32_e32 v5, 16, v5
	global_store_dwordx4 v[26:27], v[8:11], off
	v_or_b32_e32 v12, v6, v87
	v_lshlrev_b32_e32 v68, 9, v12
	v_and_or_b32 v11, v4, s96, v5
	v_bfe_u32 v5, v17, 16, 1
	v_bfe_u32 v4, v15, 16, 1
	v_add3_u32 v5, v17, v5, s95
	v_add3_u32 v4, v15, v4, s95
	v_lshrrev_b32_e32 v5, 16, v5
	v_and_or_b32 v10, v4, s96, v5
	v_bfe_u32 v5, v21, 16, 1
	v_bfe_u32 v4, v19, 16, 1
	v_add3_u32 v5, v21, v5, s95
	v_add3_u32 v4, v19, v4, s95
	v_lshrrev_b32_e32 v5, 16, v5
	v_and_or_b32 v9, v4, s96, v5
	v_bfe_u32 v5, v25, 16, 1
	v_bfe_u32 v4, v23, 16, 1
	v_add3_u32 v5, v25, v5, s95
	v_add3_u32 v4, v23, v4, s95
	v_lshrrev_b32_e32 v5, 16, v5
	v_and_or_b32 v8, v4, s96, v5
	ds_read2_b32 v[4:5], v7 offset0:215 offset1:223
	ds_read2_b32 v[12:13], v7 offset0:150 offset1:158
	v_lshl_add_u64 v[14:15], v[2:3], 0, v[68:69]
	ds_read2_b32 v[16:17], v7 offset0:20 offset1:28
	global_store_dwordx4 v[14:15], v[8:11], off
	ds_read2_b32 v[14:15], v7 offset0:85 offset1:93
	ds_read2_b32 v[20:21], v86 offset0:146 offset1:154
	s_waitcnt lgkmcnt(4)
	v_bfe_u32 v8, v4, 16, 1
	v_add3_u32 v4, v4, v8, s95
	s_waitcnt lgkmcnt(3)
	v_bfe_u32 v8, v12, 16, 1
	v_add3_u32 v8, v12, v8, s95
	v_lshrrev_b32_e32 v8, 16, v8
	ds_read2_b32 v[18:19], v86 offset0:211 offset1:219
	v_and_or_b32 v11, v4, s96, v8
	s_waitcnt lgkmcnt(3)
	v_bfe_u32 v8, v16, 16, 1
	s_waitcnt lgkmcnt(2)
	v_bfe_u32 v4, v14, 16, 1
	v_add3_u32 v8, v16, v8, s95
	ds_read2_b32 v[24:25], v86 offset0:16 offset1:24
	v_add3_u32 v4, v14, v4, s95
	v_lshrrev_b32_e32 v8, 16, v8
	ds_read2_b32 v[22:23], v86 offset0:81 offset1:89
	v_and_or_b32 v10, v4, s96, v8
	s_waitcnt lgkmcnt(3)
	v_bfe_u32 v8, v20, 16, 1
	s_waitcnt lgkmcnt(2)
	v_bfe_u32 v4, v18, 16, 1
	v_add3_u32 v8, v20, v8, s95
	v_add3_u32 v4, v18, v4, s95
	v_lshrrev_b32_e32 v8, 16, v8
	v_and_or_b32 v9, v4, s96, v8
	s_waitcnt lgkmcnt(1)
	v_bfe_u32 v8, v24, 16, 1
	s_waitcnt lgkmcnt(0)
	v_bfe_u32 v4, v22, 16, 1
	v_add3_u32 v8, v24, v8, s95
	v_add3_u32 v4, v22, v4, s95
	v_lshrrev_b32_e32 v8, 16, v8
	v_and_or_b32 v8, v4, s96, v8
	v_or_b32_e32 v4, v6, v88
	v_lshlrev_b32_e32 v68, 9, v4
	v_bfe_u32 v4, v5, 16, 1
	v_add3_u32 v4, v5, v4, s95
	v_bfe_u32 v5, v13, 16, 1
	v_add3_u32 v5, v13, v5, s95
	v_lshl_add_u64 v[26:27], v[2:3], 0, v[68:69]
	v_lshrrev_b32_e32 v5, 16, v5
	global_store_dwordx4 v[26:27], v[8:11], off
	v_or_b32_e32 v12, v6, v89
	v_lshlrev_b32_e32 v68, 9, v12
	v_and_or_b32 v11, v4, s96, v5
	v_bfe_u32 v5, v17, 16, 1
	v_bfe_u32 v4, v15, 16, 1
	v_add3_u32 v5, v17, v5, s95
	v_add3_u32 v4, v15, v4, s95
	v_lshrrev_b32_e32 v5, 16, v5
	v_and_or_b32 v10, v4, s96, v5
	v_bfe_u32 v5, v21, 16, 1
	v_bfe_u32 v4, v19, 16, 1
	v_add3_u32 v5, v21, v5, s95
	v_add3_u32 v4, v19, v4, s95
	v_lshrrev_b32_e32 v5, 16, v5
	v_and_or_b32 v9, v4, s96, v5
	v_bfe_u32 v5, v25, 16, 1
	v_bfe_u32 v4, v23, 16, 1
	v_add3_u32 v5, v25, v5, s95
	v_add3_u32 v4, v23, v4, s95
	v_lshrrev_b32_e32 v5, 16, v5
	v_and_or_b32 v8, v4, s96, v5
	ds_read2_b32 v[4:5], v7 offset0:231 offset1:239
	ds_read2_b32 v[12:13], v7 offset0:166 offset1:174
	v_lshl_add_u64 v[14:15], v[2:3], 0, v[68:69]
	ds_read2_b32 v[16:17], v7 offset0:36 offset1:44
	global_store_dwordx4 v[14:15], v[8:11], off
	ds_read2_b32 v[14:15], v7 offset0:101 offset1:109
	ds_read2_b32 v[20:21], v86 offset0:162 offset1:170
	s_waitcnt lgkmcnt(4)
	v_bfe_u32 v8, v4, 16, 1
	v_add3_u32 v4, v4, v8, s95
	s_waitcnt lgkmcnt(3)
	v_bfe_u32 v8, v12, 16, 1
	v_add3_u32 v8, v12, v8, s95
	v_lshrrev_b32_e32 v8, 16, v8
	ds_read2_b32 v[18:19], v86 offset0:227 offset1:235
	v_and_or_b32 v11, v4, s96, v8
	s_waitcnt lgkmcnt(3)
	v_bfe_u32 v8, v16, 16, 1
	s_waitcnt lgkmcnt(2)
	v_bfe_u32 v4, v14, 16, 1
	v_add3_u32 v8, v16, v8, s95
	ds_read2_b32 v[24:25], v86 offset0:32 offset1:40
	v_add3_u32 v4, v14, v4, s95
	v_lshrrev_b32_e32 v8, 16, v8
	ds_read2_b32 v[22:23], v86 offset0:97 offset1:105
	v_and_or_b32 v10, v4, s96, v8
	s_waitcnt lgkmcnt(3)
	v_bfe_u32 v8, v20, 16, 1
	s_waitcnt lgkmcnt(2)
	v_bfe_u32 v4, v18, 16, 1
	v_add3_u32 v8, v20, v8, s95
	v_add3_u32 v4, v18, v4, s95
	v_lshrrev_b32_e32 v8, 16, v8
	v_and_or_b32 v9, v4, s96, v8
	s_waitcnt lgkmcnt(1)
	v_bfe_u32 v8, v24, 16, 1
	s_waitcnt lgkmcnt(0)
	v_bfe_u32 v4, v22, 16, 1
	v_add3_u32 v8, v24, v8, s95
	v_add3_u32 v4, v22, v4, s95
	v_lshrrev_b32_e32 v8, 16, v8
	v_and_or_b32 v8, v4, s96, v8
	v_or_b32_e32 v4, v6, v90
	v_lshlrev_b32_e32 v68, 9, v4
	v_bfe_u32 v4, v5, 16, 1
	v_add3_u32 v4, v5, v4, s95
	v_bfe_u32 v5, v13, 16, 1
	v_add3_u32 v5, v13, v5, s95
	v_lshl_add_u64 v[26:27], v[2:3], 0, v[68:69]
	v_lshrrev_b32_e32 v5, 16, v5
	global_store_dwordx4 v[26:27], v[8:11], off
	v_or_b32_e32 v12, v6, v91
	v_lshlrev_b32_e32 v68, 9, v12
	v_and_or_b32 v11, v4, s96, v5
	v_bfe_u32 v5, v17, 16, 1
	v_bfe_u32 v4, v15, 16, 1
	v_add3_u32 v5, v17, v5, s95
	v_add3_u32 v4, v15, v4, s95
	v_lshrrev_b32_e32 v5, 16, v5
	v_and_or_b32 v10, v4, s96, v5
	v_bfe_u32 v5, v21, 16, 1
	v_bfe_u32 v4, v19, 16, 1
	v_add3_u32 v5, v21, v5, s95
	v_add3_u32 v4, v19, v4, s95
	v_lshrrev_b32_e32 v5, 16, v5
	v_and_or_b32 v9, v4, s96, v5
	v_bfe_u32 v5, v25, 16, 1
	v_bfe_u32 v4, v23, 16, 1
	v_add3_u32 v5, v25, v5, s95
	v_add3_u32 v4, v23, v4, s95
	v_lshrrev_b32_e32 v5, 16, v5
	v_and_or_b32 v8, v4, s96, v5
	ds_read2_b32 v[4:5], v7 offset0:247 offset1:255
	ds_read2_b32 v[12:13], v7 offset0:182 offset1:190
	v_lshl_add_u64 v[14:15], v[2:3], 0, v[68:69]
	ds_read2_b32 v[16:17], v7 offset0:52 offset1:60
	global_store_dwordx4 v[14:15], v[8:11], off
	ds_read2_b32 v[14:15], v7 offset0:117 offset1:125
	ds_read2_b32 v[20:21], v86 offset0:178 offset1:186
	s_waitcnt lgkmcnt(4)
	v_bfe_u32 v8, v4, 16, 1
	v_add3_u32 v4, v4, v8, s95
	s_waitcnt lgkmcnt(3)
	v_bfe_u32 v8, v12, 16, 1
	v_add3_u32 v8, v12, v8, s95
	v_lshrrev_b32_e32 v7, 16, v8
	ds_read2_b32 v[18:19], v86 offset0:243 offset1:251
	v_and_or_b32 v11, v4, s96, v7
	s_waitcnt lgkmcnt(3)
	v_bfe_u32 v7, v16, 16, 1
	s_waitcnt lgkmcnt(2)
	v_bfe_u32 v4, v14, 16, 1
	v_add3_u32 v7, v16, v7, s95
	ds_read2_b32 v[24:25], v86 offset0:48 offset1:56
	v_add3_u32 v4, v14, v4, s95
	v_lshrrev_b32_e32 v7, 16, v7
	ds_read2_b32 v[22:23], v86 offset0:113 offset1:121
	v_and_or_b32 v10, v4, s96, v7
	s_waitcnt lgkmcnt(3)
	v_bfe_u32 v7, v20, 16, 1
	s_waitcnt lgkmcnt(2)
	v_bfe_u32 v4, v18, 16, 1
	v_add3_u32 v7, v20, v7, s95
	v_add3_u32 v4, v18, v4, s95
	v_lshrrev_b32_e32 v7, 16, v7
	v_and_or_b32 v9, v4, s96, v7
	s_waitcnt lgkmcnt(1)
	v_bfe_u32 v7, v24, 16, 1
	s_waitcnt lgkmcnt(0)
	v_bfe_u32 v4, v22, 16, 1
	v_add3_u32 v7, v24, v7, s95
	v_add3_u32 v4, v22, v4, s95
	v_lshrrev_b32_e32 v7, 16, v7
	v_and_or_b32 v8, v4, s96, v7
	v_or_b32_e32 v4, v6, v92
	v_lshlrev_b32_e32 v68, 9, v4
	v_bfe_u32 v4, v5, 16, 1
	v_add3_u32 v4, v5, v4, s95
	v_bfe_u32 v5, v13, 16, 1
	v_add3_u32 v5, v13, v5, s95
	v_lshl_add_u64 v[26:27], v[2:3], 0, v[68:69]
	v_lshrrev_b32_e32 v5, 16, v5
	global_store_dwordx4 v[26:27], v[8:11], off
	s_nop 1
	v_and_or_b32 v11, v4, s96, v5
	v_bfe_u32 v5, v17, 16, 1
	v_bfe_u32 v4, v15, 16, 1
	v_add3_u32 v5, v17, v5, s95
	v_add3_u32 v4, v15, v4, s95
	v_lshrrev_b32_e32 v5, 16, v5
	v_and_or_b32 v10, v4, s96, v5
	v_bfe_u32 v5, v21, 16, 1
	v_bfe_u32 v4, v19, 16, 1
	v_add3_u32 v5, v21, v5, s95
	v_add3_u32 v4, v19, v4, s95
	v_lshrrev_b32_e32 v5, 16, v5
	v_and_or_b32 v9, v4, s96, v5
	v_bfe_u32 v5, v25, 16, 1
	v_bfe_u32 v4, v23, 16, 1
	v_add3_u32 v5, v25, v5, s95
	v_add3_u32 v4, v23, v4, s95
	v_lshrrev_b32_e32 v5, 16, v5
	v_and_or_b32 v8, v4, s96, v5
	v_or_b32_e32 v4, v6, v93
	v_lshlrev_b32_e32 v68, 9, v4
	v_lshl_add_u64 v[2:3], v[2:3], 0, v[68:69]
	global_store_dwordx4 v[2:3], v[8:11], off
	s_waitcnt lgkmcnt(0)

.LBB0_96:
	s_andn2_saveexec_b64 s[4:5], s[64:65]
	s_cbranch_execz .LBB0_15
	v_mul_i32_i24_e32 v3, 0x7f81, v2
	v_lshrrev_b32_e32 v4, 31, v3
	v_ashrrev_i32_e32 v3, 23, v3
	v_add_u16_e32 v3, v3, v4
	v_mul_lo_u16_e32 v4, 0x101, v3
	v_sub_u16_e32 v6, v2, v4
	v_lshlrev_b32_sdwa v115, v112, sext(v6) dst_sel:DWORD dst_unused:UNUSED_PAD src0_sel:DWORD src1_sel:WORD_0
	v_or_b32_e32 v2, 24, v115
	v_cmp_gt_i16_e32 vcc, s59, v6
	v_lshlrev_b32_sdwa v76, v112, sext(v3) dst_sel:DWORD dst_unused:UNUSED_PAD src0_sel:DWORD src1_sel:WORD_0
	v_mov_b64_e32 v[4:5], s[16:17]
	v_cndmask_b32_e32 v2, v113, v2, vcc
	v_cmp_gt_i16_e32 vcc, 40, v6
	s_mov_b32 s2, 0x8030000
	v_or_b32_e32 v78, v76, v83
	v_cndmask_b32_e32 v2, v2, v115, vcc
	v_mad_i64_i32 v[4:5], s[2:3], v74, s2, v[4:5]
	v_cmp_eq_u16_e32 vcc, s59, v6
	v_mul_hi_i32_i24_e32 v7, 0x10060, v78
	v_mul_i32_i24_e32 v6, 0x10060, v78
	v_lshl_add_u64 v[4:5], v[4:5], 0, v[6:7]
	v_ashrrev_i32_e32 v3, 31, v2
	v_lshl_add_u64 v[2:3], v[2:3], 2, v[4:5]
	v_mov_b32_e32 v73, v69
	v_cndmask_b32_e64 v116, 64, 24, vcc
	v_lshl_add_u64 v[80:81], v[2:3], 0, v[72:73]
	v_mov_b32_e32 v2, 0
	v_cmp_lt_u32_e64 s[2:3], v66, v116
	v_mov_b32_e32 v6, 0
	v_mov_b32_e32 v7, v2
	v_mov_b32_e32 v8, 0
	v_mov_b32_e32 v9, 0
	s_and_saveexec_b64 s[64:65], s[2:3]
	s_cbranch_execz .LBB0_99
	global_load_dwordx4 v[6:9], v[80:81], off nt
.LBB0_99:
	s_or_b64 exec, exec, s[64:65]
	v_mov_b32_e32 v3, 0
	v_mov_b32_e32 v4, 0
	v_mov_b32_e32 v5, 0
	s_and_saveexec_b64 s[64:65], s[2:3]
	s_cbranch_execz .LBB0_101
	v_add_co_u32_e32 v2, vcc, 0x40000, v80
	s_nop 1
	v_addc_co_u32_e32 v3, vcc, 0, v81, vcc
	global_load_dwordx4 v[2:5], v[2:3], off offset:384 nt
.LBB0_101:
	s_or_b64 exec, exec, s[64:65]
	v_mov_b32_e32 v10, 0
	v_mov_b32_e32 v14, 0
	v_mov_b32_e32 v15, 0
	v_mov_b32_e32 v16, 0
	v_mov_b32_e32 v17, 0
	s_and_saveexec_b64 s[64:65], s[2:3]
	s_cbranch_execz .LBB0_103
	v_add_co_u32_e32 v12, vcc, 0x80000, v80
	s_nop 1
	v_addc_co_u32_e32 v13, vcc, 0, v81, vcc
	global_load_dwordx4 v[14:17], v[12:13], off offset:768 nt
.LBB0_103:
	s_or_b64 exec, exec, s[64:65]
	v_mov_b32_e32 v11, 0
	v_mov_b32_e32 v12, 0
	v_mov_b32_e32 v13, 0
	s_and_saveexec_b64 s[64:65], s[2:3]
	s_cbranch_execz .LBB0_105
	v_add_co_u32_e32 v10, vcc, 0xc0000, v80
	s_nop 1
	v_addc_co_u32_e32 v11, vcc, 0, v81, vcc
	global_load_dwordx4 v[10:13], v[10:11], off offset:1152 nt
.LBB0_105:
	s_or_b64 exec, exec, s[64:65]
	v_mov_b32_e32 v18, 0
	v_mov_b32_e32 v26, 0
	v_mov_b32_e32 v27, 0
	v_mov_b32_e32 v28, 0
	v_mov_b32_e32 v29, 0
	s_and_saveexec_b64 s[64:65], s[2:3]
	s_cbranch_execz .LBB0_107
	v_add_co_u32_e32 v20, vcc, 0x100000, v80
	s_nop 1
	v_addc_co_u32_e32 v21, vcc, 0, v81, vcc
	global_load_dwordx4 v[26:29], v[20:21], off offset:1536 nt
.LBB0_107:
	s_or_b64 exec, exec, s[64:65]
	v_mov_b32_e32 v19, 0
	v_mov_b32_e32 v20, 0
	v_mov_b32_e32 v21, 0
	s_and_saveexec_b64 s[64:65], s[2:3]
	s_cbranch_execz .LBB0_109
	v_add_co_u32_e32 v18, vcc, 0x140000, v80
	s_nop 1
	v_addc_co_u32_e32 v19, vcc, 0, v81, vcc
	global_load_dwordx4 v[18:21], v[18:19], off offset:1920 nt
.LBB0_109:
	s_or_b64 exec, exec, s[64:65]
	v_mov_b32_e32 v22, 0
	v_mov_b32_e32 v34, 0
	v_mov_b32_e32 v35, 0
	v_mov_b32_e32 v36, 0
	v_mov_b32_e32 v37, 0
	s_and_saveexec_b64 s[64:65], s[2:3]
	s_cbranch_execz .LBB0_111
	v_add_co_u32_e32 v24, vcc, 0x180000, v80
	s_nop 1
	v_addc_co_u32_e32 v25, vcc, 0, v81, vcc
	global_load_dwordx4 v[34:37], v[24:25], off offset:2304 nt
.LBB0_111:
	s_or_b64 exec, exec, s[64:65]
	v_mov_b32_e32 v23, 0
	v_mov_b32_e32 v24, 0
	v_mov_b32_e32 v25, 0
	s_and_saveexec_b64 s[64:65], s[2:3]
	s_cbranch_execz .LBB0_113
	v_add_co_u32_e32 v22, vcc, 0x1c0000, v80
	s_nop 1
	v_addc_co_u32_e32 v23, vcc, 0, v81, vcc
	global_load_dwordx4 v[22:25], v[22:23], off offset:2688 nt
.LBB0_113:
	s_or_b64 exec, exec, s[64:65]
	v_mov_b32_e32 v30, 0
	v_mov_b32_e32 v42, 0
	v_mov_b32_e32 v43, 0
	v_mov_b32_e32 v44, 0
	v_mov_b32_e32 v45, 0
	s_and_saveexec_b64 s[64:65], s[2:3]
	s_cbranch_execz .LBB0_115
	v_add_co_u32_e32 v32, vcc, 0x200000, v80
	s_nop 1
	v_addc_co_u32_e32 v33, vcc, 0, v81, vcc
	global_load_dwordx4 v[42:45], v[32:33], off offset:3072 nt
.LBB0_115:
	s_or_b64 exec, exec, s[64:65]
	v_mov_b32_e32 v31, 0
	v_mov_b32_e32 v32, 0
	v_mov_b32_e32 v33, 0
	s_and_saveexec_b64 s[64:65], s[2:3]
	s_cbranch_execz .LBB0_117
	v_add_co_u32_e32 v30, vcc, 0x240000, v80
	s_nop 1
	v_addc_co_u32_e32 v31, vcc, 0, v81, vcc
	global_load_dwordx4 v[30:33], v[30:31], off offset:3456 nt
.LBB0_117:
	s_or_b64 exec, exec, s[64:65]
	v_mov_b32_e32 v38, 0
	v_mov_b32_e32 v50, 0
	v_mov_b32_e32 v51, 0
	v_mov_b32_e32 v52, 0
	v_mov_b32_e32 v53, 0
	s_and_saveexec_b64 s[64:65], s[2:3]
	s_cbranch_execz .LBB0_119
	v_add_co_u32_e32 v40, vcc, 0x280000, v80
	s_nop 1
	v_addc_co_u32_e32 v41, vcc, 0, v81, vcc
	global_load_dwordx4 v[50:53], v[40:41], off offset:3840 nt
.LBB0_119:
	s_or_b64 exec, exec, s[64:65]
	v_mov_b32_e32 v39, 0
	v_mov_b32_e32 v40, 0
	v_mov_b32_e32 v41, 0
	s_and_saveexec_b64 s[64:65], s[2:3]
	s_cbranch_execz .LBB0_121
	v_add_co_u32_e32 v38, vcc, 0x2c1000, v80
	s_nop 1
	v_addc_co_u32_e32 v39, vcc, 0, v81, vcc
	global_load_dwordx4 v[38:41], v[38:39], off offset:128 nt
.LBB0_121:
	s_or_b64 exec, exec, s[64:65]
	v_mov_b32_e32 v46, 0
	v_mov_b32_e32 v58, 0
	v_mov_b32_e32 v59, 0
	v_mov_b32_e32 v60, 0
	v_mov_b32_e32 v61, 0
	s_and_saveexec_b64 s[64:65], s[2:3]
	s_cbranch_execz .LBB0_123
	v_add_co_u32_e32 v48, vcc, 0x301000, v80
	s_nop 1
	v_addc_co_u32_e32 v49, vcc, 0, v81, vcc
	global_load_dwordx4 v[58:61], v[48:49], off offset:512 nt
.LBB0_123:
	s_or_b64 exec, exec, s[64:65]
	v_mov_b32_e32 v47, 0
	v_mov_b32_e32 v48, 0
	v_mov_b32_e32 v49, 0
	s_and_saveexec_b64 s[64:65], s[2:3]
	s_cbranch_execz .LBB0_125
	v_add_co_u32_e32 v46, vcc, 0x341000, v80
	s_nop 1
	v_addc_co_u32_e32 v47, vcc, 0, v81, vcc
	global_load_dwordx4 v[46:49], v[46:47], off offset:896 nt
.LBB0_125:
	s_or_b64 exec, exec, s[64:65]
	v_mov_b32_e32 v54, 0
	v_mov_b32_e32 v62, 0
	v_mov_b32_e32 v63, 0
	v_mov_b32_e32 v64, 0
	v_mov_b32_e32 v65, 0
	s_and_saveexec_b64 s[64:65], s[2:3]
	s_cbranch_execz .LBB0_127
	v_add_co_u32_e32 v56, vcc, 0x381000, v80
	s_nop 1
	v_addc_co_u32_e32 v57, vcc, 0, v81, vcc
	global_load_dwordx4 v[62:65], v[56:57], off offset:1280 nt
.LBB0_127:
	s_or_b64 exec, exec, s[64:65]
	v_mov_b32_e32 v55, 0
	v_mov_b32_e32 v56, 0
	v_mov_b32_e32 v57, 0
	s_and_saveexec_b64 s[64:65], s[2:3]
	s_cbranch_execz .LBB0_129
	v_add_co_u32_e32 v54, vcc, 0x3c1000, v80
	s_nop 1
	v_addc_co_u32_e32 v55, vcc, 0, v81, vcc
	global_load_dwordx4 v[54:57], v[54:55], off offset:1664 nt
